# scan state renormalised every 66 steps (pass 1) / 64 steps (pass 2) instead of 33 / 32: half the renormalisation sweeps
# baseline (speedup 1.0000x reference)
; #define NEXT_ITEM() (MIX ? (int)__builtin_amdgcn_readfirstlane(lane == 0 ? __hip_atomic_fetch_add(qctr, 1u, __ATOMIC_RELAXED, __HIP_MEMORY_SCOPE_AGENT) : 0u) : item + (int)gridDim.x * 8)
; #define SB __builtin_amdgcn_sched_barrier(0)
; #define MKR(ptr) __builtin_amdgcn_make_buffer_rsrc((void*)(ptr), 0, 0x7fffffff, 0x00027000)
; #define LD1(set, s) { const int e_ = min((int)(s), LC - 1) * (int)stp; const unsigned s4_ = ob4 + (unsigned)(e_ * 4), s2_ = ob2 + (unsigned)(e_ * 2); set.w = LDX(rW, s4_); set.a = LDX(rA, s4_); set.b = LDX(rB, s4_); \
;             set.kw = __builtin_amdgcn_raw_buffer_load_b64(rK, lo8, s2_, 0); set.v = __builtin_amdgcn_raw_buffer_load_b16(rV, lo2, s2_, 0); }
; #define TOUCH1(set) asm volatile("" :: "v"(set.w), "v"(set.a), "v"(set.b), "v"(set.kw), "v"(set.v))
; #define ST1(set) { DERIVE_BK(set); float sd[4]; ScanK<0>::dot(S, set.a, sd); ScanK<0>::updS(S, set, -((sd[0] + sd[1]) + (sd[2] + sd[3])), __uint_as_float(set.v << 16)); }
; #define TOUCH1(set) asm volatile("" :: "v"(set.w), "v"(set.a), "v"(set.b))
; template <bool MIX> __device__ __forceinline__ void scan_pass1(const Params& p, int d, float* ldsf) {
;     ...
;     for (int item = MIX ? NEXT_ITEM() : (int)(blockIdx.x * 8 + wid); item < 2 * NS; item = NEXT_ITEM()) {
;         const bool isP = item >= NS; const int idx = isP ? item - NS : item;
;         const int bh = idx / (NC - 1), c = idx - bh * (NC - 1), b = bh >> 4, h = bh & 15;
;         const int t0 = d ? (SEQ - 1 - c * LC) : c * LC;
;         const size_t off0 = ((size_t)(b * SEQ + t0)) * RW + h * 64; const long stp = d ? -(long)RW : (long)RW;
;         const unsigned ob4 = (unsigned)(off0 * 4), ob2 = (unsigned)(off0 * 2);
;         const f32x4 ka4 = *(const f32x4*)(p.k_a + h * 64 + (lane & 15) * 4), c04 = 1.0f - ka4;
;         float S[64]; int ln = lane; asm volatile("" : "+v"(ln));
;     ...
;         const __amdgpu_buffer_rsrc_t rW = MKR(Wd), rA = MKR(A), rB = MKR(Bd), rK = MKR(KB), rV = MKR(V);
;         if (!isP) {
; #pragma unroll
;             for (int i = 0; i < 64; ++i) S[i] = 0.f;
;     ...
;             In1 i0, i1; LD1(i0, 0);
; #pragma unroll 1
;             for (int s = 0; s < LC; s += 2) { TOUCH1(i0); SB; LD1(i1, s + 1); SB; ST1(i0); TOUCH1(i1); SB; LD1(i0, s + 2); SB; ST1(i1); }
;     ...
;         } else {
; #pragma unroll
;             for (int i = 0; i < 64; ++i) S[i] = (ln == i) ? 1.f : 0.f;
.Lmy_p1d0_item:
	s_cmpk_gt_i32 s0, 0x7df
	s_cbranch_scc1 .Lmy_p1d0_end
	s_mul_i32 s86, s0, 2081
	s_lshr_b32 s86, s86, 17
	s_mul_i32 s7, s86, 63
	s_sub_u32 s85, s0, s7
	s_and_b32 s87, s86, 15
	s_lshr_b32 s6, s86, 4
	s_lshl_b32 s6, s6, 14
	s_lshl_b32 s7, s85, 8
	s_add_u32 s6, s6, s7
	s_lshl_b32 s6, s6, 10
	s_lshl_b32 s7, s87, 6
	s_add_u32 s84, s6, s7
	s_lshl_b32 s72, s84, 2
	s_lshl_b32 s76, s84, 1
	s_lshl_b32 s6, s86, 6
	s_add_u32 s6, s6, s85
	s_lshl_b32 s6, s6, 14
	s_add_u32 s7, s6, 0x15800000
	s_add_u32 s90, s56, s7
	s_addc_u32 s91, s57, 0
	s_add_u32 s7, s6, 0x13800000
	s_add_u32 s92, s56, s7
	s_addc_u32 s93, s57, 0
	s_lshl_b32 s8, s87, 8
	s_add_u32 s4, s42, s8
	s_addc_u32 s5, s43, 0
	v_and_b32_e32 v129, 15, v254
	v_lshlrev_b32_e32 v130, 4, v129
	global_load_dwordx4 v[216:219], v130, s[4:5]
	buffer_load_dwordx4 v[160:163], v235, s[64:67], s72 offen
	buffer_load_dwordx4 v[164:167], v250, s[64:67], s72 offen
	buffer_load_dwordx4 v[168:171], v251, s[64:67], s72 offen
	buffer_load_dwordx2 v[172:173], v252, s[64:67], s76 offen
	buffer_load_ushort v174, v253, s[64:67], s76 offen
	s_add_u32 s72, s72, 0x1000
	s_add_u32 s76, s76, 0x800
	buffer_load_dwordx4 v[176:179], v235, s[64:67], s72 offen
	buffer_load_dwordx4 v[180:183], v250, s[64:67], s72 offen
	buffer_load_dwordx4 v[184:187], v251, s[64:67], s72 offen
	buffer_load_dwordx2 v[188:189], v252, s[64:67], s76 offen
	buffer_load_ushort v190, v253, s[64:67], s76 offen
	s_add_u32 s72, s72, 0x1000
	s_add_u32 s76, s76, 0x800
	v_and_b32_e32 v128, 63, v254
	v_mov_b32_e32 v129, 1.0
	v_mov_b32_e32 v0, 0
	v_mov_b32_e32 v1, 0
	v_mov_b32_e32 v2, 0
	v_mov_b32_e32 v3, 0
	v_mov_b32_e32 v4, 0
	v_mov_b32_e32 v5, 0
	v_mov_b32_e32 v6, 0
	v_mov_b32_e32 v7, 0
	v_mov_b32_e32 v8, 0
	v_mov_b32_e32 v9, 0
	v_mov_b32_e32 v10, 0
	v_mov_b32_e32 v11, 0
	v_mov_b32_e32 v12, 0
	v_mov_b32_e32 v13, 0
	v_mov_b32_e32 v14, 0
	v_mov_b32_e32 v15, 0
	v_mov_b32_e32 v16, 0
	v_mov_b32_e32 v17, 0
	v_mov_b32_e32 v18, 0
	v_mov_b32_e32 v19, 0
	v_mov_b32_e32 v20, 0
	v_mov_b32_e32 v21, 0
	v_mov_b32_e32 v22, 0
	v_mov_b32_e32 v23, 0
	v_mov_b32_e32 v24, 0
	v_mov_b32_e32 v25, 0
	v_mov_b32_e32 v26, 0
	v_mov_b32_e32 v27, 0
	v_mov_b32_e32 v28, 0
	v_mov_b32_e32 v29, 0
	v_mov_b32_e32 v30, 0
	v_mov_b32_e32 v31, 0
	v_mov_b32_e32 v32, 0
	v_mov_b32_e32 v33, 0
	v_mov_b32_e32 v34, 0
	v_mov_b32_e32 v35, 0
	v_mov_b32_e32 v36, 0
	v_mov_b32_e32 v37, 0
	v_mov_b32_e32 v38, 0
	v_mov_b32_e32 v39, 0
	v_mov_b32_e32 v40, 0
	v_mov_b32_e32 v41, 0
	v_mov_b32_e32 v42, 0
	v_mov_b32_e32 v43, 0
	v_mov_b32_e32 v44, 0
	v_mov_b32_e32 v45, 0
	v_mov_b32_e32 v46, 0
	v_mov_b32_e32 v47, 0
	v_mov_b32_e32 v48, 0
	v_mov_b32_e32 v49, 0
	v_mov_b32_e32 v50, 0
	v_mov_b32_e32 v51, 0
	v_mov_b32_e32 v52, 0
	v_mov_b32_e32 v53, 0
	v_mov_b32_e32 v54, 0
	v_mov_b32_e32 v55, 0
	v_mov_b32_e32 v56, 0
	v_mov_b32_e32 v57, 0
	v_mov_b32_e32 v58, 0
	v_mov_b32_e32 v59, 0
	v_mov_b32_e32 v60, 0
	v_mov_b32_e32 v61, 0
	v_mov_b32_e32 v62, 0
	v_mov_b32_e32 v63, 0
	v_cmp_eq_u32_e32 vcc, 0, v128
	s_nop 1
	v_cndmask_b32_e32 v64, 0, v129, vcc
	v_cmp_eq_u32_e32 vcc, 1, v128
	s_nop 1
	v_cndmask_b32_e32 v65, 0, v129, vcc
	v_cmp_eq_u32_e32 vcc, 2, v128
	s_nop 1
	v_cndmask_b32_e32 v66, 0, v129, vcc
	v_cmp_eq_u32_e32 vcc, 3, v128
	s_nop 1
	v_cndmask_b32_e32 v67, 0, v129, vcc
	v_cmp_eq_u32_e32 vcc, 4, v128
	s_nop 1
	v_cndmask_b32_e32 v68, 0, v129, vcc
	v_cmp_eq_u32_e32 vcc, 5, v128
	s_nop 1
	v_cndmask_b32_e32 v69, 0, v129, vcc
	v_cmp_eq_u32_e32 vcc, 6, v128
	s_nop 1
	v_cndmask_b32_e32 v70, 0, v129, vcc
	v_cmp_eq_u32_e32 vcc, 7, v128
	s_nop 1
	v_cndmask_b32_e32 v71, 0, v129, vcc
	v_cmp_eq_u32_e32 vcc, 8, v128
	s_nop 1
	v_cndmask_b32_e32 v72, 0, v129, vcc
	v_cmp_eq_u32_e32 vcc, 9, v128
	s_nop 1
	v_cndmask_b32_e32 v73, 0, v129, vcc
	v_cmp_eq_u32_e32 vcc, 10, v128
	s_nop 1
	v_cndmask_b32_e32 v74, 0, v129, vcc
	v_cmp_eq_u32_e32 vcc, 11, v128
	s_nop 1
	v_cndmask_b32_e32 v75, 0, v129, vcc
	v_cmp_eq_u32_e32 vcc, 12, v128
	s_nop 1
	v_cndmask_b32_e32 v76, 0, v129, vcc
	v_cmp_eq_u32_e32 vcc, 13, v128
	s_nop 1
	v_cndmask_b32_e32 v77, 0, v129, vcc
	v_cmp_eq_u32_e32 vcc, 14, v128
	s_nop 1
	v_cndmask_b32_e32 v78, 0, v129, vcc
	v_cmp_eq_u32_e32 vcc, 15, v128
	s_nop 1
	v_cndmask_b32_e32 v79, 0, v129, vcc
	v_cmp_eq_u32_e32 vcc, 16, v128
	s_nop 1
	v_cndmask_b32_e32 v80, 0, v129, vcc
	v_cmp_eq_u32_e32 vcc, 17, v128
	s_nop 1
	v_cndmask_b32_e32 v81, 0, v129, vcc
	v_cmp_eq_u32_e32 vcc, 18, v128
	s_nop 1
	v_cndmask_b32_e32 v82, 0, v129, vcc
	v_cmp_eq_u32_e32 vcc, 19, v128
	s_nop 1
	v_cndmask_b32_e32 v83, 0, v129, vcc
	v_cmp_eq_u32_e32 vcc, 20, v128
	s_nop 1
	v_cndmask_b32_e32 v84, 0, v129, vcc
	v_cmp_eq_u32_e32 vcc, 21, v128
	s_nop 1
	v_cndmask_b32_e32 v85, 0, v129, vcc
	v_cmp_eq_u32_e32 vcc, 22, v128
	s_nop 1
	v_cndmask_b32_e32 v86, 0, v129, vcc
	v_cmp_eq_u32_e32 vcc, 23, v128
	s_nop 1
	v_cndmask_b32_e32 v87, 0, v129, vcc
	v_cmp_eq_u32_e32 vcc, 24, v128
	s_nop 1
	v_cndmask_b32_e32 v88, 0, v129, vcc
	v_cmp_eq_u32_e32 vcc, 25, v128
	s_nop 1
	v_cndmask_b32_e32 v89, 0, v129, vcc
	v_cmp_eq_u32_e32 vcc, 26, v128
	s_nop 1
	v_cndmask_b32_e32 v90, 0, v129, vcc
	v_cmp_eq_u32_e32 vcc, 27, v128
	s_nop 1
	v_cndmask_b32_e32 v91, 0, v129, vcc
	v_cmp_eq_u32_e32 vcc, 28, v128
	s_nop 1
	v_cndmask_b32_e32 v92, 0, v129, vcc
	v_cmp_eq_u32_e32 vcc, 29, v128
	s_nop 1
	v_cndmask_b32_e32 v93, 0, v129, vcc
	v_cmp_eq_u32_e32 vcc, 30, v128
	s_nop 1
	v_cndmask_b32_e32 v94, 0, v129, vcc
	v_cmp_eq_u32_e32 vcc, 31, v128
	s_nop 1
	v_cndmask_b32_e32 v95, 0, v129, vcc
	v_cmp_eq_u32_e32 vcc, 32, v128
	s_nop 1
	v_cndmask_b32_e32 v96, 0, v129, vcc
	v_cmp_eq_u32_e32 vcc, 33, v128
	s_nop 1
	v_cndmask_b32_e32 v97, 0, v129, vcc
	v_cmp_eq_u32_e32 vcc, 34, v128
	s_nop 1
; #define SB __builtin_amdgcn_sched_barrier(0)
; #define LD1(set, s) { const int e_ = min((int)(s), LC - 1) * (int)stp; const unsigned s4_ = ob4 + (unsigned)(e_ * 4), s2_ = ob2 + (unsigned)(e_ * 2); set.w = LDX(rW, s4_); set.a = LDX(rA, s4_); set.b = LDX(rB, s4_); \
;             set.kw = __builtin_amdgcn_raw_buffer_load_b64(rK, lo8, s2_, 0); set.v = __builtin_amdgcn_raw_buffer_load_b16(rV, lo2, s2_, 0); }
; #define TOUCH1(set) asm volatile("" :: "v"(set.w), "v"(set.a), "v"(set.b), "v"(set.kw), "v"(set.v))
; #define ST1(set) { DERIVE_BK(set); float sd[4]; ScanK<0>::dot(S, set.a, sd); ScanK<0>::updS(S, set, -((sd[0] + sd[1]) + (sd[2] + sd[3])), __uint_as_float(set.v << 16)); }
; #define LD1(set, s) { const int e_ = min((int)(s), LC - 1) * (int)stp; const unsigned s4_ = ob4 + (unsigned)(e_ * 4); set.w = LDX(rW, s4_); set.a = LDX(rA, s4_); set.b = LDX(rB, s4_); }
; #define TOUCH1(set) asm volatile("" :: "v"(set.w), "v"(set.a), "v"(set.b))
; #define ST1(set) { DERIVE_B(set); float sd[4]; ScanK<0>::dot(S, set.a, sd); ScanK<0>::updP(S, set, -((sd[0] + sd[1]) + (sd[2] + sd[3]))); }
; template <bool MIX> __device__ __forceinline__ void scan_pass1(const Params& p, int d, float* ldsf) {
;     ...
;         if (!isP) {
; #pragma unroll
;             for (int i = 0; i < 64; ++i) S[i] = 0.f;
;     ...
;             In1 i0, i1; LD1(i0, 0);
; #pragma unroll 1
;             for (int s = 0; s < LC; s += 2) { TOUCH1(i0); SB; LD1(i1, s + 1); SB; ST1(i0); TOUCH1(i1); SB; LD1(i0, s + 2); SB; ST1(i1); }
;     ...
;         } else {
; #pragma unroll
;             for (int i = 0; i < 64; ++i) S[i] = (ln == i) ? 1.f : 0.f;
;     ...
;             In1 i0, i1; LD1(i0, 0);
; #pragma unroll 1
;             for (int s = 0; s < LC; s += 2) { TOUCH1(i0); SB; LD1(i1, s + 1); SB; ST1(i0); TOUCH1(i1); SB; LD1(i0, s + 2); SB; ST1(i1); }
	v_cndmask_b32_e32 v98, 0, v129, vcc
	v_cmp_eq_u32_e32 vcc, 35, v128
	s_nop 1
	v_cndmask_b32_e32 v99, 0, v129, vcc
	v_cmp_eq_u32_e32 vcc, 36, v128
	s_nop 1
	v_cndmask_b32_e32 v100, 0, v129, vcc
	v_cmp_eq_u32_e32 vcc, 37, v128
	s_nop 1
	v_cndmask_b32_e32 v101, 0, v129, vcc
	v_cmp_eq_u32_e32 vcc, 38, v128
	s_nop 1
	v_cndmask_b32_e32 v102, 0, v129, vcc
	v_cmp_eq_u32_e32 vcc, 39, v128
	s_nop 1
	v_cndmask_b32_e32 v103, 0, v129, vcc
	v_cmp_eq_u32_e32 vcc, 40, v128
	s_nop 1
	v_cndmask_b32_e32 v104, 0, v129, vcc
	v_cmp_eq_u32_e32 vcc, 41, v128
	s_nop 1
	v_cndmask_b32_e32 v105, 0, v129, vcc
	v_cmp_eq_u32_e32 vcc, 42, v128
	s_nop 1
	v_cndmask_b32_e32 v106, 0, v129, vcc
	v_cmp_eq_u32_e32 vcc, 43, v128
	s_nop 1
	v_cndmask_b32_e32 v107, 0, v129, vcc
	v_cmp_eq_u32_e32 vcc, 44, v128
	s_nop 1
	v_cndmask_b32_e32 v108, 0, v129, vcc
	v_cmp_eq_u32_e32 vcc, 45, v128
	s_nop 1
	v_cndmask_b32_e32 v109, 0, v129, vcc
	v_cmp_eq_u32_e32 vcc, 46, v128
	s_nop 1
	v_cndmask_b32_e32 v110, 0, v129, vcc
	v_cmp_eq_u32_e32 vcc, 47, v128
	s_nop 1
	v_cndmask_b32_e32 v111, 0, v129, vcc
	v_cmp_eq_u32_e32 vcc, 48, v128
	s_nop 1
	v_cndmask_b32_e32 v112, 0, v129, vcc
	v_cmp_eq_u32_e32 vcc, 49, v128
	s_nop 1
	v_cndmask_b32_e32 v113, 0, v129, vcc
	v_cmp_eq_u32_e32 vcc, 50, v128
	s_nop 1
	v_cndmask_b32_e32 v114, 0, v129, vcc
	v_cmp_eq_u32_e32 vcc, 51, v128
	s_nop 1
	v_cndmask_b32_e32 v115, 0, v129, vcc
	v_cmp_eq_u32_e32 vcc, 52, v128
	s_nop 1
	v_cndmask_b32_e32 v116, 0, v129, vcc
	v_cmp_eq_u32_e32 vcc, 53, v128
	s_nop 1
	v_cndmask_b32_e32 v117, 0, v129, vcc
	v_cmp_eq_u32_e32 vcc, 54, v128
	s_nop 1
	v_cndmask_b32_e32 v118, 0, v129, vcc
	v_cmp_eq_u32_e32 vcc, 55, v128
	s_nop 1
	v_cndmask_b32_e32 v119, 0, v129, vcc
	v_cmp_eq_u32_e32 vcc, 56, v128
	s_nop 1
	v_cndmask_b32_e32 v120, 0, v129, vcc
	v_cmp_eq_u32_e32 vcc, 57, v128
	s_nop 1
	v_cndmask_b32_e32 v121, 0, v129, vcc
	v_cmp_eq_u32_e32 vcc, 58, v128
	s_nop 1
	v_cndmask_b32_e32 v122, 0, v129, vcc
	v_cmp_eq_u32_e32 vcc, 59, v128
	s_nop 1
	v_cndmask_b32_e32 v123, 0, v129, vcc
	v_cmp_eq_u32_e32 vcc, 60, v128
	s_nop 1
	v_cndmask_b32_e32 v124, 0, v129, vcc
	v_cmp_eq_u32_e32 vcc, 61, v128
	s_nop 1
	v_cndmask_b32_e32 v125, 0, v129, vcc
	v_cmp_eq_u32_e32 vcc, 62, v128
	s_nop 1
	v_cndmask_b32_e32 v126, 0, v129, vcc
	v_cmp_eq_u32_e32 vcc, 63, v128
	s_nop 1
	v_cndmask_b32_e32 v127, 0, v129, vcc
	s_waitcnt vmcnt(0)
	v_sub_f32_e32 v220, 1.0, v216
	v_sub_f32_e32 v221, 1.0, v217
	v_sub_f32_e32 v222, 1.0, v218
	v_sub_f32_e32 v223, 1.0, v219
	v_mov_b32_e32 v236, 1.0
	v_mov_b32_e32 v237, 1.0
	v_mov_b32_e32 v238, 1.0
	v_mov_b32_e32 v239, 1.0
	s_movk_i32 s83, 85
	s_movk_i32 s9, 22
	s_branch .Lmy_p1d0_loop
.Lmy_p1d0_renorm:
	v_mul_f32_dpp v0, v236, v0 row_newbcast:0 row_mask:0xf bank_mask:0xf
	v_mul_f32_dpp v1, v237, v1 row_newbcast:0 row_mask:0xf bank_mask:0xf
	v_mul_f32_dpp v2, v238, v2 row_newbcast:0 row_mask:0xf bank_mask:0xf
	v_mul_f32_dpp v3, v239, v3 row_newbcast:0 row_mask:0xf bank_mask:0xf
	v_mul_f32_dpp v4, v236, v4 row_newbcast:1 row_mask:0xf bank_mask:0xf
	v_mul_f32_dpp v5, v237, v5 row_newbcast:1 row_mask:0xf bank_mask:0xf
	v_mul_f32_dpp v6, v238, v6 row_newbcast:1 row_mask:0xf bank_mask:0xf
	v_mul_f32_dpp v7, v239, v7 row_newbcast:1 row_mask:0xf bank_mask:0xf
	v_mul_f32_dpp v8, v236, v8 row_newbcast:2 row_mask:0xf bank_mask:0xf
	v_mul_f32_dpp v9, v237, v9 row_newbcast:2 row_mask:0xf bank_mask:0xf
	v_mul_f32_dpp v10, v238, v10 row_newbcast:2 row_mask:0xf bank_mask:0xf
	v_mul_f32_dpp v11, v239, v11 row_newbcast:2 row_mask:0xf bank_mask:0xf
	v_mul_f32_dpp v12, v236, v12 row_newbcast:3 row_mask:0xf bank_mask:0xf
	v_mul_f32_dpp v13, v237, v13 row_newbcast:3 row_mask:0xf bank_mask:0xf
	v_mul_f32_dpp v14, v238, v14 row_newbcast:3 row_mask:0xf bank_mask:0xf
	v_mul_f32_dpp v15, v239, v15 row_newbcast:3 row_mask:0xf bank_mask:0xf
	v_mul_f32_dpp v16, v236, v16 row_newbcast:4 row_mask:0xf bank_mask:0xf
	v_mul_f32_dpp v17, v237, v17 row_newbcast:4 row_mask:0xf bank_mask:0xf
	v_mul_f32_dpp v18, v238, v18 row_newbcast:4 row_mask:0xf bank_mask:0xf
	v_mul_f32_dpp v19, v239, v19 row_newbcast:4 row_mask:0xf bank_mask:0xf
	v_mul_f32_dpp v20, v236, v20 row_newbcast:5 row_mask:0xf bank_mask:0xf
	v_mul_f32_dpp v21, v237, v21 row_newbcast:5 row_mask:0xf bank_mask:0xf
	v_mul_f32_dpp v22, v238, v22 row_newbcast:5 row_mask:0xf bank_mask:0xf
	v_mul_f32_dpp v23, v239, v23 row_newbcast:5 row_mask:0xf bank_mask:0xf
	v_mul_f32_dpp v24, v236, v24 row_newbcast:6 row_mask:0xf bank_mask:0xf
	v_mul_f32_dpp v25, v237, v25 row_newbcast:6 row_mask:0xf bank_mask:0xf
	v_mul_f32_dpp v26, v238, v26 row_newbcast:6 row_mask:0xf bank_mask:0xf
	v_mul_f32_dpp v27, v239, v27 row_newbcast:6 row_mask:0xf bank_mask:0xf
	v_mul_f32_dpp v28, v236, v28 row_newbcast:7 row_mask:0xf bank_mask:0xf
	v_mul_f32_dpp v29, v237, v29 row_newbcast:7 row_mask:0xf bank_mask:0xf
	v_mul_f32_dpp v30, v238, v30 row_newbcast:7 row_mask:0xf bank_mask:0xf
	v_mul_f32_dpp v31, v239, v31 row_newbcast:7 row_mask:0xf bank_mask:0xf
	v_mul_f32_dpp v32, v236, v32 row_newbcast:8 row_mask:0xf bank_mask:0xf
	v_mul_f32_dpp v33, v237, v33 row_newbcast:8 row_mask:0xf bank_mask:0xf
	v_mul_f32_dpp v34, v238, v34 row_newbcast:8 row_mask:0xf bank_mask:0xf
	v_mul_f32_dpp v35, v239, v35 row_newbcast:8 row_mask:0xf bank_mask:0xf
	v_mul_f32_dpp v36, v236, v36 row_newbcast:9 row_mask:0xf bank_mask:0xf
	v_mul_f32_dpp v37, v237, v37 row_newbcast:9 row_mask:0xf bank_mask:0xf
	v_mul_f32_dpp v38, v238, v38 row_newbcast:9 row_mask:0xf bank_mask:0xf
	v_mul_f32_dpp v39, v239, v39 row_newbcast:9 row_mask:0xf bank_mask:0xf
	v_mul_f32_dpp v40, v236, v40 row_newbcast:10 row_mask:0xf bank_mask:0xf
	v_mul_f32_dpp v41, v237, v41 row_newbcast:10 row_mask:0xf bank_mask:0xf
; #define SB __builtin_amdgcn_sched_barrier(0)
; #define LD1(set, s) { const int e_ = min((int)(s), LC - 1) * (int)stp; const unsigned s4_ = ob4 + (unsigned)(e_ * 4), s2_ = ob2 + (unsigned)(e_ * 2); set.w = LDX(rW, s4_); set.a = LDX(rA, s4_); set.b = LDX(rB, s4_); \
;             set.kw = __builtin_amdgcn_raw_buffer_load_b64(rK, lo8, s2_, 0); set.v = __builtin_amdgcn_raw_buffer_load_b16(rV, lo2, s2_, 0); }
; #define TOUCH1(set) asm volatile("" :: "v"(set.w), "v"(set.a), "v"(set.b), "v"(set.kw), "v"(set.v))
; #define ST1(set) { DERIVE_BK(set); float sd[4]; ScanK<0>::dot(S, set.a, sd); ScanK<0>::updS(S, set, -((sd[0] + sd[1]) + (sd[2] + sd[3])), __uint_as_float(set.v << 16)); }
; #define LD1(set, s) { const int e_ = min((int)(s), LC - 1) * (int)stp; const unsigned s4_ = ob4 + (unsigned)(e_ * 4); set.w = LDX(rW, s4_); set.a = LDX(rA, s4_); set.b = LDX(rB, s4_); }
; #define TOUCH1(set) asm volatile("" :: "v"(set.w), "v"(set.a), "v"(set.b))
; #define ST1(set) { DERIVE_B(set); float sd[4]; ScanK<0>::dot(S, set.a, sd); ScanK<0>::updP(S, set, -((sd[0] + sd[1]) + (sd[2] + sd[3]))); }
; template <bool MIX> __device__ __forceinline__ void scan_pass1(const Params& p, int d, float* ldsf) {
;     ...
;             In1 i0, i1; LD1(i0, 0);
; #pragma unroll 1
;             for (int s = 0; s < LC; s += 2) { TOUCH1(i0); SB; LD1(i1, s + 1); SB; ST1(i0); TOUCH1(i1); SB; LD1(i0, s + 2); SB; ST1(i1); }
;     ...
;         } else {
; #pragma unroll
;             for (int i = 0; i < 64; ++i) S[i] = (ln == i) ? 1.f : 0.f;
;     ...
;             In1 i0, i1; LD1(i0, 0);
; #pragma unroll 1
;             for (int s = 0; s < LC; s += 2) { TOUCH1(i0); SB; LD1(i1, s + 1); SB; ST1(i0); TOUCH1(i1); SB; LD1(i0, s + 2); SB; ST1(i1); }
	v_mul_f32_dpp v42, v238, v42 row_newbcast:10 row_mask:0xf bank_mask:0xf
	v_mul_f32_dpp v43, v239, v43 row_newbcast:10 row_mask:0xf bank_mask:0xf
	v_mul_f32_dpp v44, v236, v44 row_newbcast:11 row_mask:0xf bank_mask:0xf
	v_mul_f32_dpp v45, v237, v45 row_newbcast:11 row_mask:0xf bank_mask:0xf
	v_mul_f32_dpp v46, v238, v46 row_newbcast:11 row_mask:0xf bank_mask:0xf
	v_mul_f32_dpp v47, v239, v47 row_newbcast:11 row_mask:0xf bank_mask:0xf
	v_mul_f32_dpp v48, v236, v48 row_newbcast:12 row_mask:0xf bank_mask:0xf
	v_mul_f32_dpp v49, v237, v49 row_newbcast:12 row_mask:0xf bank_mask:0xf
	v_mul_f32_dpp v50, v238, v50 row_newbcast:12 row_mask:0xf bank_mask:0xf
	v_mul_f32_dpp v51, v239, v51 row_newbcast:12 row_mask:0xf bank_mask:0xf
	v_mul_f32_dpp v52, v236, v52 row_newbcast:13 row_mask:0xf bank_mask:0xf
	v_mul_f32_dpp v53, v237, v53 row_newbcast:13 row_mask:0xf bank_mask:0xf
	v_mul_f32_dpp v54, v238, v54 row_newbcast:13 row_mask:0xf bank_mask:0xf
	v_mul_f32_dpp v55, v239, v55 row_newbcast:13 row_mask:0xf bank_mask:0xf
	v_mul_f32_dpp v56, v236, v56 row_newbcast:14 row_mask:0xf bank_mask:0xf
	v_mul_f32_dpp v57, v237, v57 row_newbcast:14 row_mask:0xf bank_mask:0xf
	v_mul_f32_dpp v58, v238, v58 row_newbcast:14 row_mask:0xf bank_mask:0xf
	v_mul_f32_dpp v59, v239, v59 row_newbcast:14 row_mask:0xf bank_mask:0xf
	v_mul_f32_dpp v60, v236, v60 row_newbcast:15 row_mask:0xf bank_mask:0xf
	v_mul_f32_dpp v61, v237, v61 row_newbcast:15 row_mask:0xf bank_mask:0xf
	v_mul_f32_dpp v62, v238, v62 row_newbcast:15 row_mask:0xf bank_mask:0xf
	v_mul_f32_dpp v63, v239, v63 row_newbcast:15 row_mask:0xf bank_mask:0xf
	v_mul_f32_dpp v64, v236, v64 row_newbcast:0 row_mask:0xf bank_mask:0xf
	v_mul_f32_dpp v65, v237, v65 row_newbcast:0 row_mask:0xf bank_mask:0xf
	v_mul_f32_dpp v66, v238, v66 row_newbcast:0 row_mask:0xf bank_mask:0xf
	v_mul_f32_dpp v67, v239, v67 row_newbcast:0 row_mask:0xf bank_mask:0xf
	v_mul_f32_dpp v68, v236, v68 row_newbcast:1 row_mask:0xf bank_mask:0xf
	v_mul_f32_dpp v69, v237, v69 row_newbcast:1 row_mask:0xf bank_mask:0xf
	v_mul_f32_dpp v70, v238, v70 row_newbcast:1 row_mask:0xf bank_mask:0xf
	v_mul_f32_dpp v71, v239, v71 row_newbcast:1 row_mask:0xf bank_mask:0xf
	v_mul_f32_dpp v72, v236, v72 row_newbcast:2 row_mask:0xf bank_mask:0xf
	v_mul_f32_dpp v73, v237, v73 row_newbcast:2 row_mask:0xf bank_mask:0xf
	v_mul_f32_dpp v74, v238, v74 row_newbcast:2 row_mask:0xf bank_mask:0xf
	v_mul_f32_dpp v75, v239, v75 row_newbcast:2 row_mask:0xf bank_mask:0xf
	v_mul_f32_dpp v76, v236, v76 row_newbcast:3 row_mask:0xf bank_mask:0xf
	v_mul_f32_dpp v77, v237, v77 row_newbcast:3 row_mask:0xf bank_mask:0xf
	v_mul_f32_dpp v78, v238, v78 row_newbcast:3 row_mask:0xf bank_mask:0xf
	v_mul_f32_dpp v79, v239, v79 row_newbcast:3 row_mask:0xf bank_mask:0xf
	v_mul_f32_dpp v80, v236, v80 row_newbcast:4 row_mask:0xf bank_mask:0xf
	v_mul_f32_dpp v81, v237, v81 row_newbcast:4 row_mask:0xf bank_mask:0xf
	v_mul_f32_dpp v82, v238, v82 row_newbcast:4 row_mask:0xf bank_mask:0xf
	v_mul_f32_dpp v83, v239, v83 row_newbcast:4 row_mask:0xf bank_mask:0xf
	v_mul_f32_dpp v84, v236, v84 row_newbcast:5 row_mask:0xf bank_mask:0xf
	v_mul_f32_dpp v85, v237, v85 row_newbcast:5 row_mask:0xf bank_mask:0xf
	v_mul_f32_dpp v86, v238, v86 row_newbcast:5 row_mask:0xf bank_mask:0xf
	v_mul_f32_dpp v87, v239, v87 row_newbcast:5 row_mask:0xf bank_mask:0xf
	v_mul_f32_dpp v88, v236, v88 row_newbcast:6 row_mask:0xf bank_mask:0xf
	v_mul_f32_dpp v89, v237, v89 row_newbcast:6 row_mask:0xf bank_mask:0xf
	v_mul_f32_dpp v90, v238, v90 row_newbcast:6 row_mask:0xf bank_mask:0xf
	v_mul_f32_dpp v91, v239, v91 row_newbcast:6 row_mask:0xf bank_mask:0xf
	v_mul_f32_dpp v92, v236, v92 row_newbcast:7 row_mask:0xf bank_mask:0xf
	v_mul_f32_dpp v93, v237, v93 row_newbcast:7 row_mask:0xf bank_mask:0xf
	v_mul_f32_dpp v94, v238, v94 row_newbcast:7 row_mask:0xf bank_mask:0xf
	v_mul_f32_dpp v95, v239, v95 row_newbcast:7 row_mask:0xf bank_mask:0xf
	v_mul_f32_dpp v96, v236, v96 row_newbcast:8 row_mask:0xf bank_mask:0xf
	v_mul_f32_dpp v97, v237, v97 row_newbcast:8 row_mask:0xf bank_mask:0xf
	v_mul_f32_dpp v98, v238, v98 row_newbcast:8 row_mask:0xf bank_mask:0xf
	v_mul_f32_dpp v99, v239, v99 row_newbcast:8 row_mask:0xf bank_mask:0xf
	v_mul_f32_dpp v100, v236, v100 row_newbcast:9 row_mask:0xf bank_mask:0xf
	v_mul_f32_dpp v101, v237, v101 row_newbcast:9 row_mask:0xf bank_mask:0xf
	v_mul_f32_dpp v102, v238, v102 row_newbcast:9 row_mask:0xf bank_mask:0xf
	v_mul_f32_dpp v103, v239, v103 row_newbcast:9 row_mask:0xf bank_mask:0xf
	v_mul_f32_dpp v104, v236, v104 row_newbcast:10 row_mask:0xf bank_mask:0xf
	v_mul_f32_dpp v105, v237, v105 row_newbcast:10 row_mask:0xf bank_mask:0xf
	v_mul_f32_dpp v106, v238, v106 row_newbcast:10 row_mask:0xf bank_mask:0xf
	v_mul_f32_dpp v107, v239, v107 row_newbcast:10 row_mask:0xf bank_mask:0xf
	v_mul_f32_dpp v108, v236, v108 row_newbcast:11 row_mask:0xf bank_mask:0xf
	v_mul_f32_dpp v109, v237, v109 row_newbcast:11 row_mask:0xf bank_mask:0xf
	v_mul_f32_dpp v110, v238, v110 row_newbcast:11 row_mask:0xf bank_mask:0xf
	v_mul_f32_dpp v111, v239, v111 row_newbcast:11 row_mask:0xf bank_mask:0xf
	v_mul_f32_dpp v112, v236, v112 row_newbcast:12 row_mask:0xf bank_mask:0xf
	v_mul_f32_dpp v113, v237, v113 row_newbcast:12 row_mask:0xf bank_mask:0xf
	v_mul_f32_dpp v114, v238, v114 row_newbcast:12 row_mask:0xf bank_mask:0xf
	v_mul_f32_dpp v115, v239, v115 row_newbcast:12 row_mask:0xf bank_mask:0xf
	v_mul_f32_dpp v116, v236, v116 row_newbcast:13 row_mask:0xf bank_mask:0xf
	v_mul_f32_dpp v117, v237, v117 row_newbcast:13 row_mask:0xf bank_mask:0xf
	v_mul_f32_dpp v118, v238, v118 row_newbcast:13 row_mask:0xf bank_mask:0xf
	v_mul_f32_dpp v119, v239, v119 row_newbcast:13 row_mask:0xf bank_mask:0xf
	v_mul_f32_dpp v120, v236, v120 row_newbcast:14 row_mask:0xf bank_mask:0xf
	v_mul_f32_dpp v121, v237, v121 row_newbcast:14 row_mask:0xf bank_mask:0xf
	v_mul_f32_dpp v122, v238, v122 row_newbcast:14 row_mask:0xf bank_mask:0xf
	v_mul_f32_dpp v123, v239, v123 row_newbcast:14 row_mask:0xf bank_mask:0xf
	v_mul_f32_dpp v124, v236, v124 row_newbcast:15 row_mask:0xf bank_mask:0xf
	v_mul_f32_dpp v125, v237, v125 row_newbcast:15 row_mask:0xf bank_mask:0xf
	v_mul_f32_dpp v126, v238, v126 row_newbcast:15 row_mask:0xf bank_mask:0xf
	v_mul_f32_dpp v127, v239, v127 row_newbcast:15 row_mask:0xf bank_mask:0xf
	v_mov_b32_e32 v236, 1.0
	v_mov_b32_e32 v237, 1.0
	v_mov_b32_e32 v238, 1.0
	v_mov_b32_e32 v239, 1.0
	s_movk_i32 s9, 22

;     static __device__ __forceinline__ void dot(const float (&S)[64], const f32x4& a, float (&s)[4]) {
;         if constexpr (K == 0) {
;             asm volatile("v_mul_f32_dpp %0, %4, %8 row_newbcast:%16" DPPM "v_mul_f32_dpp %1, %5, %9 row_newbcast:%16" DPPM "v_mul_f32_dpp %2, %6, %10 row_newbcast:%16" DPPM "v_mul_f32_dpp %3, %7, %11 row_newbcast:%16" DPPM
;                          "v_fmac_f32_dpp %0, %4, %12 row_newbcast:%17" DPPM "v_fmac_f32_dpp %1, %5, %13 row_newbcast:%17" DPPM "v_fmac_f32_dpp %2, %6, %14 row_newbcast:%17" DPPM "v_fmac_f32_dpp %3, %7, %15 row_newbcast:%17" DPPM
;                          : "=&v"(s[0]), "=&v"(s[1]), "=&v"(s[2]), "=&v"(s[3])
;                          : "v"(a[0]), "v"(a[1]), "v"(a[2]), "v"(a[3]), "v"(S[K]), "v"(S[K + 1]), "v"(S[K + 2]), "v"(S[K + 3]), "v"(S[K + 4]), "v"(S[K + 5]), "v"(S[K + 6]), "v"(S[K + 7]), "n"(N0), "n"(N1));
;         } else
;         asm volatile("v_fmac_f32_dpp %0, %4, %8 row_newbcast:%16" DPPM "v_fmac_f32_dpp %1, %5, %9 row_newbcast:%16" DPPM "v_fmac_f32_dpp %2, %6, %10 row_newbcast:%16" DPPM "v_fmac_f32_dpp %3, %7, %11 row_newbcast:%16" DPPM
;                      "v_fmac_f32_dpp %0, %4, %12 row_newbcast:%17" DPPM "v_fmac_f32_dpp %1, %5, %13 row_newbcast:%17" DPPM "v_fmac_f32_dpp %2, %6, %14 row_newbcast:%17" DPPM "v_fmac_f32_dpp %3, %7, %15 row_newbcast:%17" DPPM
;                      : "+v"(s[0]), "+v"(s[1]), "+v"(s[2]), "+v"(s[3])
;                      : "v"(a[0]), "v"(a[1]), "v"(a[2]), "v"(a[3]), "v"(S[K]), "v"(S[K + 1]), "v"(S[K + 2]), "v"(S[K + 3]), "v"(S[K + 4]), "v"(S[K + 5]), "v"(S[K + 6]), "v"(S[K + 7]), "n"(N0), "n"(N1));
;         if constexpr (K + 8 < 64) ScanK<K + 8>::dot(S, a, s);
;     }
;     static __device__ __forceinline__ void upd(float (&S)[64], const In2& in, float sa, float vv, float& y0, float& y1) {
;         float t0, t1, t2, t3;
;         asm volatile("v_mul_f32_dpp %0, %10, %27 row_newbcast:%28" DPPM "v_mul_f32_dpp %1, %11, %27 row_newbcast:%28" DPPM "v_mul_f32_dpp %2, %12, %27 row_newbcast:%28" DPPM "v_mul_f32_dpp %3, %13, %27 row_newbcast:%28" DPPM
;                      "v_fmac_f32_dpp %0, %14, %6 row_newbcast:%28" DPPM "v_fmac_f32_dpp %1, %15, %7 row_newbcast:%28" DPPM "v_fmac_f32_dpp %2, %16, %8 row_newbcast:%28" DPPM "v_fmac_f32_dpp %3, %17, %9 row_newbcast:%28" DPPM
.Lmy_p2d0_nost:
	buffer_load_dwordx4 v[156:159], v232, s[64:67], s72 offen
	buffer_load_dwordx4 v[160:163], v233, s[64:67], s72 offen
	buffer_load_dwordx4 v[164:167], v234, s[64:67], s72 offen
	buffer_load_dwordx4 v[168:171], v235, s[64:67], s72 offen
	buffer_load_dwordx2 v[172:173], v236, s[64:67], s76 offen
	buffer_load_ushort v174, v237, s[64:67], s76 offen
	s_add_u32 s72, s72, 0x1000
	s_add_u32 s76, s76, 0x800
	v_pk_mul_f32 v[224:225], v[100:101], v[216:217]
	v_pk_mul_f32 v[226:227], v[102:103], v[218:219]
	v_pk_mul_f32 v[216:217], v[216:217], v[96:97]
	v_pk_mul_f32 v[218:219], v[218:219], v[98:99]
	v_pk_fma_f32 v[184:185], v[104:105], v[188:189], v[192:193]
	v_pk_fma_f32 v[186:187], v[106:107], v[190:191], v[194:195]
	v_pk_mul_f32 v[176:177], v[100:101], v[104:105]
	v_pk_mul_f32 v[178:179], v[102:103], v[106:107]
	v_rcp_f32_e32 v220, v216
	v_rcp_f32_e32 v221, v217
	v_rcp_f32_e32 v222, v218
	v_rcp_f32_e32 v223, v219
	v_lshlrev_b32_e32 v180, 16, v112
	v_and_b32_e32 v181, 0xffff0000, v112
	v_lshlrev_b32_e32 v182, 16, v113
	v_and_b32_e32 v183, 0xffff0000, v113
	v_pk_mul_f32 v[180:181], v[180:181], v[184:185]
	v_pk_mul_f32 v[182:183], v[182:183], v[186:187]
	v_pk_mul_f32 v[228:229], v[108:109], v[216:217]
	v_pk_mul_f32 v[230:231], v[110:111], v[218:219]
	v_pk_mul_f32 v[176:177], v[176:177], v[220:221]
	v_pk_mul_f32 v[178:179], v[178:179], v[222:223]
	v_pk_mul_f32 v[180:181], v[180:181], v[220:221]
	v_pk_mul_f32 v[182:183], v[182:183], v[222:223]
	v_lshlrev_b32_e32 v203, 16, v114
	ds_write2_b32 v208, v176, v177 offset0:0 offset1:16
	ds_write2_b32 v208, v178, v179 offset0:32 offset1:48
	ds_write2_b32 v208, v180, v181 offset0:64 offset1:80
	ds_write2_b32 v208, v182, v183 offset0:96 offset1:112
	ds_read_b128 v[64:67], v209 offset:0
	ds_read_b128 v[68:71], v209 offset:16
	ds_read_b128 v[72:75], v209 offset:32
	ds_read_b128 v[76:79], v209 offset:48
	ds_read_b128 v[80:83], v209 offset:256
	ds_read_b128 v[84:87], v209 offset:272
	ds_read_b128 v[88:91], v209 offset:288
	ds_read_b128 v[92:95], v209 offset:304
	v_mul_f32_dpp v196, v224, v0 row_newbcast:0 row_mask:0xf bank_mask:0xf
	v_mul_f32_dpp v197, v225, v1 row_newbcast:0 row_mask:0xf bank_mask:0xf
	v_mul_f32_dpp v198, v226, v2 row_newbcast:0 row_mask:0xf bank_mask:0xf
	v_mul_f32_dpp v199, v227, v3 row_newbcast:0 row_mask:0xf bank_mask:0xf
	v_fmac_f32_dpp v196, v224, v4 row_newbcast:1 row_mask:0xf bank_mask:0xf
	v_fmac_f32_dpp v197, v225, v5 row_newbcast:1 row_mask:0xf bank_mask:0xf
	v_fmac_f32_dpp v198, v226, v6 row_newbcast:1 row_mask:0xf bank_mask:0xf
	v_fmac_f32_dpp v199, v227, v7 row_newbcast:1 row_mask:0xf bank_mask:0xf
	v_fmac_f32_dpp v196, v224, v8 row_newbcast:2 row_mask:0xf bank_mask:0xf
	v_fmac_f32_dpp v197, v225, v9 row_newbcast:2 row_mask:0xf bank_mask:0xf
	v_fmac_f32_dpp v198, v226, v10 row_newbcast:2 row_mask:0xf bank_mask:0xf
	v_fmac_f32_dpp v199, v227, v11 row_newbcast:2 row_mask:0xf bank_mask:0xf
	v_fmac_f32_dpp v196, v224, v12 row_newbcast:3 row_mask:0xf bank_mask:0xf
	v_fmac_f32_dpp v197, v225, v13 row_newbcast:3 row_mask:0xf bank_mask:0xf
	v_fmac_f32_dpp v198, v226, v14 row_newbcast:3 row_mask:0xf bank_mask:0xf
	v_fmac_f32_dpp v199, v227, v15 row_newbcast:3 row_mask:0xf bank_mask:0xf
	v_fmac_f32_dpp v196, v224, v16 row_newbcast:4 row_mask:0xf bank_mask:0xf
	v_fmac_f32_dpp v197, v225, v17 row_newbcast:4 row_mask:0xf bank_mask:0xf
	v_fmac_f32_dpp v198, v226, v18 row_newbcast:4 row_mask:0xf bank_mask:0xf
	v_fmac_f32_dpp v199, v227, v19 row_newbcast:4 row_mask:0xf bank_mask:0xf
	v_fmac_f32_dpp v196, v224, v20 row_newbcast:5 row_mask:0xf bank_mask:0xf
	v_fmac_f32_dpp v197, v225, v21 row_newbcast:5 row_mask:0xf bank_mask:0xf
	v_fmac_f32_dpp v198, v226, v22 row_newbcast:5 row_mask:0xf bank_mask:0xf
	v_fmac_f32_dpp v199, v227, v23 row_newbcast:5 row_mask:0xf bank_mask:0xf
	v_fmac_f32_dpp v196, v224, v24 row_newbcast:6 row_mask:0xf bank_mask:0xf
	v_fmac_f32_dpp v197, v225, v25 row_newbcast:6 row_mask:0xf bank_mask:0xf
	v_fmac_f32_dpp v198, v226, v26 row_newbcast:6 row_mask:0xf bank_mask:0xf
	v_fmac_f32_dpp v199, v227, v27 row_newbcast:6 row_mask:0xf bank_mask:0xf
	v_fmac_f32_dpp v196, v224, v28 row_newbcast:7 row_mask:0xf bank_mask:0xf
	v_fmac_f32_dpp v197, v225, v29 row_newbcast:7 row_mask:0xf bank_mask:0xf
	v_fmac_f32_dpp v198, v226, v30 row_newbcast:7 row_mask:0xf bank_mask:0xf
	v_fmac_f32_dpp v199, v227, v31 row_newbcast:7 row_mask:0xf bank_mask:0xf
	v_fmac_f32_dpp v196, v224, v32 row_newbcast:8 row_mask:0xf bank_mask:0xf
	v_fmac_f32_dpp v197, v225, v33 row_newbcast:8 row_mask:0xf bank_mask:0xf
	v_fmac_f32_dpp v198, v226, v34 row_newbcast:8 row_mask:0xf bank_mask:0xf
	v_fmac_f32_dpp v199, v227, v35 row_newbcast:8 row_mask:0xf bank_mask:0xf
	v_fmac_f32_dpp v196, v224, v36 row_newbcast:9 row_mask:0xf bank_mask:0xf
	v_fmac_f32_dpp v197, v225, v37 row_newbcast:9 row_mask:0xf bank_mask:0xf
	v_fmac_f32_dpp v198, v226, v38 row_newbcast:9 row_mask:0xf bank_mask:0xf
	v_fmac_f32_dpp v199, v227, v39 row_newbcast:9 row_mask:0xf bank_mask:0xf
	v_fmac_f32_dpp v196, v224, v40 row_newbcast:10 row_mask:0xf bank_mask:0xf
	v_fmac_f32_dpp v197, v225, v41 row_newbcast:10 row_mask:0xf bank_mask:0xf
	v_fmac_f32_dpp v198, v226, v42 row_newbcast:10 row_mask:0xf bank_mask:0xf
	v_fmac_f32_dpp v199, v227, v43 row_newbcast:10 row_mask:0xf bank_mask:0xf
	v_fmac_f32_dpp v196, v224, v44 row_newbcast:11 row_mask:0xf bank_mask:0xf
	v_fmac_f32_dpp v197, v225, v45 row_newbcast:11 row_mask:0xf bank_mask:0xf
	v_fmac_f32_dpp v198, v226, v46 row_newbcast:11 row_mask:0xf bank_mask:0xf
	v_fmac_f32_dpp v199, v227, v47 row_newbcast:11 row_mask:0xf bank_mask:0xf
	v_fmac_f32_dpp v196, v224, v48 row_newbcast:12 row_mask:0xf bank_mask:0xf
	v_fmac_f32_dpp v197, v225, v49 row_newbcast:12 row_mask:0xf bank_mask:0xf
	v_fmac_f32_dpp v198, v226, v50 row_newbcast:12 row_mask:0xf bank_mask:0xf
	v_fmac_f32_dpp v199, v227, v51 row_newbcast:12 row_mask:0xf bank_mask:0xf
	v_fmac_f32_dpp v196, v224, v52 row_newbcast:13 row_mask:0xf bank_mask:0xf
	v_fmac_f32_dpp v197, v225, v53 row_newbcast:13 row_mask:0xf bank_mask:0xf
	v_fmac_f32_dpp v198, v226, v54 row_newbcast:13 row_mask:0xf bank_mask:0xf
	v_fmac_f32_dpp v199, v227, v55 row_newbcast:13 row_mask:0xf bank_mask:0xf
	v_fmac_f32_dpp v196, v224, v56 row_newbcast:14 row_mask:0xf bank_mask:0xf
	v_fmac_f32_dpp v197, v225, v57 row_newbcast:14 row_mask:0xf bank_mask:0xf
	v_fmac_f32_dpp v198, v226, v58 row_newbcast:14 row_mask:0xf bank_mask:0xf
	v_fmac_f32_dpp v199, v227, v59 row_newbcast:14 row_mask:0xf bank_mask:0xf
	v_fmac_f32_dpp v196, v224, v60 row_newbcast:15 row_mask:0xf bank_mask:0xf
	v_fmac_f32_dpp v197, v225, v61 row_newbcast:15 row_mask:0xf bank_mask:0xf
	v_fmac_f32_dpp v198, v226, v62 row_newbcast:15 row_mask:0xf bank_mask:0xf
	v_fmac_f32_dpp v199, v227, v63 row_newbcast:15 row_mask:0xf bank_mask:0xf
	v_add_f32_e32 v196, v196, v197
	v_add_f32_e32 v198, v198, v199
	v_sub_f32_e64 v202, -v196, v198
	s_waitcnt lgkmcnt(0)
;     static __device__ __forceinline__ void upd(float (&S)[64], const In2& in, float sa, float vv, float& y0, float& y1) {
;         float t0, t1, t2, t3;
;         asm volatile("v_mul_f32_dpp %0, %10, %27 row_newbcast:%28" DPPM "v_mul_f32_dpp %1, %11, %27 row_newbcast:%28" DPPM "v_mul_f32_dpp %2, %12, %27 row_newbcast:%28" DPPM "v_mul_f32_dpp %3, %13, %27 row_newbcast:%28" DPPM
;                      "v_fmac_f32_dpp %0, %14, %6 row_newbcast:%28" DPPM "v_fmac_f32_dpp %1, %15, %7 row_newbcast:%28" DPPM "v_fmac_f32_dpp %2, %16, %8 row_newbcast:%28" DPPM "v_fmac_f32_dpp %3, %17, %9 row_newbcast:%28" DPPM
;                      "v_fmac_f32_dpp %0, %18, %26 row_newbcast:%28" DPPM "v_fmac_f32_dpp %1, %19, %26 row_newbcast:%28" DPPM "v_fmac_f32_dpp %2, %20, %26 row_newbcast:%28" DPPM "v_fmac_f32_dpp %3, %21, %26 row_newbcast:%28" DPPM
;                      "v_fmac_f32_dpp %4, %22, %0 row_newbcast:%28" DPPM "v_fmac_f32_dpp %5, %23, %1 row_newbcast:%28" DPPM "v_fmac_f32_dpp %4, %24, %2 row_newbcast:%28" DPPM "v_fmac_f32_dpp %5, %25, %3 row_newbcast:%28" DPPM
;                      : "=&v"(t0), "=&v"(t1), "=&v"(t2), "=&v"(t3), "+v"(y0), "+v"(y1)
;                      : "v"(S[K]), "v"(S[K + 1]), "v"(S[K + 2]), "v"(S[K + 3]), "v"(in.kd[0]), "v"(in.kd[1]), "v"(in.kd[2]), "v"(in.kd[3]), "v"(in.w[0]), "v"(in.w[1]), "v"(in.w[2]), "v"(in.w[3]),
;                        "v"(in.b[0]), "v"(in.b[1]), "v"(in.b[2]), "v"(in.b[3]), "v"(in.r[0]), "v"(in.r[1]), "v"(in.r[2]), "v"(in.r[3]), "v"(sa), "v"(vv), "n"(N0));
;         S[K] = t0; S[K + 1] = t1; S[K + 2] = t2; S[K + 3] = t3;
;         if constexpr (K + 4 < 64) ScanK<K + 4>::upd(S, in, sa, vv, y0, y1);
;     }
	s_nop 1
	v_mfma_f32_4x4x1_16b_f32 v[0:3], v64, v202, v[0:3]
	v_mfma_f32_4x4x1_16b_f32 v[4:7], v65, v202, v[4:7]
	v_mfma_f32_4x4x1_16b_f32 v[8:11], v66, v202, v[8:11]
	v_mfma_f32_4x4x1_16b_f32 v[12:15], v67, v202, v[12:15]
	v_mfma_f32_4x4x1_16b_f32 v[16:19], v68, v202, v[16:19]
	v_mfma_f32_4x4x1_16b_f32 v[20:23], v69, v202, v[20:23]
	v_mfma_f32_4x4x1_16b_f32 v[24:27], v70, v202, v[24:27]
	v_mfma_f32_4x4x1_16b_f32 v[28:31], v71, v202, v[28:31]
	v_mfma_f32_4x4x1_16b_f32 v[32:35], v72, v202, v[32:35]
	v_mfma_f32_4x4x1_16b_f32 v[36:39], v73, v202, v[36:39]
	v_mfma_f32_4x4x1_16b_f32 v[40:43], v74, v202, v[40:43]
	v_mfma_f32_4x4x1_16b_f32 v[44:47], v75, v202, v[44:47]
	v_mfma_f32_4x4x1_16b_f32 v[48:51], v76, v202, v[48:51]
	v_mfma_f32_4x4x1_16b_f32 v[52:55], v77, v202, v[52:55]
	v_mfma_f32_4x4x1_16b_f32 v[56:59], v78, v202, v[56:59]
	v_mfma_f32_4x4x1_16b_f32 v[60:63], v79, v202, v[60:63]
	v_mfma_f32_4x4x1_16b_f32 v[0:3], v80, v203, v[0:3]
	v_mfma_f32_4x4x1_16b_f32 v[4:7], v81, v203, v[4:7]
	v_mfma_f32_4x4x1_16b_f32 v[8:11], v82, v203, v[8:11]
	v_mfma_f32_4x4x1_16b_f32 v[12:15], v83, v203, v[12:15]
	v_mfma_f32_4x4x1_16b_f32 v[16:19], v84, v203, v[16:19]
	v_mfma_f32_4x4x1_16b_f32 v[20:23], v85, v203, v[20:23]
	v_mfma_f32_4x4x1_16b_f32 v[24:27], v86, v203, v[24:27]
	v_mfma_f32_4x4x1_16b_f32 v[28:31], v87, v203, v[28:31]
	v_mfma_f32_4x4x1_16b_f32 v[32:35], v88, v203, v[32:35]
	v_mfma_f32_4x4x1_16b_f32 v[36:39], v89, v203, v[36:39]
	v_mfma_f32_4x4x1_16b_f32 v[40:43], v90, v203, v[40:43]
	v_mfma_f32_4x4x1_16b_f32 v[44:47], v91, v203, v[44:47]
	v_mfma_f32_4x4x1_16b_f32 v[48:51], v92, v203, v[48:51]
	v_mfma_f32_4x4x1_16b_f32 v[52:55], v93, v203, v[52:55]
	v_mfma_f32_4x4x1_16b_f32 v[56:59], v94, v203, v[56:59]
	v_mfma_f32_4x4x1_16b_f32 v[60:63], v95, v203, v[60:63]
	v_mul_f32_dpp v200, v228, v0 row_newbcast:0 row_mask:0xf bank_mask:0xf
	v_mul_f32_dpp v201, v229, v1 row_newbcast:0 row_mask:0xf bank_mask:0xf
	v_fmac_f32_dpp v200, v230, v2 row_newbcast:0 row_mask:0xf bank_mask:0xf
	v_fmac_f32_dpp v201, v231, v3 row_newbcast:0 row_mask:0xf bank_mask:0xf
	v_fmac_f32_dpp v200, v228, v4 row_newbcast:1 row_mask:0xf bank_mask:0xf
	v_fmac_f32_dpp v201, v229, v5 row_newbcast:1 row_mask:0xf bank_mask:0xf
	v_fmac_f32_dpp v200, v230, v6 row_newbcast:1 row_mask:0xf bank_mask:0xf
	v_fmac_f32_dpp v201, v231, v7 row_newbcast:1 row_mask:0xf bank_mask:0xf
	v_fmac_f32_dpp v200, v228, v8 row_newbcast:2 row_mask:0xf bank_mask:0xf
	v_fmac_f32_dpp v201, v229, v9 row_newbcast:2 row_mask:0xf bank_mask:0xf
	v_fmac_f32_dpp v200, v230, v10 row_newbcast:2 row_mask:0xf bank_mask:0xf
	v_fmac_f32_dpp v201, v231, v11 row_newbcast:2 row_mask:0xf bank_mask:0xf
	v_fmac_f32_dpp v200, v228, v12 row_newbcast:3 row_mask:0xf bank_mask:0xf
	v_fmac_f32_dpp v201, v229, v13 row_newbcast:3 row_mask:0xf bank_mask:0xf
	v_fmac_f32_dpp v200, v230, v14 row_newbcast:3 row_mask:0xf bank_mask:0xf
	v_fmac_f32_dpp v201, v231, v15 row_newbcast:3 row_mask:0xf bank_mask:0xf
	v_fmac_f32_dpp v200, v228, v16 row_newbcast:4 row_mask:0xf bank_mask:0xf
	v_fmac_f32_dpp v201, v229, v17 row_newbcast:4 row_mask:0xf bank_mask:0xf
	v_fmac_f32_dpp v200, v230, v18 row_newbcast:4 row_mask:0xf bank_mask:0xf
	v_fmac_f32_dpp v201, v231, v19 row_newbcast:4 row_mask:0xf bank_mask:0xf
	v_fmac_f32_dpp v200, v228, v20 row_newbcast:5 row_mask:0xf bank_mask:0xf
	v_fmac_f32_dpp v201, v229, v21 row_newbcast:5 row_mask:0xf bank_mask:0xf
	v_fmac_f32_dpp v200, v230, v22 row_newbcast:5 row_mask:0xf bank_mask:0xf
	v_fmac_f32_dpp v201, v231, v23 row_newbcast:5 row_mask:0xf bank_mask:0xf
	v_fmac_f32_dpp v200, v228, v24 row_newbcast:6 row_mask:0xf bank_mask:0xf
	v_fmac_f32_dpp v201, v229, v25 row_newbcast:6 row_mask:0xf bank_mask:0xf
	v_fmac_f32_dpp v200, v230, v26 row_newbcast:6 row_mask:0xf bank_mask:0xf
	v_fmac_f32_dpp v201, v231, v27 row_newbcast:6 row_mask:0xf bank_mask:0xf
	v_fmac_f32_dpp v200, v228, v28 row_newbcast:7 row_mask:0xf bank_mask:0xf
	v_fmac_f32_dpp v201, v229, v29 row_newbcast:7 row_mask:0xf bank_mask:0xf
	v_fmac_f32_dpp v200, v230, v30 row_newbcast:7 row_mask:0xf bank_mask:0xf
	v_fmac_f32_dpp v201, v231, v31 row_newbcast:7 row_mask:0xf bank_mask:0xf
	v_fmac_f32_dpp v200, v228, v32 row_newbcast:8 row_mask:0xf bank_mask:0xf
	v_fmac_f32_dpp v201, v229, v33 row_newbcast:8 row_mask:0xf bank_mask:0xf
	v_fmac_f32_dpp v200, v230, v34 row_newbcast:8 row_mask:0xf bank_mask:0xf
	v_fmac_f32_dpp v201, v231, v35 row_newbcast:8 row_mask:0xf bank_mask:0xf
	v_fmac_f32_dpp v200, v228, v36 row_newbcast:9 row_mask:0xf bank_mask:0xf
	v_fmac_f32_dpp v201, v229, v37 row_newbcast:9 row_mask:0xf bank_mask:0xf
	v_fmac_f32_dpp v200, v230, v38 row_newbcast:9 row_mask:0xf bank_mask:0xf
	v_fmac_f32_dpp v201, v231, v39 row_newbcast:9 row_mask:0xf bank_mask:0xf
	v_fmac_f32_dpp v200, v228, v40 row_newbcast:10 row_mask:0xf bank_mask:0xf
	v_fmac_f32_dpp v201, v229, v41 row_newbcast:10 row_mask:0xf bank_mask:0xf
	v_fmac_f32_dpp v200, v230, v42 row_newbcast:10 row_mask:0xf bank_mask:0xf
	v_fmac_f32_dpp v201, v231, v43 row_newbcast:10 row_mask:0xf bank_mask:0xf
	v_fmac_f32_dpp v200, v228, v44 row_newbcast:11 row_mask:0xf bank_mask:0xf
	v_fmac_f32_dpp v201, v229, v45 row_newbcast:11 row_mask:0xf bank_mask:0xf
	v_fmac_f32_dpp v200, v230, v46 row_newbcast:11 row_mask:0xf bank_mask:0xf
	v_fmac_f32_dpp v201, v231, v47 row_newbcast:11 row_mask:0xf bank_mask:0xf
	v_fmac_f32_dpp v200, v228, v48 row_newbcast:12 row_mask:0xf bank_mask:0xf
	v_fmac_f32_dpp v201, v229, v49 row_newbcast:12 row_mask:0xf bank_mask:0xf
	v_fmac_f32_dpp v200, v230, v50 row_newbcast:12 row_mask:0xf bank_mask:0xf
	v_fmac_f32_dpp v201, v231, v51 row_newbcast:12 row_mask:0xf bank_mask:0xf
	v_fmac_f32_dpp v200, v228, v52 row_newbcast:13 row_mask:0xf bank_mask:0xf
	v_fmac_f32_dpp v201, v229, v53 row_newbcast:13 row_mask:0xf bank_mask:0xf
	v_fmac_f32_dpp v200, v230, v54 row_newbcast:13 row_mask:0xf bank_mask:0xf
	v_fmac_f32_dpp v201, v231, v55 row_newbcast:13 row_mask:0xf bank_mask:0xf
	v_fmac_f32_dpp v200, v228, v56 row_newbcast:14 row_mask:0xf bank_mask:0xf
	v_fmac_f32_dpp v201, v229, v57 row_newbcast:14 row_mask:0xf bank_mask:0xf
	v_fmac_f32_dpp v200, v230, v58 row_newbcast:14 row_mask:0xf bank_mask:0xf
	v_fmac_f32_dpp v201, v231, v59 row_newbcast:14 row_mask:0xf bank_mask:0xf
	v_fmac_f32_dpp v200, v228, v60 row_newbcast:15 row_mask:0xf bank_mask:0xf
	v_fmac_f32_dpp v201, v229, v61 row_newbcast:15 row_mask:0xf bank_mask:0xf
	v_fmac_f32_dpp v200, v230, v62 row_newbcast:15 row_mask:0xf bank_mask:0xf
	v_fmac_f32_dpp v201, v231, v63 row_newbcast:15 row_mask:0xf bank_mask:0xf
	v_add_f32_e32 v200, v200, v201
	s_waitcnt vmcnt(12)
;     static __device__ __forceinline__ void dot(const float (&S)[64], const f32x4& a, float (&s)[4]) {
;         if constexpr (K == 0) {
;             asm volatile("v_mul_f32_dpp %0, %4, %8 row_newbcast:%16" DPPM "v_mul_f32_dpp %1, %5, %9 row_newbcast:%16" DPPM "v_mul_f32_dpp %2, %6, %10 row_newbcast:%16" DPPM "v_mul_f32_dpp %3, %7, %11 row_newbcast:%16" DPPM
;                          "v_fmac_f32_dpp %0, %4, %12 row_newbcast:%17" DPPM "v_fmac_f32_dpp %1, %5, %13 row_newbcast:%17" DPPM "v_fmac_f32_dpp %2, %6, %14 row_newbcast:%17" DPPM "v_fmac_f32_dpp %3, %7, %15 row_newbcast:%17" DPPM
;                          : "=&v"(s[0]), "=&v"(s[1]), "=&v"(s[2]), "=&v"(s[3])
;                          : "v"(a[0]), "v"(a[1]), "v"(a[2]), "v"(a[3]), "v"(S[K]), "v"(S[K + 1]), "v"(S[K + 2]), "v"(S[K + 3]), "v"(S[K + 4]), "v"(S[K + 5]), "v"(S[K + 6]), "v"(S[K + 7]), "n"(N0), "n"(N1));
;         } else
;         asm volatile("v_fmac_f32_dpp %0, %4, %8 row_newbcast:%16" DPPM "v_fmac_f32_dpp %1, %5, %9 row_newbcast:%16" DPPM "v_fmac_f32_dpp %2, %6, %10 row_newbcast:%16" DPPM "v_fmac_f32_dpp %3, %7, %11 row_newbcast:%16" DPPM
;                      "v_fmac_f32_dpp %0, %4, %12 row_newbcast:%17" DPPM "v_fmac_f32_dpp %1, %5, %13 row_newbcast:%17" DPPM "v_fmac_f32_dpp %2, %6, %14 row_newbcast:%17" DPPM "v_fmac_f32_dpp %3, %7, %15 row_newbcast:%17" DPPM
;                      : "+v"(s[0]), "+v"(s[1]), "+v"(s[2]), "+v"(s[3])
;                      : "v"(a[0]), "v"(a[1]), "v"(a[2]), "v"(a[3]), "v"(S[K]), "v"(S[K + 1]), "v"(S[K + 2]), "v"(S[K + 3]), "v"(S[K + 4]), "v"(S[K + 5]), "v"(S[K + 6]), "v"(S[K + 7]), "n"(N0), "n"(N1));
;         if constexpr (K + 8 < 64) ScanK<K + 8>::dot(S, a, s);
;     }
;     static __device__ __forceinline__ void upd(float (&S)[64], const In2& in, float sa, float vv, float& y0, float& y1) {
;         float t0, t1, t2, t3;
;         asm volatile("v_mul_f32_dpp %0, %10, %27 row_newbcast:%28" DPPM "v_mul_f32_dpp %1, %11, %27 row_newbcast:%28" DPPM "v_mul_f32_dpp %2, %12, %27 row_newbcast:%28" DPPM "v_mul_f32_dpp %3, %13, %27 row_newbcast:%28" DPPM
;                      "v_fmac_f32_dpp %0, %14, %6 row_newbcast:%28" DPPM "v_fmac_f32_dpp %1, %15, %7 row_newbcast:%28" DPPM "v_fmac_f32_dpp %2, %16, %8 row_newbcast:%28" DPPM "v_fmac_f32_dpp %3, %17, %9 row_newbcast:%28" DPPM
	buffer_store_dword v200, v207, s[68:71], s79 offen
	s_add_u32 s79, s79, 0x1000
	buffer_load_dwordx4 v[96:99], v232, s[64:67], s72 offen
	buffer_load_dwordx4 v[100:103], v233, s[64:67], s72 offen
	buffer_load_dwordx4 v[104:107], v234, s[64:67], s72 offen
	buffer_load_dwordx4 v[108:111], v235, s[64:67], s72 offen
	buffer_load_dwordx2 v[112:113], v236, s[64:67], s76 offen
	buffer_load_ushort v114, v237, s[64:67], s76 offen
	s_add_u32 s72, s72, 0x1000
	s_add_u32 s76, s76, 0x800
	v_pk_mul_f32 v[224:225], v[120:121], v[216:217]
	v_pk_mul_f32 v[226:227], v[122:123], v[218:219]
	v_pk_mul_f32 v[216:217], v[216:217], v[116:117]
	v_pk_mul_f32 v[218:219], v[218:219], v[118:119]
	v_pk_fma_f32 v[184:185], v[124:125], v[188:189], v[192:193]
	v_pk_fma_f32 v[186:187], v[126:127], v[190:191], v[194:195]
	v_pk_mul_f32 v[176:177], v[120:121], v[124:125]
	v_pk_mul_f32 v[178:179], v[122:123], v[126:127]
	v_rcp_f32_e32 v220, v216
	v_rcp_f32_e32 v221, v217
	v_rcp_f32_e32 v222, v218
	v_rcp_f32_e32 v223, v219
	v_lshlrev_b32_e32 v180, 16, v132
	v_and_b32_e32 v181, 0xffff0000, v132
	v_lshlrev_b32_e32 v182, 16, v133
	v_and_b32_e32 v183, 0xffff0000, v133
	v_pk_mul_f32 v[180:181], v[180:181], v[184:185]
	v_pk_mul_f32 v[182:183], v[182:183], v[186:187]
	v_pk_mul_f32 v[228:229], v[128:129], v[216:217]
	v_pk_mul_f32 v[230:231], v[130:131], v[218:219]
	v_pk_mul_f32 v[176:177], v[176:177], v[220:221]
	v_pk_mul_f32 v[178:179], v[178:179], v[222:223]
	v_pk_mul_f32 v[180:181], v[180:181], v[220:221]
	v_pk_mul_f32 v[182:183], v[182:183], v[222:223]
	v_lshlrev_b32_e32 v203, 16, v134
	ds_write2_b32 v208, v176, v177 offset0:0 offset1:16
	ds_write2_b32 v208, v178, v179 offset0:32 offset1:48
	ds_write2_b32 v208, v180, v181 offset0:64 offset1:80
	ds_write2_b32 v208, v182, v183 offset0:96 offset1:112
	ds_read_b128 v[64:67], v209 offset:0
	ds_read_b128 v[68:71], v209 offset:16
	ds_read_b128 v[72:75], v209 offset:32
	ds_read_b128 v[76:79], v209 offset:48
	ds_read_b128 v[80:83], v209 offset:256
	ds_read_b128 v[84:87], v209 offset:272
	ds_read_b128 v[88:91], v209 offset:288
	ds_read_b128 v[92:95], v209 offset:304
	v_mul_f32_dpp v196, v224, v0 row_newbcast:0 row_mask:0xf bank_mask:0xf
	v_mul_f32_dpp v197, v225, v1 row_newbcast:0 row_mask:0xf bank_mask:0xf
	v_mul_f32_dpp v198, v226, v2 row_newbcast:0 row_mask:0xf bank_mask:0xf
	v_mul_f32_dpp v199, v227, v3 row_newbcast:0 row_mask:0xf bank_mask:0xf
	v_fmac_f32_dpp v196, v224, v4 row_newbcast:1 row_mask:0xf bank_mask:0xf
	v_fmac_f32_dpp v197, v225, v5 row_newbcast:1 row_mask:0xf bank_mask:0xf
	v_fmac_f32_dpp v198, v226, v6 row_newbcast:1 row_mask:0xf bank_mask:0xf
	v_fmac_f32_dpp v199, v227, v7 row_newbcast:1 row_mask:0xf bank_mask:0xf
	v_fmac_f32_dpp v196, v224, v8 row_newbcast:2 row_mask:0xf bank_mask:0xf
	v_fmac_f32_dpp v197, v225, v9 row_newbcast:2 row_mask:0xf bank_mask:0xf
	v_fmac_f32_dpp v198, v226, v10 row_newbcast:2 row_mask:0xf bank_mask:0xf
	v_fmac_f32_dpp v199, v227, v11 row_newbcast:2 row_mask:0xf bank_mask:0xf
	v_fmac_f32_dpp v196, v224, v12 row_newbcast:3 row_mask:0xf bank_mask:0xf
	v_fmac_f32_dpp v197, v225, v13 row_newbcast:3 row_mask:0xf bank_mask:0xf
	v_fmac_f32_dpp v198, v226, v14 row_newbcast:3 row_mask:0xf bank_mask:0xf
	v_fmac_f32_dpp v199, v227, v15 row_newbcast:3 row_mask:0xf bank_mask:0xf
	v_fmac_f32_dpp v196, v224, v16 row_newbcast:4 row_mask:0xf bank_mask:0xf
	v_fmac_f32_dpp v197, v225, v17 row_newbcast:4 row_mask:0xf bank_mask:0xf
	v_fmac_f32_dpp v198, v226, v18 row_newbcast:4 row_mask:0xf bank_mask:0xf
	v_fmac_f32_dpp v199, v227, v19 row_newbcast:4 row_mask:0xf bank_mask:0xf
	v_fmac_f32_dpp v196, v224, v20 row_newbcast:5 row_mask:0xf bank_mask:0xf
	v_fmac_f32_dpp v197, v225, v21 row_newbcast:5 row_mask:0xf bank_mask:0xf
	v_fmac_f32_dpp v198, v226, v22 row_newbcast:5 row_mask:0xf bank_mask:0xf
	v_fmac_f32_dpp v199, v227, v23 row_newbcast:5 row_mask:0xf bank_mask:0xf
	v_fmac_f32_dpp v196, v224, v24 row_newbcast:6 row_mask:0xf bank_mask:0xf
	v_fmac_f32_dpp v197, v225, v25 row_newbcast:6 row_mask:0xf bank_mask:0xf
	v_fmac_f32_dpp v198, v226, v26 row_newbcast:6 row_mask:0xf bank_mask:0xf
	v_fmac_f32_dpp v199, v227, v27 row_newbcast:6 row_mask:0xf bank_mask:0xf
	v_fmac_f32_dpp v196, v224, v28 row_newbcast:7 row_mask:0xf bank_mask:0xf
	v_fmac_f32_dpp v197, v225, v29 row_newbcast:7 row_mask:0xf bank_mask:0xf
	v_fmac_f32_dpp v198, v226, v30 row_newbcast:7 row_mask:0xf bank_mask:0xf
	v_fmac_f32_dpp v199, v227, v31 row_newbcast:7 row_mask:0xf bank_mask:0xf
	v_fmac_f32_dpp v196, v224, v32 row_newbcast:8 row_mask:0xf bank_mask:0xf
	v_fmac_f32_dpp v197, v225, v33 row_newbcast:8 row_mask:0xf bank_mask:0xf
	v_fmac_f32_dpp v198, v226, v34 row_newbcast:8 row_mask:0xf bank_mask:0xf
	v_fmac_f32_dpp v199, v227, v35 row_newbcast:8 row_mask:0xf bank_mask:0xf
	v_fmac_f32_dpp v196, v224, v36 row_newbcast:9 row_mask:0xf bank_mask:0xf
	v_fmac_f32_dpp v197, v225, v37 row_newbcast:9 row_mask:0xf bank_mask:0xf
	v_fmac_f32_dpp v198, v226, v38 row_newbcast:9 row_mask:0xf bank_mask:0xf
	v_fmac_f32_dpp v199, v227, v39 row_newbcast:9 row_mask:0xf bank_mask:0xf
	v_fmac_f32_dpp v196, v224, v40 row_newbcast:10 row_mask:0xf bank_mask:0xf
	v_fmac_f32_dpp v197, v225, v41 row_newbcast:10 row_mask:0xf bank_mask:0xf
	v_fmac_f32_dpp v198, v226, v42 row_newbcast:10 row_mask:0xf bank_mask:0xf
	v_fmac_f32_dpp v199, v227, v43 row_newbcast:10 row_mask:0xf bank_mask:0xf
	v_fmac_f32_dpp v196, v224, v44 row_newbcast:11 row_mask:0xf bank_mask:0xf
	v_fmac_f32_dpp v197, v225, v45 row_newbcast:11 row_mask:0xf bank_mask:0xf
	v_fmac_f32_dpp v198, v226, v46 row_newbcast:11 row_mask:0xf bank_mask:0xf
	v_fmac_f32_dpp v199, v227, v47 row_newbcast:11 row_mask:0xf bank_mask:0xf
	v_fmac_f32_dpp v196, v224, v48 row_newbcast:12 row_mask:0xf bank_mask:0xf
	v_fmac_f32_dpp v197, v225, v49 row_newbcast:12 row_mask:0xf bank_mask:0xf
	v_fmac_f32_dpp v198, v226, v50 row_newbcast:12 row_mask:0xf bank_mask:0xf
	v_fmac_f32_dpp v199, v227, v51 row_newbcast:12 row_mask:0xf bank_mask:0xf
	v_fmac_f32_dpp v196, v224, v52 row_newbcast:13 row_mask:0xf bank_mask:0xf
	v_fmac_f32_dpp v197, v225, v53 row_newbcast:13 row_mask:0xf bank_mask:0xf
	v_fmac_f32_dpp v198, v226, v54 row_newbcast:13 row_mask:0xf bank_mask:0xf
	v_fmac_f32_dpp v199, v227, v55 row_newbcast:13 row_mask:0xf bank_mask:0xf
	v_fmac_f32_dpp v196, v224, v56 row_newbcast:14 row_mask:0xf bank_mask:0xf
	v_fmac_f32_dpp v197, v225, v57 row_newbcast:14 row_mask:0xf bank_mask:0xf
	v_fmac_f32_dpp v198, v226, v58 row_newbcast:14 row_mask:0xf bank_mask:0xf
	v_fmac_f32_dpp v199, v227, v59 row_newbcast:14 row_mask:0xf bank_mask:0xf
	v_fmac_f32_dpp v196, v224, v60 row_newbcast:15 row_mask:0xf bank_mask:0xf
	v_fmac_f32_dpp v197, v225, v61 row_newbcast:15 row_mask:0xf bank_mask:0xf
	v_fmac_f32_dpp v198, v226, v62 row_newbcast:15 row_mask:0xf bank_mask:0xf
	v_fmac_f32_dpp v199, v227, v63 row_newbcast:15 row_mask:0xf bank_mask:0xf
	v_add_f32_e32 v196, v196, v197
	v_add_f32_e32 v198, v198, v199
	v_sub_f32_e64 v202, -v196, v198
	s_waitcnt lgkmcnt(0)
;     static __device__ __forceinline__ void upd(float (&S)[64], const In2& in, float sa, float vv, float& y0, float& y1) {
;         float t0, t1, t2, t3;
;         asm volatile("v_mul_f32_dpp %0, %10, %27 row_newbcast:%28" DPPM "v_mul_f32_dpp %1, %11, %27 row_newbcast:%28" DPPM "v_mul_f32_dpp %2, %12, %27 row_newbcast:%28" DPPM "v_mul_f32_dpp %3, %13, %27 row_newbcast:%28" DPPM
;                      "v_fmac_f32_dpp %0, %14, %6 row_newbcast:%28" DPPM "v_fmac_f32_dpp %1, %15, %7 row_newbcast:%28" DPPM "v_fmac_f32_dpp %2, %16, %8 row_newbcast:%28" DPPM "v_fmac_f32_dpp %3, %17, %9 row_newbcast:%28" DPPM
;                      "v_fmac_f32_dpp %0, %18, %26 row_newbcast:%28" DPPM "v_fmac_f32_dpp %1, %19, %26 row_newbcast:%28" DPPM "v_fmac_f32_dpp %2, %20, %26 row_newbcast:%28" DPPM "v_fmac_f32_dpp %3, %21, %26 row_newbcast:%28" DPPM
;                      "v_fmac_f32_dpp %4, %22, %0 row_newbcast:%28" DPPM "v_fmac_f32_dpp %5, %23, %1 row_newbcast:%28" DPPM "v_fmac_f32_dpp %4, %24, %2 row_newbcast:%28" DPPM "v_fmac_f32_dpp %5, %25, %3 row_newbcast:%28" DPPM
;                      : "=&v"(t0), "=&v"(t1), "=&v"(t2), "=&v"(t3), "+v"(y0), "+v"(y1)
;                      : "v"(S[K]), "v"(S[K + 1]), "v"(S[K + 2]), "v"(S[K + 3]), "v"(in.kd[0]), "v"(in.kd[1]), "v"(in.kd[2]), "v"(in.kd[3]), "v"(in.w[0]), "v"(in.w[1]), "v"(in.w[2]), "v"(in.w[3]),
;                        "v"(in.b[0]), "v"(in.b[1]), "v"(in.b[2]), "v"(in.b[3]), "v"(in.r[0]), "v"(in.r[1]), "v"(in.r[2]), "v"(in.r[3]), "v"(sa), "v"(vv), "n"(N0));
;         S[K] = t0; S[K + 1] = t1; S[K + 2] = t2; S[K + 3] = t3;
;         if constexpr (K + 4 < 64) ScanK<K + 4>::upd(S, in, sa, vv, y0, y1);
;     }
	s_nop 1
	v_mfma_f32_4x4x1_16b_f32 v[0:3], v64, v202, v[0:3]
	v_mfma_f32_4x4x1_16b_f32 v[4:7], v65, v202, v[4:7]
	v_mfma_f32_4x4x1_16b_f32 v[8:11], v66, v202, v[8:11]
	v_mfma_f32_4x4x1_16b_f32 v[12:15], v67, v202, v[12:15]
	v_mfma_f32_4x4x1_16b_f32 v[16:19], v68, v202, v[16:19]
	v_mfma_f32_4x4x1_16b_f32 v[20:23], v69, v202, v[20:23]
	v_mfma_f32_4x4x1_16b_f32 v[24:27], v70, v202, v[24:27]
	v_mfma_f32_4x4x1_16b_f32 v[28:31], v71, v202, v[28:31]
	v_mfma_f32_4x4x1_16b_f32 v[32:35], v72, v202, v[32:35]
	v_mfma_f32_4x4x1_16b_f32 v[36:39], v73, v202, v[36:39]
	v_mfma_f32_4x4x1_16b_f32 v[40:43], v74, v202, v[40:43]
	v_mfma_f32_4x4x1_16b_f32 v[44:47], v75, v202, v[44:47]
	v_mfma_f32_4x4x1_16b_f32 v[48:51], v76, v202, v[48:51]
	v_mfma_f32_4x4x1_16b_f32 v[52:55], v77, v202, v[52:55]
	v_mfma_f32_4x4x1_16b_f32 v[56:59], v78, v202, v[56:59]
	v_mfma_f32_4x4x1_16b_f32 v[60:63], v79, v202, v[60:63]
	v_mfma_f32_4x4x1_16b_f32 v[0:3], v80, v203, v[0:3]
	v_mfma_f32_4x4x1_16b_f32 v[4:7], v81, v203, v[4:7]
	v_mfma_f32_4x4x1_16b_f32 v[8:11], v82, v203, v[8:11]
	v_mfma_f32_4x4x1_16b_f32 v[12:15], v83, v203, v[12:15]
	v_mfma_f32_4x4x1_16b_f32 v[16:19], v84, v203, v[16:19]
	v_mfma_f32_4x4x1_16b_f32 v[20:23], v85, v203, v[20:23]
	v_mfma_f32_4x4x1_16b_f32 v[24:27], v86, v203, v[24:27]
	v_mfma_f32_4x4x1_16b_f32 v[28:31], v87, v203, v[28:31]
	v_mfma_f32_4x4x1_16b_f32 v[32:35], v88, v203, v[32:35]
	v_mfma_f32_4x4x1_16b_f32 v[36:39], v89, v203, v[36:39]
	v_mfma_f32_4x4x1_16b_f32 v[40:43], v90, v203, v[40:43]
	v_mfma_f32_4x4x1_16b_f32 v[44:47], v91, v203, v[44:47]
	v_mfma_f32_4x4x1_16b_f32 v[48:51], v92, v203, v[48:51]
	v_mfma_f32_4x4x1_16b_f32 v[52:55], v93, v203, v[52:55]
	v_mfma_f32_4x4x1_16b_f32 v[56:59], v94, v203, v[56:59]
	v_mfma_f32_4x4x1_16b_f32 v[60:63], v95, v203, v[60:63]
	v_mul_f32_dpp v200, v228, v0 row_newbcast:0 row_mask:0xf bank_mask:0xf
	v_mul_f32_dpp v201, v229, v1 row_newbcast:0 row_mask:0xf bank_mask:0xf
	v_fmac_f32_dpp v200, v230, v2 row_newbcast:0 row_mask:0xf bank_mask:0xf
	v_fmac_f32_dpp v201, v231, v3 row_newbcast:0 row_mask:0xf bank_mask:0xf
	v_fmac_f32_dpp v200, v228, v4 row_newbcast:1 row_mask:0xf bank_mask:0xf
	v_fmac_f32_dpp v201, v229, v5 row_newbcast:1 row_mask:0xf bank_mask:0xf
	v_fmac_f32_dpp v200, v230, v6 row_newbcast:1 row_mask:0xf bank_mask:0xf
	v_fmac_f32_dpp v201, v231, v7 row_newbcast:1 row_mask:0xf bank_mask:0xf
	v_fmac_f32_dpp v200, v228, v8 row_newbcast:2 row_mask:0xf bank_mask:0xf
	v_fmac_f32_dpp v201, v229, v9 row_newbcast:2 row_mask:0xf bank_mask:0xf
	v_fmac_f32_dpp v200, v230, v10 row_newbcast:2 row_mask:0xf bank_mask:0xf
	v_fmac_f32_dpp v201, v231, v11 row_newbcast:2 row_mask:0xf bank_mask:0xf
	v_fmac_f32_dpp v200, v228, v12 row_newbcast:3 row_mask:0xf bank_mask:0xf
	v_fmac_f32_dpp v201, v229, v13 row_newbcast:3 row_mask:0xf bank_mask:0xf
	v_fmac_f32_dpp v200, v230, v14 row_newbcast:3 row_mask:0xf bank_mask:0xf
	v_fmac_f32_dpp v201, v231, v15 row_newbcast:3 row_mask:0xf bank_mask:0xf
	v_fmac_f32_dpp v200, v228, v16 row_newbcast:4 row_mask:0xf bank_mask:0xf
	v_fmac_f32_dpp v201, v229, v17 row_newbcast:4 row_mask:0xf bank_mask:0xf
	v_fmac_f32_dpp v200, v230, v18 row_newbcast:4 row_mask:0xf bank_mask:0xf
	v_fmac_f32_dpp v201, v231, v19 row_newbcast:4 row_mask:0xf bank_mask:0xf
	v_fmac_f32_dpp v200, v228, v20 row_newbcast:5 row_mask:0xf bank_mask:0xf
	v_fmac_f32_dpp v201, v229, v21 row_newbcast:5 row_mask:0xf bank_mask:0xf
	v_fmac_f32_dpp v200, v230, v22 row_newbcast:5 row_mask:0xf bank_mask:0xf
	v_fmac_f32_dpp v201, v231, v23 row_newbcast:5 row_mask:0xf bank_mask:0xf
	v_fmac_f32_dpp v200, v228, v24 row_newbcast:6 row_mask:0xf bank_mask:0xf
	v_fmac_f32_dpp v201, v229, v25 row_newbcast:6 row_mask:0xf bank_mask:0xf
	v_fmac_f32_dpp v200, v230, v26 row_newbcast:6 row_mask:0xf bank_mask:0xf
	v_fmac_f32_dpp v201, v231, v27 row_newbcast:6 row_mask:0xf bank_mask:0xf
	v_fmac_f32_dpp v200, v228, v28 row_newbcast:7 row_mask:0xf bank_mask:0xf
	v_fmac_f32_dpp v201, v229, v29 row_newbcast:7 row_mask:0xf bank_mask:0xf
	v_fmac_f32_dpp v200, v230, v30 row_newbcast:7 row_mask:0xf bank_mask:0xf
	v_fmac_f32_dpp v201, v231, v31 row_newbcast:7 row_mask:0xf bank_mask:0xf
	v_fmac_f32_dpp v200, v228, v32 row_newbcast:8 row_mask:0xf bank_mask:0xf
	v_fmac_f32_dpp v201, v229, v33 row_newbcast:8 row_mask:0xf bank_mask:0xf
	v_fmac_f32_dpp v200, v230, v34 row_newbcast:8 row_mask:0xf bank_mask:0xf
	v_fmac_f32_dpp v201, v231, v35 row_newbcast:8 row_mask:0xf bank_mask:0xf
	v_fmac_f32_dpp v200, v228, v36 row_newbcast:9 row_mask:0xf bank_mask:0xf
	v_fmac_f32_dpp v201, v229, v37 row_newbcast:9 row_mask:0xf bank_mask:0xf
	v_fmac_f32_dpp v200, v230, v38 row_newbcast:9 row_mask:0xf bank_mask:0xf
	v_fmac_f32_dpp v201, v231, v39 row_newbcast:9 row_mask:0xf bank_mask:0xf
	v_fmac_f32_dpp v200, v228, v40 row_newbcast:10 row_mask:0xf bank_mask:0xf
	v_fmac_f32_dpp v201, v229, v41 row_newbcast:10 row_mask:0xf bank_mask:0xf
	v_fmac_f32_dpp v200, v230, v42 row_newbcast:10 row_mask:0xf bank_mask:0xf
	v_fmac_f32_dpp v201, v231, v43 row_newbcast:10 row_mask:0xf bank_mask:0xf
	v_fmac_f32_dpp v200, v228, v44 row_newbcast:11 row_mask:0xf bank_mask:0xf
	v_fmac_f32_dpp v201, v229, v45 row_newbcast:11 row_mask:0xf bank_mask:0xf
	v_fmac_f32_dpp v200, v230, v46 row_newbcast:11 row_mask:0xf bank_mask:0xf
	v_fmac_f32_dpp v201, v231, v47 row_newbcast:11 row_mask:0xf bank_mask:0xf
	v_fmac_f32_dpp v200, v228, v48 row_newbcast:12 row_mask:0xf bank_mask:0xf
	v_fmac_f32_dpp v201, v229, v49 row_newbcast:12 row_mask:0xf bank_mask:0xf
	v_fmac_f32_dpp v200, v230, v50 row_newbcast:12 row_mask:0xf bank_mask:0xf
	v_fmac_f32_dpp v201, v231, v51 row_newbcast:12 row_mask:0xf bank_mask:0xf
	v_fmac_f32_dpp v200, v228, v52 row_newbcast:13 row_mask:0xf bank_mask:0xf
	v_fmac_f32_dpp v201, v229, v53 row_newbcast:13 row_mask:0xf bank_mask:0xf
	v_fmac_f32_dpp v200, v230, v54 row_newbcast:13 row_mask:0xf bank_mask:0xf
	v_fmac_f32_dpp v201, v231, v55 row_newbcast:13 row_mask:0xf bank_mask:0xf
	v_fmac_f32_dpp v200, v228, v56 row_newbcast:14 row_mask:0xf bank_mask:0xf
	v_fmac_f32_dpp v201, v229, v57 row_newbcast:14 row_mask:0xf bank_mask:0xf
	v_fmac_f32_dpp v200, v230, v58 row_newbcast:14 row_mask:0xf bank_mask:0xf
	v_fmac_f32_dpp v201, v231, v59 row_newbcast:14 row_mask:0xf bank_mask:0xf
	v_fmac_f32_dpp v200, v228, v60 row_newbcast:15 row_mask:0xf bank_mask:0xf
	v_fmac_f32_dpp v201, v229, v61 row_newbcast:15 row_mask:0xf bank_mask:0xf
	v_fmac_f32_dpp v200, v230, v62 row_newbcast:15 row_mask:0xf bank_mask:0xf
	v_fmac_f32_dpp v201, v231, v63 row_newbcast:15 row_mask:0xf bank_mask:0xf
	v_add_f32_e32 v200, v200, v201
	s_waitcnt vmcnt(12)
;     static __device__ __forceinline__ void dot(const float (&S)[64], const f32x4& a, float (&s)[4]) {
;         if constexpr (K == 0) {
;             asm volatile("v_mul_f32_dpp %0, %4, %8 row_newbcast:%16" DPPM "v_mul_f32_dpp %1, %5, %9 row_newbcast:%16" DPPM "v_mul_f32_dpp %2, %6, %10 row_newbcast:%16" DPPM "v_mul_f32_dpp %3, %7, %11 row_newbcast:%16" DPPM
;                          "v_fmac_f32_dpp %0, %4, %12 row_newbcast:%17" DPPM "v_fmac_f32_dpp %1, %5, %13 row_newbcast:%17" DPPM "v_fmac_f32_dpp %2, %6, %14 row_newbcast:%17" DPPM "v_fmac_f32_dpp %3, %7, %15 row_newbcast:%17" DPPM
;                          : "=&v"(s[0]), "=&v"(s[1]), "=&v"(s[2]), "=&v"(s[3])
;                          : "v"(a[0]), "v"(a[1]), "v"(a[2]), "v"(a[3]), "v"(S[K]), "v"(S[K + 1]), "v"(S[K + 2]), "v"(S[K + 3]), "v"(S[K + 4]), "v"(S[K + 5]), "v"(S[K + 6]), "v"(S[K + 7]), "n"(N0), "n"(N1));
;         } else
;         asm volatile("v_fmac_f32_dpp %0, %4, %8 row_newbcast:%16" DPPM "v_fmac_f32_dpp %1, %5, %9 row_newbcast:%16" DPPM "v_fmac_f32_dpp %2, %6, %10 row_newbcast:%16" DPPM "v_fmac_f32_dpp %3, %7, %11 row_newbcast:%16" DPPM
;                      "v_fmac_f32_dpp %0, %4, %12 row_newbcast:%17" DPPM "v_fmac_f32_dpp %1, %5, %13 row_newbcast:%17" DPPM "v_fmac_f32_dpp %2, %6, %14 row_newbcast:%17" DPPM "v_fmac_f32_dpp %3, %7, %15 row_newbcast:%17" DPPM
;                      : "+v"(s[0]), "+v"(s[1]), "+v"(s[2]), "+v"(s[3])
;                      : "v"(a[0]), "v"(a[1]), "v"(a[2]), "v"(a[3]), "v"(S[K]), "v"(S[K + 1]), "v"(S[K + 2]), "v"(S[K + 3]), "v"(S[K + 4]), "v"(S[K + 5]), "v"(S[K + 6]), "v"(S[K + 7]), "n"(N0), "n"(N1));
;         if constexpr (K + 8 < 64) ScanK<K + 8>::dot(S, a, s);
;     }
;     static __device__ __forceinline__ void upd(float (&S)[64], const In2& in, float sa, float vv, float& y0, float& y1) {
;         float t0, t1, t2, t3;
;         asm volatile("v_mul_f32_dpp %0, %10, %27 row_newbcast:%28" DPPM "v_mul_f32_dpp %1, %11, %27 row_newbcast:%28" DPPM "v_mul_f32_dpp %2, %12, %27 row_newbcast:%28" DPPM "v_mul_f32_dpp %3, %13, %27 row_newbcast:%28" DPPM
;                      "v_fmac_f32_dpp %0, %14, %6 row_newbcast:%28" DPPM "v_fmac_f32_dpp %1, %15, %7 row_newbcast:%28" DPPM "v_fmac_f32_dpp %2, %16, %8 row_newbcast:%28" DPPM "v_fmac_f32_dpp %3, %17, %9 row_newbcast:%28" DPPM
	buffer_store_dword v200, v207, s[68:71], s79 offen
	s_add_u32 s79, s79, 0x1000
	buffer_load_dwordx4 v[116:119], v232, s[64:67], s72 offen
	buffer_load_dwordx4 v[120:123], v233, s[64:67], s72 offen
	buffer_load_dwordx4 v[124:127], v234, s[64:67], s72 offen
	buffer_load_dwordx4 v[128:131], v235, s[64:67], s72 offen
	buffer_load_dwordx2 v[132:133], v236, s[64:67], s76 offen
	buffer_load_ushort v134, v237, s[64:67], s76 offen
	s_add_u32 s72, s72, 0x1000
	s_add_u32 s76, s76, 0x800
	v_pk_mul_f32 v[224:225], v[140:141], v[216:217]
	v_pk_mul_f32 v[226:227], v[142:143], v[218:219]
	v_pk_mul_f32 v[216:217], v[216:217], v[136:137]
	v_pk_mul_f32 v[218:219], v[218:219], v[138:139]
	v_pk_fma_f32 v[184:185], v[144:145], v[188:189], v[192:193]
	v_pk_fma_f32 v[186:187], v[146:147], v[190:191], v[194:195]
	v_pk_mul_f32 v[176:177], v[140:141], v[144:145]
	v_pk_mul_f32 v[178:179], v[142:143], v[146:147]
	v_rcp_f32_e32 v220, v216
	v_rcp_f32_e32 v221, v217
	v_rcp_f32_e32 v222, v218
	v_rcp_f32_e32 v223, v219
	v_lshlrev_b32_e32 v180, 16, v152
	v_and_b32_e32 v181, 0xffff0000, v152
	v_lshlrev_b32_e32 v182, 16, v153
	v_and_b32_e32 v183, 0xffff0000, v153
	v_pk_mul_f32 v[180:181], v[180:181], v[184:185]
	v_pk_mul_f32 v[182:183], v[182:183], v[186:187]
	v_pk_mul_f32 v[228:229], v[148:149], v[216:217]
	v_pk_mul_f32 v[230:231], v[150:151], v[218:219]
	v_pk_mul_f32 v[176:177], v[176:177], v[220:221]
	v_pk_mul_f32 v[178:179], v[178:179], v[222:223]
	v_pk_mul_f32 v[180:181], v[180:181], v[220:221]
	v_pk_mul_f32 v[182:183], v[182:183], v[222:223]
	v_lshlrev_b32_e32 v203, 16, v154
	ds_write2_b32 v208, v176, v177 offset0:0 offset1:16
	ds_write2_b32 v208, v178, v179 offset0:32 offset1:48
	ds_write2_b32 v208, v180, v181 offset0:64 offset1:80
	ds_write2_b32 v208, v182, v183 offset0:96 offset1:112
	ds_read_b128 v[64:67], v209 offset:0
	ds_read_b128 v[68:71], v209 offset:16
	ds_read_b128 v[72:75], v209 offset:32
	ds_read_b128 v[76:79], v209 offset:48
	ds_read_b128 v[80:83], v209 offset:256
	ds_read_b128 v[84:87], v209 offset:272
	ds_read_b128 v[88:91], v209 offset:288
	ds_read_b128 v[92:95], v209 offset:304
	v_mul_f32_dpp v196, v224, v0 row_newbcast:0 row_mask:0xf bank_mask:0xf
	v_mul_f32_dpp v197, v225, v1 row_newbcast:0 row_mask:0xf bank_mask:0xf
	v_mul_f32_dpp v198, v226, v2 row_newbcast:0 row_mask:0xf bank_mask:0xf
	v_mul_f32_dpp v199, v227, v3 row_newbcast:0 row_mask:0xf bank_mask:0xf
	v_fmac_f32_dpp v196, v224, v4 row_newbcast:1 row_mask:0xf bank_mask:0xf
	v_fmac_f32_dpp v197, v225, v5 row_newbcast:1 row_mask:0xf bank_mask:0xf
	v_fmac_f32_dpp v198, v226, v6 row_newbcast:1 row_mask:0xf bank_mask:0xf
	v_fmac_f32_dpp v199, v227, v7 row_newbcast:1 row_mask:0xf bank_mask:0xf
	v_fmac_f32_dpp v196, v224, v8 row_newbcast:2 row_mask:0xf bank_mask:0xf
	v_fmac_f32_dpp v197, v225, v9 row_newbcast:2 row_mask:0xf bank_mask:0xf
	v_fmac_f32_dpp v198, v226, v10 row_newbcast:2 row_mask:0xf bank_mask:0xf
	v_fmac_f32_dpp v199, v227, v11 row_newbcast:2 row_mask:0xf bank_mask:0xf
	v_fmac_f32_dpp v196, v224, v12 row_newbcast:3 row_mask:0xf bank_mask:0xf
	v_fmac_f32_dpp v197, v225, v13 row_newbcast:3 row_mask:0xf bank_mask:0xf
	v_fmac_f32_dpp v198, v226, v14 row_newbcast:3 row_mask:0xf bank_mask:0xf
	v_fmac_f32_dpp v199, v227, v15 row_newbcast:3 row_mask:0xf bank_mask:0xf
	v_fmac_f32_dpp v196, v224, v16 row_newbcast:4 row_mask:0xf bank_mask:0xf
	v_fmac_f32_dpp v197, v225, v17 row_newbcast:4 row_mask:0xf bank_mask:0xf
	v_fmac_f32_dpp v198, v226, v18 row_newbcast:4 row_mask:0xf bank_mask:0xf
	v_fmac_f32_dpp v199, v227, v19 row_newbcast:4 row_mask:0xf bank_mask:0xf
	v_fmac_f32_dpp v196, v224, v20 row_newbcast:5 row_mask:0xf bank_mask:0xf
	v_fmac_f32_dpp v197, v225, v21 row_newbcast:5 row_mask:0xf bank_mask:0xf
	v_fmac_f32_dpp v198, v226, v22 row_newbcast:5 row_mask:0xf bank_mask:0xf
	v_fmac_f32_dpp v199, v227, v23 row_newbcast:5 row_mask:0xf bank_mask:0xf
	v_fmac_f32_dpp v196, v224, v24 row_newbcast:6 row_mask:0xf bank_mask:0xf
	v_fmac_f32_dpp v197, v225, v25 row_newbcast:6 row_mask:0xf bank_mask:0xf
	v_fmac_f32_dpp v198, v226, v26 row_newbcast:6 row_mask:0xf bank_mask:0xf
	v_fmac_f32_dpp v199, v227, v27 row_newbcast:6 row_mask:0xf bank_mask:0xf
	v_fmac_f32_dpp v196, v224, v28 row_newbcast:7 row_mask:0xf bank_mask:0xf
	v_fmac_f32_dpp v197, v225, v29 row_newbcast:7 row_mask:0xf bank_mask:0xf
	v_fmac_f32_dpp v198, v226, v30 row_newbcast:7 row_mask:0xf bank_mask:0xf
	v_fmac_f32_dpp v199, v227, v31 row_newbcast:7 row_mask:0xf bank_mask:0xf
	v_fmac_f32_dpp v196, v224, v32 row_newbcast:8 row_mask:0xf bank_mask:0xf
	v_fmac_f32_dpp v197, v225, v33 row_newbcast:8 row_mask:0xf bank_mask:0xf
	v_fmac_f32_dpp v198, v226, v34 row_newbcast:8 row_mask:0xf bank_mask:0xf
	v_fmac_f32_dpp v199, v227, v35 row_newbcast:8 row_mask:0xf bank_mask:0xf
	v_fmac_f32_dpp v196, v224, v36 row_newbcast:9 row_mask:0xf bank_mask:0xf
	v_fmac_f32_dpp v197, v225, v37 row_newbcast:9 row_mask:0xf bank_mask:0xf
	v_fmac_f32_dpp v198, v226, v38 row_newbcast:9 row_mask:0xf bank_mask:0xf
	v_fmac_f32_dpp v199, v227, v39 row_newbcast:9 row_mask:0xf bank_mask:0xf
	v_fmac_f32_dpp v196, v224, v40 row_newbcast:10 row_mask:0xf bank_mask:0xf
	v_fmac_f32_dpp v197, v225, v41 row_newbcast:10 row_mask:0xf bank_mask:0xf
	v_fmac_f32_dpp v198, v226, v42 row_newbcast:10 row_mask:0xf bank_mask:0xf
	v_fmac_f32_dpp v199, v227, v43 row_newbcast:10 row_mask:0xf bank_mask:0xf
	v_fmac_f32_dpp v196, v224, v44 row_newbcast:11 row_mask:0xf bank_mask:0xf
	v_fmac_f32_dpp v197, v225, v45 row_newbcast:11 row_mask:0xf bank_mask:0xf
	v_fmac_f32_dpp v198, v226, v46 row_newbcast:11 row_mask:0xf bank_mask:0xf
	v_fmac_f32_dpp v199, v227, v47 row_newbcast:11 row_mask:0xf bank_mask:0xf
	v_fmac_f32_dpp v196, v224, v48 row_newbcast:12 row_mask:0xf bank_mask:0xf
	v_fmac_f32_dpp v197, v225, v49 row_newbcast:12 row_mask:0xf bank_mask:0xf
	v_fmac_f32_dpp v198, v226, v50 row_newbcast:12 row_mask:0xf bank_mask:0xf
	v_fmac_f32_dpp v199, v227, v51 row_newbcast:12 row_mask:0xf bank_mask:0xf
	v_fmac_f32_dpp v196, v224, v52 row_newbcast:13 row_mask:0xf bank_mask:0xf
	v_fmac_f32_dpp v197, v225, v53 row_newbcast:13 row_mask:0xf bank_mask:0xf
	v_fmac_f32_dpp v198, v226, v54 row_newbcast:13 row_mask:0xf bank_mask:0xf
	v_fmac_f32_dpp v199, v227, v55 row_newbcast:13 row_mask:0xf bank_mask:0xf
	v_fmac_f32_dpp v196, v224, v56 row_newbcast:14 row_mask:0xf bank_mask:0xf
	v_fmac_f32_dpp v197, v225, v57 row_newbcast:14 row_mask:0xf bank_mask:0xf
	v_fmac_f32_dpp v198, v226, v58 row_newbcast:14 row_mask:0xf bank_mask:0xf
	v_fmac_f32_dpp v199, v227, v59 row_newbcast:14 row_mask:0xf bank_mask:0xf
	v_fmac_f32_dpp v196, v224, v60 row_newbcast:15 row_mask:0xf bank_mask:0xf
	v_fmac_f32_dpp v197, v225, v61 row_newbcast:15 row_mask:0xf bank_mask:0xf
	v_fmac_f32_dpp v198, v226, v62 row_newbcast:15 row_mask:0xf bank_mask:0xf
	v_fmac_f32_dpp v199, v227, v63 row_newbcast:15 row_mask:0xf bank_mask:0xf
	v_add_f32_e32 v196, v196, v197
	v_add_f32_e32 v198, v198, v199
	v_sub_f32_e64 v202, -v196, v198
	s_waitcnt lgkmcnt(0)
;     static __device__ __forceinline__ void upd(float (&S)[64], const In2& in, float sa, float vv, float& y0, float& y1) {
;         float t0, t1, t2, t3;
;         asm volatile("v_mul_f32_dpp %0, %10, %27 row_newbcast:%28" DPPM "v_mul_f32_dpp %1, %11, %27 row_newbcast:%28" DPPM "v_mul_f32_dpp %2, %12, %27 row_newbcast:%28" DPPM "v_mul_f32_dpp %3, %13, %27 row_newbcast:%28" DPPM
;                      "v_fmac_f32_dpp %0, %14, %6 row_newbcast:%28" DPPM "v_fmac_f32_dpp %1, %15, %7 row_newbcast:%28" DPPM "v_fmac_f32_dpp %2, %16, %8 row_newbcast:%28" DPPM "v_fmac_f32_dpp %3, %17, %9 row_newbcast:%28" DPPM
;                      "v_fmac_f32_dpp %0, %18, %26 row_newbcast:%28" DPPM "v_fmac_f32_dpp %1, %19, %26 row_newbcast:%28" DPPM "v_fmac_f32_dpp %2, %20, %26 row_newbcast:%28" DPPM "v_fmac_f32_dpp %3, %21, %26 row_newbcast:%28" DPPM
;                      "v_fmac_f32_dpp %4, %22, %0 row_newbcast:%28" DPPM "v_fmac_f32_dpp %5, %23, %1 row_newbcast:%28" DPPM "v_fmac_f32_dpp %4, %24, %2 row_newbcast:%28" DPPM "v_fmac_f32_dpp %5, %25, %3 row_newbcast:%28" DPPM
;                      : "=&v"(t0), "=&v"(t1), "=&v"(t2), "=&v"(t3), "+v"(y0), "+v"(y1)
;                      : "v"(S[K]), "v"(S[K + 1]), "v"(S[K + 2]), "v"(S[K + 3]), "v"(in.kd[0]), "v"(in.kd[1]), "v"(in.kd[2]), "v"(in.kd[3]), "v"(in.w[0]), "v"(in.w[1]), "v"(in.w[2]), "v"(in.w[3]),
;                        "v"(in.b[0]), "v"(in.b[1]), "v"(in.b[2]), "v"(in.b[3]), "v"(in.r[0]), "v"(in.r[1]), "v"(in.r[2]), "v"(in.r[3]), "v"(sa), "v"(vv), "n"(N0));
;         S[K] = t0; S[K + 1] = t1; S[K + 2] = t2; S[K + 3] = t3;
;         if constexpr (K + 4 < 64) ScanK<K + 4>::upd(S, in, sa, vv, y0, y1);
;     }
	s_nop 1
	v_mfma_f32_4x4x1_16b_f32 v[0:3], v64, v202, v[0:3]
	v_mfma_f32_4x4x1_16b_f32 v[4:7], v65, v202, v[4:7]
	v_mfma_f32_4x4x1_16b_f32 v[8:11], v66, v202, v[8:11]
	v_mfma_f32_4x4x1_16b_f32 v[12:15], v67, v202, v[12:15]
	v_mfma_f32_4x4x1_16b_f32 v[16:19], v68, v202, v[16:19]
	v_mfma_f32_4x4x1_16b_f32 v[20:23], v69, v202, v[20:23]
	v_mfma_f32_4x4x1_16b_f32 v[24:27], v70, v202, v[24:27]
	v_mfma_f32_4x4x1_16b_f32 v[28:31], v71, v202, v[28:31]
	v_mfma_f32_4x4x1_16b_f32 v[32:35], v72, v202, v[32:35]
	v_mfma_f32_4x4x1_16b_f32 v[36:39], v73, v202, v[36:39]
	v_mfma_f32_4x4x1_16b_f32 v[40:43], v74, v202, v[40:43]
	v_mfma_f32_4x4x1_16b_f32 v[44:47], v75, v202, v[44:47]
	v_mfma_f32_4x4x1_16b_f32 v[48:51], v76, v202, v[48:51]
	v_mfma_f32_4x4x1_16b_f32 v[52:55], v77, v202, v[52:55]
	v_mfma_f32_4x4x1_16b_f32 v[56:59], v78, v202, v[56:59]
	v_mfma_f32_4x4x1_16b_f32 v[60:63], v79, v202, v[60:63]
	v_mfma_f32_4x4x1_16b_f32 v[0:3], v80, v203, v[0:3]
	v_mfma_f32_4x4x1_16b_f32 v[4:7], v81, v203, v[4:7]
	v_mfma_f32_4x4x1_16b_f32 v[8:11], v82, v203, v[8:11]
	v_mfma_f32_4x4x1_16b_f32 v[12:15], v83, v203, v[12:15]
	v_mfma_f32_4x4x1_16b_f32 v[16:19], v84, v203, v[16:19]
	v_mfma_f32_4x4x1_16b_f32 v[20:23], v85, v203, v[20:23]
	v_mfma_f32_4x4x1_16b_f32 v[24:27], v86, v203, v[24:27]
	v_mfma_f32_4x4x1_16b_f32 v[28:31], v87, v203, v[28:31]
	v_mfma_f32_4x4x1_16b_f32 v[32:35], v88, v203, v[32:35]
	v_mfma_f32_4x4x1_16b_f32 v[36:39], v89, v203, v[36:39]
	v_mfma_f32_4x4x1_16b_f32 v[40:43], v90, v203, v[40:43]
	v_mfma_f32_4x4x1_16b_f32 v[44:47], v91, v203, v[44:47]
	v_mfma_f32_4x4x1_16b_f32 v[48:51], v92, v203, v[48:51]
	v_mfma_f32_4x4x1_16b_f32 v[52:55], v93, v203, v[52:55]
	v_mfma_f32_4x4x1_16b_f32 v[56:59], v94, v203, v[56:59]
	v_mfma_f32_4x4x1_16b_f32 v[60:63], v95, v203, v[60:63]
	v_mul_f32_dpp v200, v228, v0 row_newbcast:0 row_mask:0xf bank_mask:0xf
	v_mul_f32_dpp v201, v229, v1 row_newbcast:0 row_mask:0xf bank_mask:0xf
	v_fmac_f32_dpp v200, v230, v2 row_newbcast:0 row_mask:0xf bank_mask:0xf
	v_fmac_f32_dpp v201, v231, v3 row_newbcast:0 row_mask:0xf bank_mask:0xf
	v_fmac_f32_dpp v200, v228, v4 row_newbcast:1 row_mask:0xf bank_mask:0xf
	v_fmac_f32_dpp v201, v229, v5 row_newbcast:1 row_mask:0xf bank_mask:0xf
	v_fmac_f32_dpp v200, v230, v6 row_newbcast:1 row_mask:0xf bank_mask:0xf
	v_fmac_f32_dpp v201, v231, v7 row_newbcast:1 row_mask:0xf bank_mask:0xf
	v_fmac_f32_dpp v200, v228, v8 row_newbcast:2 row_mask:0xf bank_mask:0xf
	v_fmac_f32_dpp v201, v229, v9 row_newbcast:2 row_mask:0xf bank_mask:0xf
	v_fmac_f32_dpp v200, v230, v10 row_newbcast:2 row_mask:0xf bank_mask:0xf
	v_fmac_f32_dpp v201, v231, v11 row_newbcast:2 row_mask:0xf bank_mask:0xf
	v_fmac_f32_dpp v200, v228, v12 row_newbcast:3 row_mask:0xf bank_mask:0xf
	v_fmac_f32_dpp v201, v229, v13 row_newbcast:3 row_mask:0xf bank_mask:0xf
	v_fmac_f32_dpp v200, v230, v14 row_newbcast:3 row_mask:0xf bank_mask:0xf
	v_fmac_f32_dpp v201, v231, v15 row_newbcast:3 row_mask:0xf bank_mask:0xf
	v_fmac_f32_dpp v200, v228, v16 row_newbcast:4 row_mask:0xf bank_mask:0xf
	v_fmac_f32_dpp v201, v229, v17 row_newbcast:4 row_mask:0xf bank_mask:0xf
	v_fmac_f32_dpp v200, v230, v18 row_newbcast:4 row_mask:0xf bank_mask:0xf
	v_fmac_f32_dpp v201, v231, v19 row_newbcast:4 row_mask:0xf bank_mask:0xf
	v_fmac_f32_dpp v200, v228, v20 row_newbcast:5 row_mask:0xf bank_mask:0xf
	v_fmac_f32_dpp v201, v229, v21 row_newbcast:5 row_mask:0xf bank_mask:0xf
	v_fmac_f32_dpp v200, v230, v22 row_newbcast:5 row_mask:0xf bank_mask:0xf
	v_fmac_f32_dpp v201, v231, v23 row_newbcast:5 row_mask:0xf bank_mask:0xf
	v_fmac_f32_dpp v200, v228, v24 row_newbcast:6 row_mask:0xf bank_mask:0xf
	v_fmac_f32_dpp v201, v229, v25 row_newbcast:6 row_mask:0xf bank_mask:0xf
	v_fmac_f32_dpp v200, v230, v26 row_newbcast:6 row_mask:0xf bank_mask:0xf
	v_fmac_f32_dpp v201, v231, v27 row_newbcast:6 row_mask:0xf bank_mask:0xf
	v_fmac_f32_dpp v200, v228, v28 row_newbcast:7 row_mask:0xf bank_mask:0xf
	v_fmac_f32_dpp v201, v229, v29 row_newbcast:7 row_mask:0xf bank_mask:0xf
	v_fmac_f32_dpp v200, v230, v30 row_newbcast:7 row_mask:0xf bank_mask:0xf
	v_fmac_f32_dpp v201, v231, v31 row_newbcast:7 row_mask:0xf bank_mask:0xf
	v_fmac_f32_dpp v200, v228, v32 row_newbcast:8 row_mask:0xf bank_mask:0xf
	v_fmac_f32_dpp v201, v229, v33 row_newbcast:8 row_mask:0xf bank_mask:0xf
	v_fmac_f32_dpp v200, v230, v34 row_newbcast:8 row_mask:0xf bank_mask:0xf
	v_fmac_f32_dpp v201, v231, v35 row_newbcast:8 row_mask:0xf bank_mask:0xf
	v_fmac_f32_dpp v200, v228, v36 row_newbcast:9 row_mask:0xf bank_mask:0xf
	v_fmac_f32_dpp v201, v229, v37 row_newbcast:9 row_mask:0xf bank_mask:0xf
	v_fmac_f32_dpp v200, v230, v38 row_newbcast:9 row_mask:0xf bank_mask:0xf
	v_fmac_f32_dpp v201, v231, v39 row_newbcast:9 row_mask:0xf bank_mask:0xf
	v_fmac_f32_dpp v200, v228, v40 row_newbcast:10 row_mask:0xf bank_mask:0xf
	v_fmac_f32_dpp v201, v229, v41 row_newbcast:10 row_mask:0xf bank_mask:0xf
	v_fmac_f32_dpp v200, v230, v42 row_newbcast:10 row_mask:0xf bank_mask:0xf
	v_fmac_f32_dpp v201, v231, v43 row_newbcast:10 row_mask:0xf bank_mask:0xf
	v_fmac_f32_dpp v200, v228, v44 row_newbcast:11 row_mask:0xf bank_mask:0xf
	v_fmac_f32_dpp v201, v229, v45 row_newbcast:11 row_mask:0xf bank_mask:0xf
	v_fmac_f32_dpp v200, v230, v46 row_newbcast:11 row_mask:0xf bank_mask:0xf
	v_fmac_f32_dpp v201, v231, v47 row_newbcast:11 row_mask:0xf bank_mask:0xf
	v_fmac_f32_dpp v200, v228, v48 row_newbcast:12 row_mask:0xf bank_mask:0xf
	v_fmac_f32_dpp v201, v229, v49 row_newbcast:12 row_mask:0xf bank_mask:0xf
	v_fmac_f32_dpp v200, v230, v50 row_newbcast:12 row_mask:0xf bank_mask:0xf
	v_fmac_f32_dpp v201, v231, v51 row_newbcast:12 row_mask:0xf bank_mask:0xf
	v_fmac_f32_dpp v200, v228, v52 row_newbcast:13 row_mask:0xf bank_mask:0xf
	v_fmac_f32_dpp v201, v229, v53 row_newbcast:13 row_mask:0xf bank_mask:0xf
	v_fmac_f32_dpp v200, v230, v54 row_newbcast:13 row_mask:0xf bank_mask:0xf
	v_fmac_f32_dpp v201, v231, v55 row_newbcast:13 row_mask:0xf bank_mask:0xf
	v_fmac_f32_dpp v200, v228, v56 row_newbcast:14 row_mask:0xf bank_mask:0xf
	v_fmac_f32_dpp v201, v229, v57 row_newbcast:14 row_mask:0xf bank_mask:0xf
	v_fmac_f32_dpp v200, v230, v58 row_newbcast:14 row_mask:0xf bank_mask:0xf
	v_fmac_f32_dpp v201, v231, v59 row_newbcast:14 row_mask:0xf bank_mask:0xf
	v_fmac_f32_dpp v200, v228, v60 row_newbcast:15 row_mask:0xf bank_mask:0xf
	v_fmac_f32_dpp v201, v229, v61 row_newbcast:15 row_mask:0xf bank_mask:0xf
	v_fmac_f32_dpp v200, v230, v62 row_newbcast:15 row_mask:0xf bank_mask:0xf
	v_fmac_f32_dpp v201, v231, v63 row_newbcast:15 row_mask:0xf bank_mask:0xf
	v_add_f32_e32 v200, v200, v201
	s_waitcnt vmcnt(12)
;     static __device__ __forceinline__ void dot(const float (&S)[64], const f32x4& a, float (&s)[4]) {
;         if constexpr (K == 0) {
;             asm volatile("v_mul_f32_dpp %0, %4, %8 row_newbcast:%16" DPPM "v_mul_f32_dpp %1, %5, %9 row_newbcast:%16" DPPM "v_mul_f32_dpp %2, %6, %10 row_newbcast:%16" DPPM "v_mul_f32_dpp %3, %7, %11 row_newbcast:%16" DPPM
;                          "v_fmac_f32_dpp %0, %4, %12 row_newbcast:%17" DPPM "v_fmac_f32_dpp %1, %5, %13 row_newbcast:%17" DPPM "v_fmac_f32_dpp %2, %6, %14 row_newbcast:%17" DPPM "v_fmac_f32_dpp %3, %7, %15 row_newbcast:%17" DPPM
;                          : "=&v"(s[0]), "=&v"(s[1]), "=&v"(s[2]), "=&v"(s[3])
;                          : "v"(a[0]), "v"(a[1]), "v"(a[2]), "v"(a[3]), "v"(S[K]), "v"(S[K + 1]), "v"(S[K + 2]), "v"(S[K + 3]), "v"(S[K + 4]), "v"(S[K + 5]), "v"(S[K + 6]), "v"(S[K + 7]), "n"(N0), "n"(N1));
;         } else
;         asm volatile("v_fmac_f32_dpp %0, %4, %8 row_newbcast:%16" DPPM "v_fmac_f32_dpp %1, %5, %9 row_newbcast:%16" DPPM "v_fmac_f32_dpp %2, %6, %10 row_newbcast:%16" DPPM "v_fmac_f32_dpp %3, %7, %11 row_newbcast:%16" DPPM
;                      "v_fmac_f32_dpp %0, %4, %12 row_newbcast:%17" DPPM "v_fmac_f32_dpp %1, %5, %13 row_newbcast:%17" DPPM "v_fmac_f32_dpp %2, %6, %14 row_newbcast:%17" DPPM "v_fmac_f32_dpp %3, %7, %15 row_newbcast:%17" DPPM
;                      : "+v"(s[0]), "+v"(s[1]), "+v"(s[2]), "+v"(s[3])
;                      : "v"(a[0]), "v"(a[1]), "v"(a[2]), "v"(a[3]), "v"(S[K]), "v"(S[K + 1]), "v"(S[K + 2]), "v"(S[K + 3]), "v"(S[K + 4]), "v"(S[K + 5]), "v"(S[K + 6]), "v"(S[K + 7]), "n"(N0), "n"(N1));
;         if constexpr (K + 8 < 64) ScanK<K + 8>::dot(S, a, s);
;     }
;     static __device__ __forceinline__ void upd(float (&S)[64], const In2& in, float sa, float vv, float& y0, float& y1) {
;         float t0, t1, t2, t3;
;         asm volatile("v_mul_f32_dpp %0, %10, %27 row_newbcast:%28" DPPM "v_mul_f32_dpp %1, %11, %27 row_newbcast:%28" DPPM "v_mul_f32_dpp %2, %12, %27 row_newbcast:%28" DPPM "v_mul_f32_dpp %3, %13, %27 row_newbcast:%28" DPPM
;                      "v_fmac_f32_dpp %0, %14, %6 row_newbcast:%28" DPPM "v_fmac_f32_dpp %1, %15, %7 row_newbcast:%28" DPPM "v_fmac_f32_dpp %2, %16, %8 row_newbcast:%28" DPPM "v_fmac_f32_dpp %3, %17, %9 row_newbcast:%28" DPPM
	buffer_store_dword v200, v207, s[68:71], s79 offen
	s_add_u32 s79, s79, 0x1000
	buffer_load_dwordx4 v[136:139], v232, s[64:67], s72 offen
	buffer_load_dwordx4 v[140:143], v233, s[64:67], s72 offen
	buffer_load_dwordx4 v[144:147], v234, s[64:67], s72 offen
	buffer_load_dwordx4 v[148:151], v235, s[64:67], s72 offen
	buffer_load_dwordx2 v[152:153], v236, s[64:67], s76 offen
	buffer_load_ushort v154, v237, s[64:67], s76 offen
	s_add_u32 s72, s72, 0x1000
	s_add_u32 s76, s76, 0x800
	v_pk_mul_f32 v[224:225], v[160:161], v[216:217]
	v_pk_mul_f32 v[226:227], v[162:163], v[218:219]
	v_pk_mul_f32 v[216:217], v[216:217], v[156:157]
	v_pk_mul_f32 v[218:219], v[218:219], v[158:159]
	v_pk_fma_f32 v[184:185], v[164:165], v[188:189], v[192:193]
	v_pk_fma_f32 v[186:187], v[166:167], v[190:191], v[194:195]
	v_pk_mul_f32 v[176:177], v[160:161], v[164:165]
	v_pk_mul_f32 v[178:179], v[162:163], v[166:167]
	v_rcp_f32_e32 v220, v216
	v_rcp_f32_e32 v221, v217
	v_rcp_f32_e32 v222, v218
	v_rcp_f32_e32 v223, v219
	v_lshlrev_b32_e32 v180, 16, v172
	v_and_b32_e32 v181, 0xffff0000, v172
	v_lshlrev_b32_e32 v182, 16, v173
	v_and_b32_e32 v183, 0xffff0000, v173
	v_pk_mul_f32 v[180:181], v[180:181], v[184:185]
	v_pk_mul_f32 v[182:183], v[182:183], v[186:187]
	v_pk_mul_f32 v[228:229], v[168:169], v[216:217]
	v_pk_mul_f32 v[230:231], v[170:171], v[218:219]
	v_pk_mul_f32 v[176:177], v[176:177], v[220:221]
	v_pk_mul_f32 v[178:179], v[178:179], v[222:223]
	v_pk_mul_f32 v[180:181], v[180:181], v[220:221]
	v_pk_mul_f32 v[182:183], v[182:183], v[222:223]
	v_lshlrev_b32_e32 v203, 16, v174
	ds_write2_b32 v208, v176, v177 offset0:0 offset1:16
	ds_write2_b32 v208, v178, v179 offset0:32 offset1:48
	ds_write2_b32 v208, v180, v181 offset0:64 offset1:80
	ds_write2_b32 v208, v182, v183 offset0:96 offset1:112
	ds_read_b128 v[64:67], v209 offset:0
	ds_read_b128 v[68:71], v209 offset:16
	ds_read_b128 v[72:75], v209 offset:32
	ds_read_b128 v[76:79], v209 offset:48
	ds_read_b128 v[80:83], v209 offset:256
	ds_read_b128 v[84:87], v209 offset:272
	ds_read_b128 v[88:91], v209 offset:288
	ds_read_b128 v[92:95], v209 offset:304
	v_mul_f32_dpp v196, v224, v0 row_newbcast:0 row_mask:0xf bank_mask:0xf
	v_mul_f32_dpp v197, v225, v1 row_newbcast:0 row_mask:0xf bank_mask:0xf
	v_mul_f32_dpp v198, v226, v2 row_newbcast:0 row_mask:0xf bank_mask:0xf
	v_mul_f32_dpp v199, v227, v3 row_newbcast:0 row_mask:0xf bank_mask:0xf
	v_fmac_f32_dpp v196, v224, v4 row_newbcast:1 row_mask:0xf bank_mask:0xf
	v_fmac_f32_dpp v197, v225, v5 row_newbcast:1 row_mask:0xf bank_mask:0xf
	v_fmac_f32_dpp v198, v226, v6 row_newbcast:1 row_mask:0xf bank_mask:0xf
	v_fmac_f32_dpp v199, v227, v7 row_newbcast:1 row_mask:0xf bank_mask:0xf
	v_fmac_f32_dpp v196, v224, v8 row_newbcast:2 row_mask:0xf bank_mask:0xf
	v_fmac_f32_dpp v197, v225, v9 row_newbcast:2 row_mask:0xf bank_mask:0xf
	v_fmac_f32_dpp v198, v226, v10 row_newbcast:2 row_mask:0xf bank_mask:0xf
	v_fmac_f32_dpp v199, v227, v11 row_newbcast:2 row_mask:0xf bank_mask:0xf
	v_fmac_f32_dpp v196, v224, v12 row_newbcast:3 row_mask:0xf bank_mask:0xf
	v_fmac_f32_dpp v197, v225, v13 row_newbcast:3 row_mask:0xf bank_mask:0xf
	v_fmac_f32_dpp v198, v226, v14 row_newbcast:3 row_mask:0xf bank_mask:0xf
	v_fmac_f32_dpp v199, v227, v15 row_newbcast:3 row_mask:0xf bank_mask:0xf
	v_fmac_f32_dpp v196, v224, v16 row_newbcast:4 row_mask:0xf bank_mask:0xf
	v_fmac_f32_dpp v197, v225, v17 row_newbcast:4 row_mask:0xf bank_mask:0xf
	v_fmac_f32_dpp v198, v226, v18 row_newbcast:4 row_mask:0xf bank_mask:0xf
	v_fmac_f32_dpp v199, v227, v19 row_newbcast:4 row_mask:0xf bank_mask:0xf
	v_fmac_f32_dpp v196, v224, v20 row_newbcast:5 row_mask:0xf bank_mask:0xf
	v_fmac_f32_dpp v197, v225, v21 row_newbcast:5 row_mask:0xf bank_mask:0xf
	v_fmac_f32_dpp v198, v226, v22 row_newbcast:5 row_mask:0xf bank_mask:0xf
	v_fmac_f32_dpp v199, v227, v23 row_newbcast:5 row_mask:0xf bank_mask:0xf
	v_fmac_f32_dpp v196, v224, v24 row_newbcast:6 row_mask:0xf bank_mask:0xf
	v_fmac_f32_dpp v197, v225, v25 row_newbcast:6 row_mask:0xf bank_mask:0xf
	v_fmac_f32_dpp v198, v226, v26 row_newbcast:6 row_mask:0xf bank_mask:0xf
	v_fmac_f32_dpp v199, v227, v27 row_newbcast:6 row_mask:0xf bank_mask:0xf
	v_fmac_f32_dpp v196, v224, v28 row_newbcast:7 row_mask:0xf bank_mask:0xf
	v_fmac_f32_dpp v197, v225, v29 row_newbcast:7 row_mask:0xf bank_mask:0xf
	v_fmac_f32_dpp v198, v226, v30 row_newbcast:7 row_mask:0xf bank_mask:0xf
	v_fmac_f32_dpp v199, v227, v31 row_newbcast:7 row_mask:0xf bank_mask:0xf
	v_fmac_f32_dpp v196, v224, v32 row_newbcast:8 row_mask:0xf bank_mask:0xf
	v_fmac_f32_dpp v197, v225, v33 row_newbcast:8 row_mask:0xf bank_mask:0xf
	v_fmac_f32_dpp v198, v226, v34 row_newbcast:8 row_mask:0xf bank_mask:0xf
	v_fmac_f32_dpp v199, v227, v35 row_newbcast:8 row_mask:0xf bank_mask:0xf
	v_fmac_f32_dpp v196, v224, v36 row_newbcast:9 row_mask:0xf bank_mask:0xf
	v_fmac_f32_dpp v197, v225, v37 row_newbcast:9 row_mask:0xf bank_mask:0xf
	v_fmac_f32_dpp v198, v226, v38 row_newbcast:9 row_mask:0xf bank_mask:0xf
	v_fmac_f32_dpp v199, v227, v39 row_newbcast:9 row_mask:0xf bank_mask:0xf
	v_fmac_f32_dpp v196, v224, v40 row_newbcast:10 row_mask:0xf bank_mask:0xf
	v_fmac_f32_dpp v197, v225, v41 row_newbcast:10 row_mask:0xf bank_mask:0xf
	v_fmac_f32_dpp v198, v226, v42 row_newbcast:10 row_mask:0xf bank_mask:0xf
	v_fmac_f32_dpp v199, v227, v43 row_newbcast:10 row_mask:0xf bank_mask:0xf
	v_fmac_f32_dpp v196, v224, v44 row_newbcast:11 row_mask:0xf bank_mask:0xf
	v_fmac_f32_dpp v197, v225, v45 row_newbcast:11 row_mask:0xf bank_mask:0xf
	v_fmac_f32_dpp v198, v226, v46 row_newbcast:11 row_mask:0xf bank_mask:0xf
	v_fmac_f32_dpp v199, v227, v47 row_newbcast:11 row_mask:0xf bank_mask:0xf
	v_fmac_f32_dpp v196, v224, v48 row_newbcast:12 row_mask:0xf bank_mask:0xf
	v_fmac_f32_dpp v197, v225, v49 row_newbcast:12 row_mask:0xf bank_mask:0xf
	v_fmac_f32_dpp v198, v226, v50 row_newbcast:12 row_mask:0xf bank_mask:0xf
	v_fmac_f32_dpp v199, v227, v51 row_newbcast:12 row_mask:0xf bank_mask:0xf
	v_fmac_f32_dpp v196, v224, v52 row_newbcast:13 row_mask:0xf bank_mask:0xf
	v_fmac_f32_dpp v197, v225, v53 row_newbcast:13 row_mask:0xf bank_mask:0xf
	v_fmac_f32_dpp v198, v226, v54 row_newbcast:13 row_mask:0xf bank_mask:0xf
	v_fmac_f32_dpp v199, v227, v55 row_newbcast:13 row_mask:0xf bank_mask:0xf
	v_fmac_f32_dpp v196, v224, v56 row_newbcast:14 row_mask:0xf bank_mask:0xf
	v_fmac_f32_dpp v197, v225, v57 row_newbcast:14 row_mask:0xf bank_mask:0xf
	v_fmac_f32_dpp v198, v226, v58 row_newbcast:14 row_mask:0xf bank_mask:0xf
	v_fmac_f32_dpp v199, v227, v59 row_newbcast:14 row_mask:0xf bank_mask:0xf
	v_fmac_f32_dpp v196, v224, v60 row_newbcast:15 row_mask:0xf bank_mask:0xf
	v_fmac_f32_dpp v197, v225, v61 row_newbcast:15 row_mask:0xf bank_mask:0xf
	v_fmac_f32_dpp v198, v226, v62 row_newbcast:15 row_mask:0xf bank_mask:0xf
	v_fmac_f32_dpp v199, v227, v63 row_newbcast:15 row_mask:0xf bank_mask:0xf
	v_add_f32_e32 v196, v196, v197
	v_add_f32_e32 v198, v198, v199
	v_sub_f32_e64 v202, -v196, v198
	s_waitcnt lgkmcnt(0)
; #define SB __builtin_amdgcn_sched_barrier(0)
; #define ST2(set, s) { DERIVE_BK(set); float sd[4]; ScanK<0>::dot(S, set.a, sd); float y0 = set.yo, y1 = 0.f; ScanK<0>::upd(S, set, -((sd[0] + sd[1]) + (sd[2] + sd[3])), __uint_as_float(set.v << 16), y0, y1); __builtin_amdgcn_raw_buffer_store_b32(__float_as_uint(y0 + y1), rY, lo4b, ob4 + (unsigned)((int)(s) * (int)stp * 4), 0); }
;     static __device__ __forceinline__ void upd(float (&S)[64], const In2& in, float sa, float vv, float& y0, float& y1) {
;         float t0, t1, t2, t3;
;         asm volatile("v_mul_f32_dpp %0, %10, %27 row_newbcast:%28" DPPM "v_mul_f32_dpp %1, %11, %27 row_newbcast:%28" DPPM "v_mul_f32_dpp %2, %12, %27 row_newbcast:%28" DPPM "v_mul_f32_dpp %3, %13, %27 row_newbcast:%28" DPPM
;                      "v_fmac_f32_dpp %0, %14, %6 row_newbcast:%28" DPPM "v_fmac_f32_dpp %1, %15, %7 row_newbcast:%28" DPPM "v_fmac_f32_dpp %2, %16, %8 row_newbcast:%28" DPPM "v_fmac_f32_dpp %3, %17, %9 row_newbcast:%28" DPPM
;                      "v_fmac_f32_dpp %0, %18, %26 row_newbcast:%28" DPPM "v_fmac_f32_dpp %1, %19, %26 row_newbcast:%28" DPPM "v_fmac_f32_dpp %2, %20, %26 row_newbcast:%28" DPPM "v_fmac_f32_dpp %3, %21, %26 row_newbcast:%28" DPPM
;                      "v_fmac_f32_dpp %4, %22, %0 row_newbcast:%28" DPPM "v_fmac_f32_dpp %5, %23, %1 row_newbcast:%28" DPPM "v_fmac_f32_dpp %4, %24, %2 row_newbcast:%28" DPPM "v_fmac_f32_dpp %5, %25, %3 row_newbcast:%28" DPPM
;                      : "=&v"(t0), "=&v"(t1), "=&v"(t2), "=&v"(t3), "+v"(y0), "+v"(y1)
;                      : "v"(S[K]), "v"(S[K + 1]), "v"(S[K + 2]), "v"(S[K + 3]), "v"(in.kd[0]), "v"(in.kd[1]), "v"(in.kd[2]), "v"(in.kd[3]), "v"(in.w[0]), "v"(in.w[1]), "v"(in.w[2]), "v"(in.w[3]),
;                        "v"(in.b[0]), "v"(in.b[1]), "v"(in.b[2]), "v"(in.b[3]), "v"(in.r[0]), "v"(in.r[1]), "v"(in.r[2]), "v"(in.r[3]), "v"(sa), "v"(vv), "n"(N0));
;         S[K] = t0; S[K + 1] = t1; S[K + 2] = t2; S[K + 3] = t3;
;         if constexpr (K + 4 < 64) ScanK<K + 4>::upd(S, in, sa, vv, y0, y1);
; __device__ __forceinline__ void scan_pass2(const Params& p, int d) {
;     ...
;         In2 i0, i1; LD2(i0, 0);
; #pragma unroll 1
;         for (int s = 0; s < LC; s += 2) { TOUCH2(i0); SB; LD2(i1, s + 1); SB; ST2(i0, s); TOUCH2(i1); SB; LD2(i0, s + 2); SB; ST2(i1, s + 1); }
	s_nop 1
	v_mfma_f32_4x4x1_16b_f32 v[0:3], v64, v202, v[0:3]
	v_mfma_f32_4x4x1_16b_f32 v[4:7], v65, v202, v[4:7]
	v_mfma_f32_4x4x1_16b_f32 v[8:11], v66, v202, v[8:11]
	v_mfma_f32_4x4x1_16b_f32 v[12:15], v67, v202, v[12:15]
	v_mfma_f32_4x4x1_16b_f32 v[16:19], v68, v202, v[16:19]
	v_mfma_f32_4x4x1_16b_f32 v[20:23], v69, v202, v[20:23]
	v_mfma_f32_4x4x1_16b_f32 v[24:27], v70, v202, v[24:27]
	v_mfma_f32_4x4x1_16b_f32 v[28:31], v71, v202, v[28:31]
	v_mfma_f32_4x4x1_16b_f32 v[32:35], v72, v202, v[32:35]
	v_mfma_f32_4x4x1_16b_f32 v[36:39], v73, v202, v[36:39]
	v_mfma_f32_4x4x1_16b_f32 v[40:43], v74, v202, v[40:43]
	v_mfma_f32_4x4x1_16b_f32 v[44:47], v75, v202, v[44:47]
	v_mfma_f32_4x4x1_16b_f32 v[48:51], v76, v202, v[48:51]
	v_mfma_f32_4x4x1_16b_f32 v[52:55], v77, v202, v[52:55]
	v_mfma_f32_4x4x1_16b_f32 v[56:59], v78, v202, v[56:59]
	v_mfma_f32_4x4x1_16b_f32 v[60:63], v79, v202, v[60:63]
	v_mfma_f32_4x4x1_16b_f32 v[0:3], v80, v203, v[0:3]
	v_mfma_f32_4x4x1_16b_f32 v[4:7], v81, v203, v[4:7]
	v_mfma_f32_4x4x1_16b_f32 v[8:11], v82, v203, v[8:11]
	v_mfma_f32_4x4x1_16b_f32 v[12:15], v83, v203, v[12:15]
	v_mfma_f32_4x4x1_16b_f32 v[16:19], v84, v203, v[16:19]
	v_mfma_f32_4x4x1_16b_f32 v[20:23], v85, v203, v[20:23]
	v_mfma_f32_4x4x1_16b_f32 v[24:27], v86, v203, v[24:27]
	v_mfma_f32_4x4x1_16b_f32 v[28:31], v87, v203, v[28:31]
	v_mfma_f32_4x4x1_16b_f32 v[32:35], v88, v203, v[32:35]
	v_mfma_f32_4x4x1_16b_f32 v[36:39], v89, v203, v[36:39]
	v_mfma_f32_4x4x1_16b_f32 v[40:43], v90, v203, v[40:43]
	v_mfma_f32_4x4x1_16b_f32 v[44:47], v91, v203, v[44:47]
	v_mfma_f32_4x4x1_16b_f32 v[48:51], v92, v203, v[48:51]
	v_mfma_f32_4x4x1_16b_f32 v[52:55], v93, v203, v[52:55]
	v_mfma_f32_4x4x1_16b_f32 v[56:59], v94, v203, v[56:59]
	v_mfma_f32_4x4x1_16b_f32 v[60:63], v95, v203, v[60:63]
	v_mul_f32_dpp v200, v228, v0 row_newbcast:0 row_mask:0xf bank_mask:0xf
	v_mul_f32_dpp v201, v229, v1 row_newbcast:0 row_mask:0xf bank_mask:0xf
	v_fmac_f32_dpp v200, v230, v2 row_newbcast:0 row_mask:0xf bank_mask:0xf
	v_fmac_f32_dpp v201, v231, v3 row_newbcast:0 row_mask:0xf bank_mask:0xf
	v_fmac_f32_dpp v200, v228, v4 row_newbcast:1 row_mask:0xf bank_mask:0xf
	v_fmac_f32_dpp v201, v229, v5 row_newbcast:1 row_mask:0xf bank_mask:0xf
	v_fmac_f32_dpp v200, v230, v6 row_newbcast:1 row_mask:0xf bank_mask:0xf
	v_fmac_f32_dpp v201, v231, v7 row_newbcast:1 row_mask:0xf bank_mask:0xf
	v_fmac_f32_dpp v200, v228, v8 row_newbcast:2 row_mask:0xf bank_mask:0xf
	v_fmac_f32_dpp v201, v229, v9 row_newbcast:2 row_mask:0xf bank_mask:0xf
	v_fmac_f32_dpp v200, v230, v10 row_newbcast:2 row_mask:0xf bank_mask:0xf
	v_fmac_f32_dpp v201, v231, v11 row_newbcast:2 row_mask:0xf bank_mask:0xf
	v_fmac_f32_dpp v200, v228, v12 row_newbcast:3 row_mask:0xf bank_mask:0xf
	v_fmac_f32_dpp v201, v229, v13 row_newbcast:3 row_mask:0xf bank_mask:0xf
	v_fmac_f32_dpp v200, v230, v14 row_newbcast:3 row_mask:0xf bank_mask:0xf
	v_fmac_f32_dpp v201, v231, v15 row_newbcast:3 row_mask:0xf bank_mask:0xf
	v_fmac_f32_dpp v200, v228, v16 row_newbcast:4 row_mask:0xf bank_mask:0xf
	v_fmac_f32_dpp v201, v229, v17 row_newbcast:4 row_mask:0xf bank_mask:0xf
	v_fmac_f32_dpp v200, v230, v18 row_newbcast:4 row_mask:0xf bank_mask:0xf
	v_fmac_f32_dpp v201, v231, v19 row_newbcast:4 row_mask:0xf bank_mask:0xf
	v_fmac_f32_dpp v200, v228, v20 row_newbcast:5 row_mask:0xf bank_mask:0xf
	v_fmac_f32_dpp v201, v229, v21 row_newbcast:5 row_mask:0xf bank_mask:0xf
	v_fmac_f32_dpp v200, v230, v22 row_newbcast:5 row_mask:0xf bank_mask:0xf
	v_fmac_f32_dpp v201, v231, v23 row_newbcast:5 row_mask:0xf bank_mask:0xf
	v_fmac_f32_dpp v200, v228, v24 row_newbcast:6 row_mask:0xf bank_mask:0xf
	v_fmac_f32_dpp v201, v229, v25 row_newbcast:6 row_mask:0xf bank_mask:0xf
	v_fmac_f32_dpp v200, v230, v26 row_newbcast:6 row_mask:0xf bank_mask:0xf
	v_fmac_f32_dpp v201, v231, v27 row_newbcast:6 row_mask:0xf bank_mask:0xf
	v_fmac_f32_dpp v200, v228, v28 row_newbcast:7 row_mask:0xf bank_mask:0xf
	v_fmac_f32_dpp v201, v229, v29 row_newbcast:7 row_mask:0xf bank_mask:0xf
	v_fmac_f32_dpp v200, v230, v30 row_newbcast:7 row_mask:0xf bank_mask:0xf
	v_fmac_f32_dpp v201, v231, v31 row_newbcast:7 row_mask:0xf bank_mask:0xf
	v_fmac_f32_dpp v200, v228, v32 row_newbcast:8 row_mask:0xf bank_mask:0xf
	v_fmac_f32_dpp v201, v229, v33 row_newbcast:8 row_mask:0xf bank_mask:0xf
	v_fmac_f32_dpp v200, v230, v34 row_newbcast:8 row_mask:0xf bank_mask:0xf
	v_fmac_f32_dpp v201, v231, v35 row_newbcast:8 row_mask:0xf bank_mask:0xf
	v_fmac_f32_dpp v200, v228, v36 row_newbcast:9 row_mask:0xf bank_mask:0xf
	v_fmac_f32_dpp v201, v229, v37 row_newbcast:9 row_mask:0xf bank_mask:0xf
	v_fmac_f32_dpp v200, v230, v38 row_newbcast:9 row_mask:0xf bank_mask:0xf
	v_fmac_f32_dpp v201, v231, v39 row_newbcast:9 row_mask:0xf bank_mask:0xf
	v_fmac_f32_dpp v200, v228, v40 row_newbcast:10 row_mask:0xf bank_mask:0xf
	v_fmac_f32_dpp v201, v229, v41 row_newbcast:10 row_mask:0xf bank_mask:0xf
	v_fmac_f32_dpp v200, v230, v42 row_newbcast:10 row_mask:0xf bank_mask:0xf
	v_fmac_f32_dpp v201, v231, v43 row_newbcast:10 row_mask:0xf bank_mask:0xf
	v_fmac_f32_dpp v200, v228, v44 row_newbcast:11 row_mask:0xf bank_mask:0xf
	v_fmac_f32_dpp v201, v229, v45 row_newbcast:11 row_mask:0xf bank_mask:0xf
	v_fmac_f32_dpp v200, v230, v46 row_newbcast:11 row_mask:0xf bank_mask:0xf
	v_fmac_f32_dpp v201, v231, v47 row_newbcast:11 row_mask:0xf bank_mask:0xf
	v_fmac_f32_dpp v200, v228, v48 row_newbcast:12 row_mask:0xf bank_mask:0xf
	v_fmac_f32_dpp v201, v229, v49 row_newbcast:12 row_mask:0xf bank_mask:0xf
	v_fmac_f32_dpp v200, v230, v50 row_newbcast:12 row_mask:0xf bank_mask:0xf
	v_fmac_f32_dpp v201, v231, v51 row_newbcast:12 row_mask:0xf bank_mask:0xf
	v_fmac_f32_dpp v200, v228, v52 row_newbcast:13 row_mask:0xf bank_mask:0xf
	v_fmac_f32_dpp v201, v229, v53 row_newbcast:13 row_mask:0xf bank_mask:0xf
	v_fmac_f32_dpp v200, v230, v54 row_newbcast:13 row_mask:0xf bank_mask:0xf
	v_fmac_f32_dpp v201, v231, v55 row_newbcast:13 row_mask:0xf bank_mask:0xf
	v_fmac_f32_dpp v200, v228, v56 row_newbcast:14 row_mask:0xf bank_mask:0xf
	v_fmac_f32_dpp v201, v229, v57 row_newbcast:14 row_mask:0xf bank_mask:0xf
	v_fmac_f32_dpp v200, v230, v58 row_newbcast:14 row_mask:0xf bank_mask:0xf
	v_fmac_f32_dpp v201, v231, v59 row_newbcast:14 row_mask:0xf bank_mask:0xf
	v_fmac_f32_dpp v200, v228, v60 row_newbcast:15 row_mask:0xf bank_mask:0xf
	v_fmac_f32_dpp v201, v229, v61 row_newbcast:15 row_mask:0xf bank_mask:0xf
	v_fmac_f32_dpp v200, v230, v62 row_newbcast:15 row_mask:0xf bank_mask:0xf
	v_fmac_f32_dpp v201, v231, v63 row_newbcast:15 row_mask:0xf bank_mask:0xf
	v_add_f32_e32 v200, v200, v201
	s_sub_u32 s83, s83, 1
	s_cmp_eq_u32 s83, 0
	s_cbranch_scc1 .Lmy_p2d0_ldone
	s_and_b32 s9, s83, 15
	s_cmp_eq_u32 s9, 0
	s_cbranch_scc1 .Lmy_p2d0_renorm
	s_branch .Lmy_p2d0_loop

; #define NEXT_ITEM() (MIX ? (int)__builtin_amdgcn_readfirstlane(lane == 0 ? __hip_atomic_fetch_add(qctr, 1u, __ATOMIC_RELAXED, __HIP_MEMORY_SCOPE_AGENT) : 0u) : item + (int)gridDim.x * 8)
; #define SB __builtin_amdgcn_sched_barrier(0)
; #define MKR(ptr) __builtin_amdgcn_make_buffer_rsrc((void*)(ptr), 0, 0x7fffffff, 0x00027000)
; #define LD1(set, s) { const int e_ = min((int)(s), LC - 1) * (int)stp; const unsigned s4_ = ob4 + (unsigned)(e_ * 4), s2_ = ob2 + (unsigned)(e_ * 2); set.w = LDX(rW, s4_); set.a = LDX(rA, s4_); set.b = LDX(rB, s4_); \
;             set.kw = __builtin_amdgcn_raw_buffer_load_b64(rK, lo8, s2_, 0); set.v = __builtin_amdgcn_raw_buffer_load_b16(rV, lo2, s2_, 0); }
; #define TOUCH1(set) asm volatile("" :: "v"(set.w), "v"(set.a), "v"(set.b), "v"(set.kw), "v"(set.v))
; #define TOUCH1(set) asm volatile("" :: "v"(set.w), "v"(set.a), "v"(set.b))
; template <bool MIX> __device__ __forceinline__ void scan_pass1(const Params& p, int d, float* ldsf) {
;     ...
;     for (int item = MIX ? NEXT_ITEM() : (int)(blockIdx.x * 8 + wid); item < 2 * NS; item = NEXT_ITEM()) {
;         const bool isP = item >= NS; const int idx = isP ? item - NS : item;
;         const int bh = idx / (NC - 1), c = idx - bh * (NC - 1), b = bh >> 4, h = bh & 15;
;         const int t0 = d ? (SEQ - 1 - c * LC) : c * LC;
;         const size_t off0 = ((size_t)(b * SEQ + t0)) * RW + h * 64; const long stp = d ? -(long)RW : (long)RW;
;         const unsigned ob4 = (unsigned)(off0 * 4), ob2 = (unsigned)(off0 * 2);
;         const f32x4 ka4 = *(const f32x4*)(p.k_a + h * 64 + (lane & 15) * 4), c04 = 1.0f - ka4;
;         float S[64]; int ln = lane; asm volatile("" : "+v"(ln));
;     ...
;         const __amdgpu_buffer_rsrc_t rW = MKR(Wd), rA = MKR(A), rB = MKR(Bd), rK = MKR(KB), rV = MKR(V);
;         if (!isP) {
; #pragma unroll
;             for (int i = 0; i < 64; ++i) S[i] = 0.f;
;     ...
;             In1 i0, i1; LD1(i0, 0);
; #pragma unroll 1
;             for (int s = 0; s < LC; s += 2) { TOUCH1(i0); SB; LD1(i1, s + 1); SB; ST1(i0); TOUCH1(i1); SB; LD1(i0, s + 2); SB; ST1(i1); }
;     ...
;         } else {
; #pragma unroll
;             for (int i = 0; i < 64; ++i) S[i] = (ln == i) ? 1.f : 0.f;
;     ...
;             In1 i0, i1; LD1(i0, 0);
; #pragma unroll 1
;             for (int s = 0; s < LC; s += 2) { TOUCH1(i0); SB; LD1(i1, s + 1); SB; ST1(i0); TOUCH1(i1); SB; LD1(i0, s + 2); SB; ST1(i1); }
.Lmy_p1d1_item:
	s_cmpk_gt_i32 s0, 0x7df
	s_cbranch_scc1 .Lmy_p1d1_end
	s_mul_i32 s86, s0, 2081
	s_lshr_b32 s86, s86, 17
	s_mul_i32 s7, s86, 63
	s_sub_u32 s85, s0, s7
	s_and_b32 s87, s86, 15
	s_lshr_b32 s6, s86, 4
	s_lshl_b32 s6, s6, 14
	s_lshl_b32 s7, s85, 8
	s_sub_u32 s7, 0x3fff, s7
	s_add_u32 s6, s6, s7
	s_lshl_b32 s6, s6, 10
	s_lshl_b32 s7, s87, 6
	s_add_u32 s84, s6, s7
	s_lshl_b32 s72, s84, 2
	s_lshl_b32 s76, s84, 1
	s_lshl_b32 s6, s86, 6
	s_add_u32 s6, s6, s85
	s_lshl_b32 s6, s6, 14
	s_add_u32 s7, s6, 0x15800000
	s_add_u32 s90, s56, s7
	s_addc_u32 s91, s57, 0
	s_add_u32 s7, s6, 0x13800000
	s_add_u32 s92, s56, s7
	s_addc_u32 s93, s57, 0
	s_lshl_b32 s8, s87, 8
	s_add_u32 s4, s42, s8
	s_addc_u32 s5, s43, 0
	v_and_b32_e32 v129, 15, v254
	v_lshlrev_b32_e32 v130, 4, v129
	global_load_dwordx4 v[216:219], v130, s[4:5]
	buffer_load_dwordx4 v[160:163], v235, s[64:67], s72 offen
	buffer_load_dwordx4 v[164:167], v250, s[64:67], s72 offen
	buffer_load_dwordx4 v[168:171], v251, s[64:67], s72 offen
	buffer_load_dwordx2 v[172:173], v252, s[64:67], s76 offen
	buffer_load_ushort v174, v253, s[64:67], s76 offen
	s_add_i32 s72, s72, 0xfffff000
	s_max_i32 s72, s72, 0
	s_add_i32 s76, s76, 0xfffff800
	s_max_i32 s76, s76, 0
	buffer_load_dwordx4 v[176:179], v235, s[64:67], s72 offen
	buffer_load_dwordx4 v[180:183], v250, s[64:67], s72 offen
	buffer_load_dwordx4 v[184:187], v251, s[64:67], s72 offen
	buffer_load_dwordx2 v[188:189], v252, s[64:67], s76 offen
	buffer_load_ushort v190, v253, s[64:67], s76 offen
	s_add_i32 s72, s72, 0xfffff000
	s_max_i32 s72, s72, 0
	s_add_i32 s76, s76, 0xfffff800
	s_max_i32 s76, s76, 0
	v_and_b32_e32 v128, 63, v254
	v_mov_b32_e32 v129, 1.0
	v_mov_b32_e32 v0, 0
	v_mov_b32_e32 v1, 0
	v_mov_b32_e32 v2, 0
	v_mov_b32_e32 v3, 0
	v_mov_b32_e32 v4, 0
	v_mov_b32_e32 v5, 0
	v_mov_b32_e32 v6, 0
	v_mov_b32_e32 v7, 0
	v_mov_b32_e32 v8, 0
	v_mov_b32_e32 v9, 0
	v_mov_b32_e32 v10, 0
	v_mov_b32_e32 v11, 0
	v_mov_b32_e32 v12, 0
	v_mov_b32_e32 v13, 0
	v_mov_b32_e32 v14, 0
	v_mov_b32_e32 v15, 0
	v_mov_b32_e32 v16, 0
	v_mov_b32_e32 v17, 0
	v_mov_b32_e32 v18, 0
	v_mov_b32_e32 v19, 0
	v_mov_b32_e32 v20, 0
	v_mov_b32_e32 v21, 0
	v_mov_b32_e32 v22, 0
	v_mov_b32_e32 v23, 0
	v_mov_b32_e32 v24, 0
	v_mov_b32_e32 v25, 0
	v_mov_b32_e32 v26, 0
	v_mov_b32_e32 v27, 0
	v_mov_b32_e32 v28, 0
	v_mov_b32_e32 v29, 0
	v_mov_b32_e32 v30, 0
	v_mov_b32_e32 v31, 0
	v_mov_b32_e32 v32, 0
	v_mov_b32_e32 v33, 0
	v_mov_b32_e32 v34, 0
	v_mov_b32_e32 v35, 0
	v_mov_b32_e32 v36, 0
	v_mov_b32_e32 v37, 0
	v_mov_b32_e32 v38, 0
	v_mov_b32_e32 v39, 0
	v_mov_b32_e32 v40, 0
	v_mov_b32_e32 v41, 0
	v_mov_b32_e32 v42, 0
	v_mov_b32_e32 v43, 0
	v_mov_b32_e32 v44, 0
	v_mov_b32_e32 v45, 0
	v_mov_b32_e32 v46, 0
	v_mov_b32_e32 v47, 0
	v_mov_b32_e32 v48, 0
	v_mov_b32_e32 v49, 0
	v_mov_b32_e32 v50, 0
	v_mov_b32_e32 v51, 0
	v_mov_b32_e32 v52, 0
	v_mov_b32_e32 v53, 0
	v_mov_b32_e32 v54, 0
	v_mov_b32_e32 v55, 0
	v_mov_b32_e32 v56, 0
	v_mov_b32_e32 v57, 0
	v_mov_b32_e32 v58, 0
	v_mov_b32_e32 v59, 0
	v_mov_b32_e32 v60, 0
	v_mov_b32_e32 v61, 0
	v_mov_b32_e32 v62, 0
	v_mov_b32_e32 v63, 0
	v_cmp_eq_u32_e32 vcc, 0, v128
	s_nop 1
	v_cndmask_b32_e32 v64, 0, v129, vcc
	v_cmp_eq_u32_e32 vcc, 1, v128
	s_nop 1
	v_cndmask_b32_e32 v65, 0, v129, vcc
	v_cmp_eq_u32_e32 vcc, 2, v128
	s_nop 1
	v_cndmask_b32_e32 v66, 0, v129, vcc
	v_cmp_eq_u32_e32 vcc, 3, v128
	s_nop 1
	v_cndmask_b32_e32 v67, 0, v129, vcc
	v_cmp_eq_u32_e32 vcc, 4, v128
	s_nop 1
	v_cndmask_b32_e32 v68, 0, v129, vcc
	v_cmp_eq_u32_e32 vcc, 5, v128
	s_nop 1
	v_cndmask_b32_e32 v69, 0, v129, vcc
	v_cmp_eq_u32_e32 vcc, 6, v128
	s_nop 1
	v_cndmask_b32_e32 v70, 0, v129, vcc
	v_cmp_eq_u32_e32 vcc, 7, v128
	s_nop 1
	v_cndmask_b32_e32 v71, 0, v129, vcc
	v_cmp_eq_u32_e32 vcc, 8, v128
	s_nop 1
	v_cndmask_b32_e32 v72, 0, v129, vcc
	v_cmp_eq_u32_e32 vcc, 9, v128
	s_nop 1
	v_cndmask_b32_e32 v73, 0, v129, vcc
	v_cmp_eq_u32_e32 vcc, 10, v128
	s_nop 1
	v_cndmask_b32_e32 v74, 0, v129, vcc
	v_cmp_eq_u32_e32 vcc, 11, v128
	s_nop 1
	v_cndmask_b32_e32 v75, 0, v129, vcc
	v_cmp_eq_u32_e32 vcc, 12, v128
	s_nop 1
	v_cndmask_b32_e32 v76, 0, v129, vcc
	v_cmp_eq_u32_e32 vcc, 13, v128
	s_nop 1
	v_cndmask_b32_e32 v77, 0, v129, vcc
	v_cmp_eq_u32_e32 vcc, 14, v128
	s_nop 1
; #define SB __builtin_amdgcn_sched_barrier(0)
; #define MKR(ptr) __builtin_amdgcn_make_buffer_rsrc((void*)(ptr), 0, 0x7fffffff, 0x00027000)
; #define LD1(set, s) { const int e_ = min((int)(s), LC - 1) * (int)stp; const unsigned s4_ = ob4 + (unsigned)(e_ * 4), s2_ = ob2 + (unsigned)(e_ * 2); set.w = LDX(rW, s4_); set.a = LDX(rA, s4_); set.b = LDX(rB, s4_); \
;             set.kw = __builtin_amdgcn_raw_buffer_load_b64(rK, lo8, s2_, 0); set.v = __builtin_amdgcn_raw_buffer_load_b16(rV, lo2, s2_, 0); }
; #define TOUCH1(set) asm volatile("" :: "v"(set.w), "v"(set.a), "v"(set.b), "v"(set.kw), "v"(set.v))
; #define ST1(set) { DERIVE_BK(set); float sd[4]; ScanK<0>::dot(S, set.a, sd); ScanK<0>::updS(S, set, -((sd[0] + sd[1]) + (sd[2] + sd[3])), __uint_as_float(set.v << 16)); }
; #define LD1(set, s) { const int e_ = min((int)(s), LC - 1) * (int)stp; const unsigned s4_ = ob4 + (unsigned)(e_ * 4); set.w = LDX(rW, s4_); set.a = LDX(rA, s4_); set.b = LDX(rB, s4_); }
; #define TOUCH1(set) asm volatile("" :: "v"(set.w), "v"(set.a), "v"(set.b))
; #define ST1(set) { DERIVE_B(set); float sd[4]; ScanK<0>::dot(S, set.a, sd); ScanK<0>::updP(S, set, -((sd[0] + sd[1]) + (sd[2] + sd[3]))); }
; template <bool MIX> __device__ __forceinline__ void scan_pass1(const Params& p, int d, float* ldsf) {
;     ...
;         const f32x4 ka4 = *(const f32x4*)(p.k_a + h * 64 + (lane & 15) * 4), c04 = 1.0f - ka4;
;         float S[64]; int ln = lane; asm volatile("" : "+v"(ln));
;     ...
;         const __amdgpu_buffer_rsrc_t rW = MKR(Wd), rA = MKR(A), rB = MKR(Bd), rK = MKR(KB), rV = MKR(V);
;         if (!isP) {
; #pragma unroll
;             for (int i = 0; i < 64; ++i) S[i] = 0.f;
;     ...
;             In1 i0, i1; LD1(i0, 0);
; #pragma unroll 1
;             for (int s = 0; s < LC; s += 2) { TOUCH1(i0); SB; LD1(i1, s + 1); SB; ST1(i0); TOUCH1(i1); SB; LD1(i0, s + 2); SB; ST1(i1); }
;     ...
;         } else {
; #pragma unroll
;             for (int i = 0; i < 64; ++i) S[i] = (ln == i) ? 1.f : 0.f;
;     ...
;             In1 i0, i1; LD1(i0, 0);
; #pragma unroll 1
;             for (int s = 0; s < LC; s += 2) { TOUCH1(i0); SB; LD1(i1, s + 1); SB; ST1(i0); TOUCH1(i1); SB; LD1(i0, s + 2); SB; ST1(i1); }
	v_cndmask_b32_e32 v78, 0, v129, vcc
	v_cmp_eq_u32_e32 vcc, 15, v128
	s_nop 1
	v_cndmask_b32_e32 v79, 0, v129, vcc
	v_cmp_eq_u32_e32 vcc, 16, v128
	s_nop 1
	v_cndmask_b32_e32 v80, 0, v129, vcc
	v_cmp_eq_u32_e32 vcc, 17, v128
	s_nop 1
	v_cndmask_b32_e32 v81, 0, v129, vcc
	v_cmp_eq_u32_e32 vcc, 18, v128
	s_nop 1
	v_cndmask_b32_e32 v82, 0, v129, vcc
	v_cmp_eq_u32_e32 vcc, 19, v128
	s_nop 1
	v_cndmask_b32_e32 v83, 0, v129, vcc
	v_cmp_eq_u32_e32 vcc, 20, v128
	s_nop 1
	v_cndmask_b32_e32 v84, 0, v129, vcc
	v_cmp_eq_u32_e32 vcc, 21, v128
	s_nop 1
	v_cndmask_b32_e32 v85, 0, v129, vcc
	v_cmp_eq_u32_e32 vcc, 22, v128
	s_nop 1
	v_cndmask_b32_e32 v86, 0, v129, vcc
	v_cmp_eq_u32_e32 vcc, 23, v128
	s_nop 1
	v_cndmask_b32_e32 v87, 0, v129, vcc
	v_cmp_eq_u32_e32 vcc, 24, v128
	s_nop 1
	v_cndmask_b32_e32 v88, 0, v129, vcc
	v_cmp_eq_u32_e32 vcc, 25, v128
	s_nop 1
	v_cndmask_b32_e32 v89, 0, v129, vcc
	v_cmp_eq_u32_e32 vcc, 26, v128
	s_nop 1
	v_cndmask_b32_e32 v90, 0, v129, vcc
	v_cmp_eq_u32_e32 vcc, 27, v128
	s_nop 1
	v_cndmask_b32_e32 v91, 0, v129, vcc
	v_cmp_eq_u32_e32 vcc, 28, v128
	s_nop 1
	v_cndmask_b32_e32 v92, 0, v129, vcc
	v_cmp_eq_u32_e32 vcc, 29, v128
	s_nop 1
	v_cndmask_b32_e32 v93, 0, v129, vcc
	v_cmp_eq_u32_e32 vcc, 30, v128
	s_nop 1
	v_cndmask_b32_e32 v94, 0, v129, vcc
	v_cmp_eq_u32_e32 vcc, 31, v128
	s_nop 1
	v_cndmask_b32_e32 v95, 0, v129, vcc
	v_cmp_eq_u32_e32 vcc, 32, v128
	s_nop 1
	v_cndmask_b32_e32 v96, 0, v129, vcc
	v_cmp_eq_u32_e32 vcc, 33, v128
	s_nop 1
	v_cndmask_b32_e32 v97, 0, v129, vcc
	v_cmp_eq_u32_e32 vcc, 34, v128
	s_nop 1
	v_cndmask_b32_e32 v98, 0, v129, vcc
	v_cmp_eq_u32_e32 vcc, 35, v128
	s_nop 1
	v_cndmask_b32_e32 v99, 0, v129, vcc
	v_cmp_eq_u32_e32 vcc, 36, v128
	s_nop 1
	v_cndmask_b32_e32 v100, 0, v129, vcc
	v_cmp_eq_u32_e32 vcc, 37, v128
	s_nop 1
	v_cndmask_b32_e32 v101, 0, v129, vcc
	v_cmp_eq_u32_e32 vcc, 38, v128
	s_nop 1
	v_cndmask_b32_e32 v102, 0, v129, vcc
	v_cmp_eq_u32_e32 vcc, 39, v128
	s_nop 1
	v_cndmask_b32_e32 v103, 0, v129, vcc
	v_cmp_eq_u32_e32 vcc, 40, v128
	s_nop 1
	v_cndmask_b32_e32 v104, 0, v129, vcc
	v_cmp_eq_u32_e32 vcc, 41, v128
	s_nop 1
	v_cndmask_b32_e32 v105, 0, v129, vcc
	v_cmp_eq_u32_e32 vcc, 42, v128
	s_nop 1
	v_cndmask_b32_e32 v106, 0, v129, vcc
	v_cmp_eq_u32_e32 vcc, 43, v128
	s_nop 1
	v_cndmask_b32_e32 v107, 0, v129, vcc
	v_cmp_eq_u32_e32 vcc, 44, v128
	s_nop 1
	v_cndmask_b32_e32 v108, 0, v129, vcc
	v_cmp_eq_u32_e32 vcc, 45, v128
	s_nop 1
	v_cndmask_b32_e32 v109, 0, v129, vcc
	v_cmp_eq_u32_e32 vcc, 46, v128
	s_nop 1
	v_cndmask_b32_e32 v110, 0, v129, vcc
	v_cmp_eq_u32_e32 vcc, 47, v128
	s_nop 1
	v_cndmask_b32_e32 v111, 0, v129, vcc
	v_cmp_eq_u32_e32 vcc, 48, v128
	s_nop 1
	v_cndmask_b32_e32 v112, 0, v129, vcc
	v_cmp_eq_u32_e32 vcc, 49, v128
	s_nop 1
	v_cndmask_b32_e32 v113, 0, v129, vcc
	v_cmp_eq_u32_e32 vcc, 50, v128
	s_nop 1
	v_cndmask_b32_e32 v114, 0, v129, vcc
	v_cmp_eq_u32_e32 vcc, 51, v128
	s_nop 1
	v_cndmask_b32_e32 v115, 0, v129, vcc
	v_cmp_eq_u32_e32 vcc, 52, v128
	s_nop 1
	v_cndmask_b32_e32 v116, 0, v129, vcc
	v_cmp_eq_u32_e32 vcc, 53, v128
	s_nop 1
	v_cndmask_b32_e32 v117, 0, v129, vcc
	v_cmp_eq_u32_e32 vcc, 54, v128
	s_nop 1
	v_cndmask_b32_e32 v118, 0, v129, vcc
	v_cmp_eq_u32_e32 vcc, 55, v128
	s_nop 1
	v_cndmask_b32_e32 v119, 0, v129, vcc
	v_cmp_eq_u32_e32 vcc, 56, v128
	s_nop 1
	v_cndmask_b32_e32 v120, 0, v129, vcc
	v_cmp_eq_u32_e32 vcc, 57, v128
	s_nop 1
	v_cndmask_b32_e32 v121, 0, v129, vcc
	v_cmp_eq_u32_e32 vcc, 58, v128
	s_nop 1
	v_cndmask_b32_e32 v122, 0, v129, vcc
	v_cmp_eq_u32_e32 vcc, 59, v128
	s_nop 1
	v_cndmask_b32_e32 v123, 0, v129, vcc
	v_cmp_eq_u32_e32 vcc, 60, v128
	s_nop 1
	v_cndmask_b32_e32 v124, 0, v129, vcc
	v_cmp_eq_u32_e32 vcc, 61, v128
	s_nop 1
	v_cndmask_b32_e32 v125, 0, v129, vcc
	v_cmp_eq_u32_e32 vcc, 62, v128
	s_nop 1
	v_cndmask_b32_e32 v126, 0, v129, vcc
	v_cmp_eq_u32_e32 vcc, 63, v128
	s_nop 1
	v_cndmask_b32_e32 v127, 0, v129, vcc
	s_waitcnt vmcnt(0)
	v_sub_f32_e32 v220, 1.0, v216
	v_sub_f32_e32 v221, 1.0, v217
	v_sub_f32_e32 v222, 1.0, v218
	v_sub_f32_e32 v223, 1.0, v219
	v_mov_b32_e32 v236, 1.0
	v_mov_b32_e32 v237, 1.0
	v_mov_b32_e32 v238, 1.0
	v_mov_b32_e32 v239, 1.0
	s_movk_i32 s83, 85
	s_movk_i32 s9, 22
	s_branch .Lmy_p1d1_loop

;     static __device__ __forceinline__ void dot(const float (&S)[64], const f32x4& a, float (&s)[4]) {
;         if constexpr (K == 0) {
;             asm volatile("v_mul_f32_dpp %0, %4, %8 row_newbcast:%16" DPPM "v_mul_f32_dpp %1, %5, %9 row_newbcast:%16" DPPM "v_mul_f32_dpp %2, %6, %10 row_newbcast:%16" DPPM "v_mul_f32_dpp %3, %7, %11 row_newbcast:%16" DPPM
;                          "v_fmac_f32_dpp %0, %4, %12 row_newbcast:%17" DPPM "v_fmac_f32_dpp %1, %5, %13 row_newbcast:%17" DPPM "v_fmac_f32_dpp %2, %6, %14 row_newbcast:%17" DPPM "v_fmac_f32_dpp %3, %7, %15 row_newbcast:%17" DPPM
;                          : "=&v"(s[0]), "=&v"(s[1]), "=&v"(s[2]), "=&v"(s[3])
;                          : "v"(a[0]), "v"(a[1]), "v"(a[2]), "v"(a[3]), "v"(S[K]), "v"(S[K + 1]), "v"(S[K + 2]), "v"(S[K + 3]), "v"(S[K + 4]), "v"(S[K + 5]), "v"(S[K + 6]), "v"(S[K + 7]), "n"(N0), "n"(N1));
;         } else
;         asm volatile("v_fmac_f32_dpp %0, %4, %8 row_newbcast:%16" DPPM "v_fmac_f32_dpp %1, %5, %9 row_newbcast:%16" DPPM "v_fmac_f32_dpp %2, %6, %10 row_newbcast:%16" DPPM "v_fmac_f32_dpp %3, %7, %11 row_newbcast:%16" DPPM
;                      "v_fmac_f32_dpp %0, %4, %12 row_newbcast:%17" DPPM "v_fmac_f32_dpp %1, %5, %13 row_newbcast:%17" DPPM "v_fmac_f32_dpp %2, %6, %14 row_newbcast:%17" DPPM "v_fmac_f32_dpp %3, %7, %15 row_newbcast:%17" DPPM
;                      : "+v"(s[0]), "+v"(s[1]), "+v"(s[2]), "+v"(s[3])
;                      : "v"(a[0]), "v"(a[1]), "v"(a[2]), "v"(a[3]), "v"(S[K]), "v"(S[K + 1]), "v"(S[K + 2]), "v"(S[K + 3]), "v"(S[K + 4]), "v"(S[K + 5]), "v"(S[K + 6]), "v"(S[K + 7]), "n"(N0), "n"(N1));
;         if constexpr (K + 8 < 64) ScanK<K + 8>::dot(S, a, s);
;     }
;     static __device__ __forceinline__ void upd(float (&S)[64], const In2& in, float sa, float vv, float& y0, float& y1) {
;         float t0, t1, t2, t3;
;         asm volatile("v_mul_f32_dpp %0, %10, %27 row_newbcast:%28" DPPM "v_mul_f32_dpp %1, %11, %27 row_newbcast:%28" DPPM "v_mul_f32_dpp %2, %12, %27 row_newbcast:%28" DPPM "v_mul_f32_dpp %3, %13, %27 row_newbcast:%28" DPPM
;                      "v_fmac_f32_dpp %0, %14, %6 row_newbcast:%28" DPPM "v_fmac_f32_dpp %1, %15, %7 row_newbcast:%28" DPPM "v_fmac_f32_dpp %2, %16, %8 row_newbcast:%28" DPPM "v_fmac_f32_dpp %3, %17, %9 row_newbcast:%28" DPPM
.Lmy_p2d1_nost:
	buffer_load_dwordx4 v[156:159], v232, s[64:67], s72 offen
	buffer_load_dwordx4 v[160:163], v233, s[64:67], s72 offen
	buffer_load_dwordx4 v[164:167], v234, s[64:67], s72 offen
	buffer_load_dwordx4 v[168:171], v235, s[64:67], s72 offen
	buffer_load_dwordx2 v[172:173], v236, s[64:67], s76 offen
	buffer_load_ushort v174, v237, s[64:67], s76 offen
	buffer_load_dword v175, v207, s[68:71], s78 offen
	s_add_i32 s72, s72, 0xfffff000
	s_max_i32 s72, s72, 0
	s_add_i32 s76, s76, 0xfffff800
	s_max_i32 s76, s76, 0
	s_add_i32 s78, s78, 0xfffff000
	s_max_i32 s78, s78, 0
	v_pk_mul_f32 v[224:225], v[100:101], v[216:217]
	v_pk_mul_f32 v[226:227], v[102:103], v[218:219]
	v_pk_mul_f32 v[216:217], v[216:217], v[96:97]
	v_pk_mul_f32 v[218:219], v[218:219], v[98:99]
	v_pk_fma_f32 v[184:185], v[104:105], v[188:189], v[192:193]
	v_pk_fma_f32 v[186:187], v[106:107], v[190:191], v[194:195]
	v_pk_mul_f32 v[176:177], v[100:101], v[104:105]
	v_pk_mul_f32 v[178:179], v[102:103], v[106:107]
	v_rcp_f32_e32 v220, v216
	v_rcp_f32_e32 v221, v217
	v_rcp_f32_e32 v222, v218
	v_rcp_f32_e32 v223, v219
	v_lshlrev_b32_e32 v180, 16, v112
	v_and_b32_e32 v181, 0xffff0000, v112
	v_lshlrev_b32_e32 v182, 16, v113
	v_and_b32_e32 v183, 0xffff0000, v113
	v_pk_mul_f32 v[180:181], v[180:181], v[184:185]
	v_pk_mul_f32 v[182:183], v[182:183], v[186:187]
	v_pk_mul_f32 v[228:229], v[108:109], v[216:217]
	v_pk_mul_f32 v[230:231], v[110:111], v[218:219]
	v_pk_mul_f32 v[176:177], v[176:177], v[220:221]
	v_pk_mul_f32 v[178:179], v[178:179], v[222:223]
	v_pk_mul_f32 v[180:181], v[180:181], v[220:221]
	v_pk_mul_f32 v[182:183], v[182:183], v[222:223]
	v_lshlrev_b32_e32 v203, 16, v114
	ds_write2_b32 v208, v176, v177 offset0:0 offset1:16
	ds_write2_b32 v208, v178, v179 offset0:32 offset1:48
	ds_write2_b32 v208, v180, v181 offset0:64 offset1:80
	ds_write2_b32 v208, v182, v183 offset0:96 offset1:112
	ds_read_b128 v[64:67], v209 offset:0
	ds_read_b128 v[68:71], v209 offset:16
	ds_read_b128 v[72:75], v209 offset:32
	ds_read_b128 v[76:79], v209 offset:48
	ds_read_b128 v[80:83], v209 offset:256
	ds_read_b128 v[84:87], v209 offset:272
	ds_read_b128 v[88:91], v209 offset:288
	ds_read_b128 v[92:95], v209 offset:304
	v_mul_f32_dpp v196, v224, v0 row_newbcast:0 row_mask:0xf bank_mask:0xf
	v_mul_f32_dpp v197, v225, v1 row_newbcast:0 row_mask:0xf bank_mask:0xf
	v_mul_f32_dpp v198, v226, v2 row_newbcast:0 row_mask:0xf bank_mask:0xf
	v_mul_f32_dpp v199, v227, v3 row_newbcast:0 row_mask:0xf bank_mask:0xf
	v_fmac_f32_dpp v196, v224, v4 row_newbcast:1 row_mask:0xf bank_mask:0xf
	v_fmac_f32_dpp v197, v225, v5 row_newbcast:1 row_mask:0xf bank_mask:0xf
	v_fmac_f32_dpp v198, v226, v6 row_newbcast:1 row_mask:0xf bank_mask:0xf
	v_fmac_f32_dpp v199, v227, v7 row_newbcast:1 row_mask:0xf bank_mask:0xf
	v_fmac_f32_dpp v196, v224, v8 row_newbcast:2 row_mask:0xf bank_mask:0xf
	v_fmac_f32_dpp v197, v225, v9 row_newbcast:2 row_mask:0xf bank_mask:0xf
	v_fmac_f32_dpp v198, v226, v10 row_newbcast:2 row_mask:0xf bank_mask:0xf
	v_fmac_f32_dpp v199, v227, v11 row_newbcast:2 row_mask:0xf bank_mask:0xf
	v_fmac_f32_dpp v196, v224, v12 row_newbcast:3 row_mask:0xf bank_mask:0xf
	v_fmac_f32_dpp v197, v225, v13 row_newbcast:3 row_mask:0xf bank_mask:0xf
	v_fmac_f32_dpp v198, v226, v14 row_newbcast:3 row_mask:0xf bank_mask:0xf
	v_fmac_f32_dpp v199, v227, v15 row_newbcast:3 row_mask:0xf bank_mask:0xf
	v_fmac_f32_dpp v196, v224, v16 row_newbcast:4 row_mask:0xf bank_mask:0xf
	v_fmac_f32_dpp v197, v225, v17 row_newbcast:4 row_mask:0xf bank_mask:0xf
	v_fmac_f32_dpp v198, v226, v18 row_newbcast:4 row_mask:0xf bank_mask:0xf
	v_fmac_f32_dpp v199, v227, v19 row_newbcast:4 row_mask:0xf bank_mask:0xf
	v_fmac_f32_dpp v196, v224, v20 row_newbcast:5 row_mask:0xf bank_mask:0xf
	v_fmac_f32_dpp v197, v225, v21 row_newbcast:5 row_mask:0xf bank_mask:0xf
	v_fmac_f32_dpp v198, v226, v22 row_newbcast:5 row_mask:0xf bank_mask:0xf
	v_fmac_f32_dpp v199, v227, v23 row_newbcast:5 row_mask:0xf bank_mask:0xf
	v_fmac_f32_dpp v196, v224, v24 row_newbcast:6 row_mask:0xf bank_mask:0xf
	v_fmac_f32_dpp v197, v225, v25 row_newbcast:6 row_mask:0xf bank_mask:0xf
	v_fmac_f32_dpp v198, v226, v26 row_newbcast:6 row_mask:0xf bank_mask:0xf
	v_fmac_f32_dpp v199, v227, v27 row_newbcast:6 row_mask:0xf bank_mask:0xf
	v_fmac_f32_dpp v196, v224, v28 row_newbcast:7 row_mask:0xf bank_mask:0xf
	v_fmac_f32_dpp v197, v225, v29 row_newbcast:7 row_mask:0xf bank_mask:0xf
	v_fmac_f32_dpp v198, v226, v30 row_newbcast:7 row_mask:0xf bank_mask:0xf
	v_fmac_f32_dpp v199, v227, v31 row_newbcast:7 row_mask:0xf bank_mask:0xf
	v_fmac_f32_dpp v196, v224, v32 row_newbcast:8 row_mask:0xf bank_mask:0xf
	v_fmac_f32_dpp v197, v225, v33 row_newbcast:8 row_mask:0xf bank_mask:0xf
	v_fmac_f32_dpp v198, v226, v34 row_newbcast:8 row_mask:0xf bank_mask:0xf
	v_fmac_f32_dpp v199, v227, v35 row_newbcast:8 row_mask:0xf bank_mask:0xf
	v_fmac_f32_dpp v196, v224, v36 row_newbcast:9 row_mask:0xf bank_mask:0xf
	v_fmac_f32_dpp v197, v225, v37 row_newbcast:9 row_mask:0xf bank_mask:0xf
	v_fmac_f32_dpp v198, v226, v38 row_newbcast:9 row_mask:0xf bank_mask:0xf
	v_fmac_f32_dpp v199, v227, v39 row_newbcast:9 row_mask:0xf bank_mask:0xf
	v_fmac_f32_dpp v196, v224, v40 row_newbcast:10 row_mask:0xf bank_mask:0xf
	v_fmac_f32_dpp v197, v225, v41 row_newbcast:10 row_mask:0xf bank_mask:0xf
	v_fmac_f32_dpp v198, v226, v42 row_newbcast:10 row_mask:0xf bank_mask:0xf
	v_fmac_f32_dpp v199, v227, v43 row_newbcast:10 row_mask:0xf bank_mask:0xf
	v_fmac_f32_dpp v196, v224, v44 row_newbcast:11 row_mask:0xf bank_mask:0xf
	v_fmac_f32_dpp v197, v225, v45 row_newbcast:11 row_mask:0xf bank_mask:0xf
	v_fmac_f32_dpp v198, v226, v46 row_newbcast:11 row_mask:0xf bank_mask:0xf
;     static __device__ __forceinline__ void dot(const float (&S)[64], const f32x4& a, float (&s)[4]) {
;         if constexpr (K == 0) {
;             asm volatile("v_mul_f32_dpp %0, %4, %8 row_newbcast:%16" DPPM "v_mul_f32_dpp %1, %5, %9 row_newbcast:%16" DPPM "v_mul_f32_dpp %2, %6, %10 row_newbcast:%16" DPPM "v_mul_f32_dpp %3, %7, %11 row_newbcast:%16" DPPM
;                          "v_fmac_f32_dpp %0, %4, %12 row_newbcast:%17" DPPM "v_fmac_f32_dpp %1, %5, %13 row_newbcast:%17" DPPM "v_fmac_f32_dpp %2, %6, %14 row_newbcast:%17" DPPM "v_fmac_f32_dpp %3, %7, %15 row_newbcast:%17" DPPM
;                          : "=&v"(s[0]), "=&v"(s[1]), "=&v"(s[2]), "=&v"(s[3])
;                          : "v"(a[0]), "v"(a[1]), "v"(a[2]), "v"(a[3]), "v"(S[K]), "v"(S[K + 1]), "v"(S[K + 2]), "v"(S[K + 3]), "v"(S[K + 4]), "v"(S[K + 5]), "v"(S[K + 6]), "v"(S[K + 7]), "n"(N0), "n"(N1));
;         } else
;         asm volatile("v_fmac_f32_dpp %0, %4, %8 row_newbcast:%16" DPPM "v_fmac_f32_dpp %1, %5, %9 row_newbcast:%16" DPPM "v_fmac_f32_dpp %2, %6, %10 row_newbcast:%16" DPPM "v_fmac_f32_dpp %3, %7, %11 row_newbcast:%16" DPPM
;                      "v_fmac_f32_dpp %0, %4, %12 row_newbcast:%17" DPPM "v_fmac_f32_dpp %1, %5, %13 row_newbcast:%17" DPPM "v_fmac_f32_dpp %2, %6, %14 row_newbcast:%17" DPPM "v_fmac_f32_dpp %3, %7, %15 row_newbcast:%17" DPPM
;                      : "+v"(s[0]), "+v"(s[1]), "+v"(s[2]), "+v"(s[3])
;                      : "v"(a[0]), "v"(a[1]), "v"(a[2]), "v"(a[3]), "v"(S[K]), "v"(S[K + 1]), "v"(S[K + 2]), "v"(S[K + 3]), "v"(S[K + 4]), "v"(S[K + 5]), "v"(S[K + 6]), "v"(S[K + 7]), "n"(N0), "n"(N1));
;         if constexpr (K + 8 < 64) ScanK<K + 8>::dot(S, a, s);
;     }
;     static __device__ __forceinline__ void upd(float (&S)[64], const In2& in, float sa, float vv, float& y0, float& y1) {
;         float t0, t1, t2, t3;
;         asm volatile("v_mul_f32_dpp %0, %10, %27 row_newbcast:%28" DPPM "v_mul_f32_dpp %1, %11, %27 row_newbcast:%28" DPPM "v_mul_f32_dpp %2, %12, %27 row_newbcast:%28" DPPM "v_mul_f32_dpp %3, %13, %27 row_newbcast:%28" DPPM
;                      "v_fmac_f32_dpp %0, %14, %6 row_newbcast:%28" DPPM "v_fmac_f32_dpp %1, %15, %7 row_newbcast:%28" DPPM "v_fmac_f32_dpp %2, %16, %8 row_newbcast:%28" DPPM "v_fmac_f32_dpp %3, %17, %9 row_newbcast:%28" DPPM
	v_fmac_f32_dpp v199, v227, v47 row_newbcast:11 row_mask:0xf bank_mask:0xf
	v_fmac_f32_dpp v196, v224, v48 row_newbcast:12 row_mask:0xf bank_mask:0xf
	v_fmac_f32_dpp v197, v225, v49 row_newbcast:12 row_mask:0xf bank_mask:0xf
	v_fmac_f32_dpp v198, v226, v50 row_newbcast:12 row_mask:0xf bank_mask:0xf
	v_fmac_f32_dpp v199, v227, v51 row_newbcast:12 row_mask:0xf bank_mask:0xf
	v_fmac_f32_dpp v196, v224, v52 row_newbcast:13 row_mask:0xf bank_mask:0xf
	v_fmac_f32_dpp v197, v225, v53 row_newbcast:13 row_mask:0xf bank_mask:0xf
	v_fmac_f32_dpp v198, v226, v54 row_newbcast:13 row_mask:0xf bank_mask:0xf
	v_fmac_f32_dpp v199, v227, v55 row_newbcast:13 row_mask:0xf bank_mask:0xf
	v_fmac_f32_dpp v196, v224, v56 row_newbcast:14 row_mask:0xf bank_mask:0xf
	v_fmac_f32_dpp v197, v225, v57 row_newbcast:14 row_mask:0xf bank_mask:0xf
	v_fmac_f32_dpp v198, v226, v58 row_newbcast:14 row_mask:0xf bank_mask:0xf
	v_fmac_f32_dpp v199, v227, v59 row_newbcast:14 row_mask:0xf bank_mask:0xf
	v_fmac_f32_dpp v196, v224, v60 row_newbcast:15 row_mask:0xf bank_mask:0xf
	v_fmac_f32_dpp v197, v225, v61 row_newbcast:15 row_mask:0xf bank_mask:0xf
	v_fmac_f32_dpp v198, v226, v62 row_newbcast:15 row_mask:0xf bank_mask:0xf
	v_fmac_f32_dpp v199, v227, v63 row_newbcast:15 row_mask:0xf bank_mask:0xf
	v_add_f32_e32 v196, v196, v197
	v_add_f32_e32 v198, v198, v199
	v_sub_f32_e64 v202, -v196, v198
	s_waitcnt lgkmcnt(0)
	s_nop 1
	v_mfma_f32_4x4x1_16b_f32 v[0:3], v64, v202, v[0:3]
	v_mfma_f32_4x4x1_16b_f32 v[4:7], v65, v202, v[4:7]
	v_mfma_f32_4x4x1_16b_f32 v[8:11], v66, v202, v[8:11]
	v_mfma_f32_4x4x1_16b_f32 v[12:15], v67, v202, v[12:15]
	v_mfma_f32_4x4x1_16b_f32 v[16:19], v68, v202, v[16:19]
	v_mfma_f32_4x4x1_16b_f32 v[20:23], v69, v202, v[20:23]
	v_mfma_f32_4x4x1_16b_f32 v[24:27], v70, v202, v[24:27]
	v_mfma_f32_4x4x1_16b_f32 v[28:31], v71, v202, v[28:31]
	v_mfma_f32_4x4x1_16b_f32 v[32:35], v72, v202, v[32:35]
	v_mfma_f32_4x4x1_16b_f32 v[36:39], v73, v202, v[36:39]
	v_mfma_f32_4x4x1_16b_f32 v[40:43], v74, v202, v[40:43]
	v_mfma_f32_4x4x1_16b_f32 v[44:47], v75, v202, v[44:47]
	v_mfma_f32_4x4x1_16b_f32 v[48:51], v76, v202, v[48:51]
	v_mfma_f32_4x4x1_16b_f32 v[52:55], v77, v202, v[52:55]
	v_mfma_f32_4x4x1_16b_f32 v[56:59], v78, v202, v[56:59]
	v_mfma_f32_4x4x1_16b_f32 v[60:63], v79, v202, v[60:63]
	v_mfma_f32_4x4x1_16b_f32 v[0:3], v80, v203, v[0:3]
	v_mfma_f32_4x4x1_16b_f32 v[4:7], v81, v203, v[4:7]
	v_mfma_f32_4x4x1_16b_f32 v[8:11], v82, v203, v[8:11]
	v_mfma_f32_4x4x1_16b_f32 v[12:15], v83, v203, v[12:15]
	v_mfma_f32_4x4x1_16b_f32 v[16:19], v84, v203, v[16:19]
	v_mfma_f32_4x4x1_16b_f32 v[20:23], v85, v203, v[20:23]
	v_mfma_f32_4x4x1_16b_f32 v[24:27], v86, v203, v[24:27]
	v_mfma_f32_4x4x1_16b_f32 v[28:31], v87, v203, v[28:31]
	v_mfma_f32_4x4x1_16b_f32 v[32:35], v88, v203, v[32:35]
	v_mfma_f32_4x4x1_16b_f32 v[36:39], v89, v203, v[36:39]
	v_mfma_f32_4x4x1_16b_f32 v[40:43], v90, v203, v[40:43]
	v_mfma_f32_4x4x1_16b_f32 v[44:47], v91, v203, v[44:47]
	v_mfma_f32_4x4x1_16b_f32 v[48:51], v92, v203, v[48:51]
	v_mfma_f32_4x4x1_16b_f32 v[52:55], v93, v203, v[52:55]
	v_mfma_f32_4x4x1_16b_f32 v[56:59], v94, v203, v[56:59]
	v_mfma_f32_4x4x1_16b_f32 v[60:63], v95, v203, v[60:63]
	v_fmac_f32_dpp v115, v228, v0 row_newbcast:0 row_mask:0xf bank_mask:0xf
	v_mul_f32_dpp v201, v229, v1 row_newbcast:0 row_mask:0xf bank_mask:0xf
	v_fmac_f32_dpp v115, v230, v2 row_newbcast:0 row_mask:0xf bank_mask:0xf
	v_fmac_f32_dpp v201, v231, v3 row_newbcast:0 row_mask:0xf bank_mask:0xf
	v_fmac_f32_dpp v115, v228, v4 row_newbcast:1 row_mask:0xf bank_mask:0xf
	v_fmac_f32_dpp v201, v229, v5 row_newbcast:1 row_mask:0xf bank_mask:0xf
	v_fmac_f32_dpp v115, v230, v6 row_newbcast:1 row_mask:0xf bank_mask:0xf
	v_fmac_f32_dpp v201, v231, v7 row_newbcast:1 row_mask:0xf bank_mask:0xf
	v_fmac_f32_dpp v115, v228, v8 row_newbcast:2 row_mask:0xf bank_mask:0xf
	v_fmac_f32_dpp v201, v229, v9 row_newbcast:2 row_mask:0xf bank_mask:0xf
	v_fmac_f32_dpp v115, v230, v10 row_newbcast:2 row_mask:0xf bank_mask:0xf
	v_fmac_f32_dpp v201, v231, v11 row_newbcast:2 row_mask:0xf bank_mask:0xf
	v_fmac_f32_dpp v115, v228, v12 row_newbcast:3 row_mask:0xf bank_mask:0xf
	v_fmac_f32_dpp v201, v229, v13 row_newbcast:3 row_mask:0xf bank_mask:0xf
	v_fmac_f32_dpp v115, v230, v14 row_newbcast:3 row_mask:0xf bank_mask:0xf
	v_fmac_f32_dpp v201, v231, v15 row_newbcast:3 row_mask:0xf bank_mask:0xf
	v_fmac_f32_dpp v115, v228, v16 row_newbcast:4 row_mask:0xf bank_mask:0xf
	v_fmac_f32_dpp v201, v229, v17 row_newbcast:4 row_mask:0xf bank_mask:0xf
	v_fmac_f32_dpp v115, v230, v18 row_newbcast:4 row_mask:0xf bank_mask:0xf
	v_fmac_f32_dpp v201, v231, v19 row_newbcast:4 row_mask:0xf bank_mask:0xf
	v_fmac_f32_dpp v115, v228, v20 row_newbcast:5 row_mask:0xf bank_mask:0xf
	v_fmac_f32_dpp v201, v229, v21 row_newbcast:5 row_mask:0xf bank_mask:0xf
	v_fmac_f32_dpp v115, v230, v22 row_newbcast:5 row_mask:0xf bank_mask:0xf
	v_fmac_f32_dpp v201, v231, v23 row_newbcast:5 row_mask:0xf bank_mask:0xf
	v_fmac_f32_dpp v115, v228, v24 row_newbcast:6 row_mask:0xf bank_mask:0xf
	v_fmac_f32_dpp v201, v229, v25 row_newbcast:6 row_mask:0xf bank_mask:0xf
	v_fmac_f32_dpp v115, v230, v26 row_newbcast:6 row_mask:0xf bank_mask:0xf
	v_fmac_f32_dpp v201, v231, v27 row_newbcast:6 row_mask:0xf bank_mask:0xf
	v_fmac_f32_dpp v115, v228, v28 row_newbcast:7 row_mask:0xf bank_mask:0xf
	v_fmac_f32_dpp v201, v229, v29 row_newbcast:7 row_mask:0xf bank_mask:0xf
	v_fmac_f32_dpp v115, v230, v30 row_newbcast:7 row_mask:0xf bank_mask:0xf
	v_fmac_f32_dpp v201, v231, v31 row_newbcast:7 row_mask:0xf bank_mask:0xf
	v_fmac_f32_dpp v115, v228, v32 row_newbcast:8 row_mask:0xf bank_mask:0xf
; #define SB __builtin_amdgcn_sched_barrier(0)
; #define ST2(set, s) { DERIVE_BK(set); float sd[4]; ScanK<0>::dot(S, set.a, sd); float y0 = set.yo, y1 = 0.f; ScanK<0>::upd(S, set, -((sd[0] + sd[1]) + (sd[2] + sd[3])), __uint_as_float(set.v << 16), y0, y1); __builtin_amdgcn_raw_buffer_store_b32(__float_as_uint(y0 + y1), rY, lo4b, ob4 + (unsigned)((int)(s) * (int)stp * 4), 0); }
;     static __device__ __forceinline__ void upd(float (&S)[64], const In2& in, float sa, float vv, float& y0, float& y1) {
;         float t0, t1, t2, t3;
;         asm volatile("v_mul_f32_dpp %0, %10, %27 row_newbcast:%28" DPPM "v_mul_f32_dpp %1, %11, %27 row_newbcast:%28" DPPM "v_mul_f32_dpp %2, %12, %27 row_newbcast:%28" DPPM "v_mul_f32_dpp %3, %13, %27 row_newbcast:%28" DPPM
;                      "v_fmac_f32_dpp %0, %14, %6 row_newbcast:%28" DPPM "v_fmac_f32_dpp %1, %15, %7 row_newbcast:%28" DPPM "v_fmac_f32_dpp %2, %16, %8 row_newbcast:%28" DPPM "v_fmac_f32_dpp %3, %17, %9 row_newbcast:%28" DPPM
;                      "v_fmac_f32_dpp %0, %18, %26 row_newbcast:%28" DPPM "v_fmac_f32_dpp %1, %19, %26 row_newbcast:%28" DPPM "v_fmac_f32_dpp %2, %20, %26 row_newbcast:%28" DPPM "v_fmac_f32_dpp %3, %21, %26 row_newbcast:%28" DPPM
;                      "v_fmac_f32_dpp %4, %22, %0 row_newbcast:%28" DPPM "v_fmac_f32_dpp %5, %23, %1 row_newbcast:%28" DPPM "v_fmac_f32_dpp %4, %24, %2 row_newbcast:%28" DPPM "v_fmac_f32_dpp %5, %25, %3 row_newbcast:%28" DPPM
;                      : "=&v"(t0), "=&v"(t1), "=&v"(t2), "=&v"(t3), "+v"(y0), "+v"(y1)
;                      : "v"(S[K]), "v"(S[K + 1]), "v"(S[K + 2]), "v"(S[K + 3]), "v"(in.kd[0]), "v"(in.kd[1]), "v"(in.kd[2]), "v"(in.kd[3]), "v"(in.w[0]), "v"(in.w[1]), "v"(in.w[2]), "v"(in.w[3]),
;                        "v"(in.b[0]), "v"(in.b[1]), "v"(in.b[2]), "v"(in.b[3]), "v"(in.r[0]), "v"(in.r[1]), "v"(in.r[2]), "v"(in.r[3]), "v"(sa), "v"(vv), "n"(N0));
;         S[K] = t0; S[K + 1] = t1; S[K + 2] = t2; S[K + 3] = t3;
;         if constexpr (K + 4 < 64) ScanK<K + 4>::upd(S, in, sa, vv, y0, y1);
; __device__ __forceinline__ void scan_pass2(const Params& p, int d) {
;     ...
;         In2 i0, i1; LD2(i0, 0);
; #pragma unroll 1
;         for (int s = 0; s < LC; s += 2) { TOUCH2(i0); SB; LD2(i1, s + 1); SB; ST2(i0, s); TOUCH2(i1); SB; LD2(i0, s + 2); SB; ST2(i1, s + 1); }
	v_fmac_f32_dpp v201, v229, v33 row_newbcast:8 row_mask:0xf bank_mask:0xf
	v_fmac_f32_dpp v115, v230, v34 row_newbcast:8 row_mask:0xf bank_mask:0xf
	v_fmac_f32_dpp v201, v231, v35 row_newbcast:8 row_mask:0xf bank_mask:0xf
	v_fmac_f32_dpp v115, v228, v36 row_newbcast:9 row_mask:0xf bank_mask:0xf
	v_fmac_f32_dpp v201, v229, v37 row_newbcast:9 row_mask:0xf bank_mask:0xf
	v_fmac_f32_dpp v115, v230, v38 row_newbcast:9 row_mask:0xf bank_mask:0xf
	v_fmac_f32_dpp v201, v231, v39 row_newbcast:9 row_mask:0xf bank_mask:0xf
	v_fmac_f32_dpp v115, v228, v40 row_newbcast:10 row_mask:0xf bank_mask:0xf
	v_fmac_f32_dpp v201, v229, v41 row_newbcast:10 row_mask:0xf bank_mask:0xf
	v_fmac_f32_dpp v115, v230, v42 row_newbcast:10 row_mask:0xf bank_mask:0xf
	v_fmac_f32_dpp v201, v231, v43 row_newbcast:10 row_mask:0xf bank_mask:0xf
	v_fmac_f32_dpp v115, v228, v44 row_newbcast:11 row_mask:0xf bank_mask:0xf
	v_fmac_f32_dpp v201, v229, v45 row_newbcast:11 row_mask:0xf bank_mask:0xf
	v_fmac_f32_dpp v115, v230, v46 row_newbcast:11 row_mask:0xf bank_mask:0xf
	v_fmac_f32_dpp v201, v231, v47 row_newbcast:11 row_mask:0xf bank_mask:0xf
	v_fmac_f32_dpp v115, v228, v48 row_newbcast:12 row_mask:0xf bank_mask:0xf
	v_fmac_f32_dpp v201, v229, v49 row_newbcast:12 row_mask:0xf bank_mask:0xf
	v_fmac_f32_dpp v115, v230, v50 row_newbcast:12 row_mask:0xf bank_mask:0xf
	v_fmac_f32_dpp v201, v231, v51 row_newbcast:12 row_mask:0xf bank_mask:0xf
	v_fmac_f32_dpp v115, v228, v52 row_newbcast:13 row_mask:0xf bank_mask:0xf
	v_fmac_f32_dpp v201, v229, v53 row_newbcast:13 row_mask:0xf bank_mask:0xf
	v_fmac_f32_dpp v115, v230, v54 row_newbcast:13 row_mask:0xf bank_mask:0xf
	v_fmac_f32_dpp v201, v231, v55 row_newbcast:13 row_mask:0xf bank_mask:0xf
	v_fmac_f32_dpp v115, v228, v56 row_newbcast:14 row_mask:0xf bank_mask:0xf
	v_fmac_f32_dpp v201, v229, v57 row_newbcast:14 row_mask:0xf bank_mask:0xf
	v_fmac_f32_dpp v115, v230, v58 row_newbcast:14 row_mask:0xf bank_mask:0xf
	v_fmac_f32_dpp v201, v231, v59 row_newbcast:14 row_mask:0xf bank_mask:0xf
	v_fmac_f32_dpp v115, v228, v60 row_newbcast:15 row_mask:0xf bank_mask:0xf
	v_fmac_f32_dpp v201, v229, v61 row_newbcast:15 row_mask:0xf bank_mask:0xf
	v_fmac_f32_dpp v115, v230, v62 row_newbcast:15 row_mask:0xf bank_mask:0xf
	v_fmac_f32_dpp v201, v231, v63 row_newbcast:15 row_mask:0xf bank_mask:0xf
	v_add_f32_e32 v200, v115, v201
	s_waitcnt vmcnt(14)
	buffer_store_dword v200, v207, s[68:71], s79 offen
	s_add_u32 s79, s79, 0xfffff000
	buffer_load_dwordx4 v[96:99], v232, s[64:67], s72 offen
	buffer_load_dwordx4 v[100:103], v233, s[64:67], s72 offen
	buffer_load_dwordx4 v[104:107], v234, s[64:67], s72 offen
	buffer_load_dwordx4 v[108:111], v235, s[64:67], s72 offen
	buffer_load_dwordx2 v[112:113], v236, s[64:67], s76 offen
	buffer_load_ushort v114, v237, s[64:67], s76 offen
	buffer_load_dword v115, v207, s[68:71], s78 offen
	s_add_i32 s72, s72, 0xfffff000
	s_max_i32 s72, s72, 0
	s_add_i32 s76, s76, 0xfffff800
	s_max_i32 s76, s76, 0
	s_add_i32 s78, s78, 0xfffff000
	s_max_i32 s78, s78, 0
	v_pk_mul_f32 v[224:225], v[120:121], v[216:217]
	v_pk_mul_f32 v[226:227], v[122:123], v[218:219]
	v_pk_mul_f32 v[216:217], v[216:217], v[116:117]
	v_pk_mul_f32 v[218:219], v[218:219], v[118:119]
	v_pk_fma_f32 v[184:185], v[124:125], v[188:189], v[192:193]
	v_pk_fma_f32 v[186:187], v[126:127], v[190:191], v[194:195]
	v_pk_mul_f32 v[176:177], v[120:121], v[124:125]
	v_pk_mul_f32 v[178:179], v[122:123], v[126:127]
	v_rcp_f32_e32 v220, v216
	v_rcp_f32_e32 v221, v217
	v_rcp_f32_e32 v222, v218
	v_rcp_f32_e32 v223, v219
	v_lshlrev_b32_e32 v180, 16, v132
	v_and_b32_e32 v181, 0xffff0000, v132
	v_lshlrev_b32_e32 v182, 16, v133
	v_and_b32_e32 v183, 0xffff0000, v133
	v_pk_mul_f32 v[180:181], v[180:181], v[184:185]
	v_pk_mul_f32 v[182:183], v[182:183], v[186:187]
	v_pk_mul_f32 v[228:229], v[128:129], v[216:217]
	v_pk_mul_f32 v[230:231], v[130:131], v[218:219]
	v_pk_mul_f32 v[176:177], v[176:177], v[220:221]
	v_pk_mul_f32 v[178:179], v[178:179], v[222:223]
	v_pk_mul_f32 v[180:181], v[180:181], v[220:221]
	v_pk_mul_f32 v[182:183], v[182:183], v[222:223]
	v_lshlrev_b32_e32 v203, 16, v134
	ds_write2_b32 v208, v176, v177 offset0:0 offset1:16
	ds_write2_b32 v208, v178, v179 offset0:32 offset1:48
	ds_write2_b32 v208, v180, v181 offset0:64 offset1:80
	ds_write2_b32 v208, v182, v183 offset0:96 offset1:112
	ds_read_b128 v[64:67], v209 offset:0
	ds_read_b128 v[68:71], v209 offset:16
	ds_read_b128 v[72:75], v209 offset:32
	ds_read_b128 v[76:79], v209 offset:48
	ds_read_b128 v[80:83], v209 offset:256
	ds_read_b128 v[84:87], v209 offset:272
	ds_read_b128 v[88:91], v209 offset:288
	ds_read_b128 v[92:95], v209 offset:304
	v_mul_f32_dpp v196, v224, v0 row_newbcast:0 row_mask:0xf bank_mask:0xf
	v_mul_f32_dpp v197, v225, v1 row_newbcast:0 row_mask:0xf bank_mask:0xf
	v_mul_f32_dpp v198, v226, v2 row_newbcast:0 row_mask:0xf bank_mask:0xf
	v_mul_f32_dpp v199, v227, v3 row_newbcast:0 row_mask:0xf bank_mask:0xf
	v_fmac_f32_dpp v196, v224, v4 row_newbcast:1 row_mask:0xf bank_mask:0xf
	v_fmac_f32_dpp v197, v225, v5 row_newbcast:1 row_mask:0xf bank_mask:0xf
	v_fmac_f32_dpp v198, v226, v6 row_newbcast:1 row_mask:0xf bank_mask:0xf
	v_fmac_f32_dpp v199, v227, v7 row_newbcast:1 row_mask:0xf bank_mask:0xf
	v_fmac_f32_dpp v196, v224, v8 row_newbcast:2 row_mask:0xf bank_mask:0xf
	v_fmac_f32_dpp v197, v225, v9 row_newbcast:2 row_mask:0xf bank_mask:0xf
	v_fmac_f32_dpp v198, v226, v10 row_newbcast:2 row_mask:0xf bank_mask:0xf
	v_fmac_f32_dpp v199, v227, v11 row_newbcast:2 row_mask:0xf bank_mask:0xf
	v_fmac_f32_dpp v196, v224, v12 row_newbcast:3 row_mask:0xf bank_mask:0xf
	v_fmac_f32_dpp v197, v225, v13 row_newbcast:3 row_mask:0xf bank_mask:0xf
;     static __device__ __forceinline__ void dot(const float (&S)[64], const f32x4& a, float (&s)[4]) {
;         if constexpr (K == 0) {
;             asm volatile("v_mul_f32_dpp %0, %4, %8 row_newbcast:%16" DPPM "v_mul_f32_dpp %1, %5, %9 row_newbcast:%16" DPPM "v_mul_f32_dpp %2, %6, %10 row_newbcast:%16" DPPM "v_mul_f32_dpp %3, %7, %11 row_newbcast:%16" DPPM
;                          "v_fmac_f32_dpp %0, %4, %12 row_newbcast:%17" DPPM "v_fmac_f32_dpp %1, %5, %13 row_newbcast:%17" DPPM "v_fmac_f32_dpp %2, %6, %14 row_newbcast:%17" DPPM "v_fmac_f32_dpp %3, %7, %15 row_newbcast:%17" DPPM
;                          : "=&v"(s[0]), "=&v"(s[1]), "=&v"(s[2]), "=&v"(s[3])
;                          : "v"(a[0]), "v"(a[1]), "v"(a[2]), "v"(a[3]), "v"(S[K]), "v"(S[K + 1]), "v"(S[K + 2]), "v"(S[K + 3]), "v"(S[K + 4]), "v"(S[K + 5]), "v"(S[K + 6]), "v"(S[K + 7]), "n"(N0), "n"(N1));
;         } else
;         asm volatile("v_fmac_f32_dpp %0, %4, %8 row_newbcast:%16" DPPM "v_fmac_f32_dpp %1, %5, %9 row_newbcast:%16" DPPM "v_fmac_f32_dpp %2, %6, %10 row_newbcast:%16" DPPM "v_fmac_f32_dpp %3, %7, %11 row_newbcast:%16" DPPM
;                      "v_fmac_f32_dpp %0, %4, %12 row_newbcast:%17" DPPM "v_fmac_f32_dpp %1, %5, %13 row_newbcast:%17" DPPM "v_fmac_f32_dpp %2, %6, %14 row_newbcast:%17" DPPM "v_fmac_f32_dpp %3, %7, %15 row_newbcast:%17" DPPM
;                      : "+v"(s[0]), "+v"(s[1]), "+v"(s[2]), "+v"(s[3])
;                      : "v"(a[0]), "v"(a[1]), "v"(a[2]), "v"(a[3]), "v"(S[K]), "v"(S[K + 1]), "v"(S[K + 2]), "v"(S[K + 3]), "v"(S[K + 4]), "v"(S[K + 5]), "v"(S[K + 6]), "v"(S[K + 7]), "n"(N0), "n"(N1));
;         if constexpr (K + 8 < 64) ScanK<K + 8>::dot(S, a, s);
;     }
;     static __device__ __forceinline__ void upd(float (&S)[64], const In2& in, float sa, float vv, float& y0, float& y1) {
;         float t0, t1, t2, t3;
;         asm volatile("v_mul_f32_dpp %0, %10, %27 row_newbcast:%28" DPPM "v_mul_f32_dpp %1, %11, %27 row_newbcast:%28" DPPM "v_mul_f32_dpp %2, %12, %27 row_newbcast:%28" DPPM "v_mul_f32_dpp %3, %13, %27 row_newbcast:%28" DPPM
;                      "v_fmac_f32_dpp %0, %14, %6 row_newbcast:%28" DPPM "v_fmac_f32_dpp %1, %15, %7 row_newbcast:%28" DPPM "v_fmac_f32_dpp %2, %16, %8 row_newbcast:%28" DPPM "v_fmac_f32_dpp %3, %17, %9 row_newbcast:%28" DPPM
	v_fmac_f32_dpp v198, v226, v14 row_newbcast:3 row_mask:0xf bank_mask:0xf
	v_fmac_f32_dpp v199, v227, v15 row_newbcast:3 row_mask:0xf bank_mask:0xf
	v_fmac_f32_dpp v196, v224, v16 row_newbcast:4 row_mask:0xf bank_mask:0xf
	v_fmac_f32_dpp v197, v225, v17 row_newbcast:4 row_mask:0xf bank_mask:0xf
	v_fmac_f32_dpp v198, v226, v18 row_newbcast:4 row_mask:0xf bank_mask:0xf
	v_fmac_f32_dpp v199, v227, v19 row_newbcast:4 row_mask:0xf bank_mask:0xf
	v_fmac_f32_dpp v196, v224, v20 row_newbcast:5 row_mask:0xf bank_mask:0xf
	v_fmac_f32_dpp v197, v225, v21 row_newbcast:5 row_mask:0xf bank_mask:0xf
	v_fmac_f32_dpp v198, v226, v22 row_newbcast:5 row_mask:0xf bank_mask:0xf
	v_fmac_f32_dpp v199, v227, v23 row_newbcast:5 row_mask:0xf bank_mask:0xf
	v_fmac_f32_dpp v196, v224, v24 row_newbcast:6 row_mask:0xf bank_mask:0xf
	v_fmac_f32_dpp v197, v225, v25 row_newbcast:6 row_mask:0xf bank_mask:0xf
	v_fmac_f32_dpp v198, v226, v26 row_newbcast:6 row_mask:0xf bank_mask:0xf
	v_fmac_f32_dpp v199, v227, v27 row_newbcast:6 row_mask:0xf bank_mask:0xf
	v_fmac_f32_dpp v196, v224, v28 row_newbcast:7 row_mask:0xf bank_mask:0xf
	v_fmac_f32_dpp v197, v225, v29 row_newbcast:7 row_mask:0xf bank_mask:0xf
	v_fmac_f32_dpp v198, v226, v30 row_newbcast:7 row_mask:0xf bank_mask:0xf
	v_fmac_f32_dpp v199, v227, v31 row_newbcast:7 row_mask:0xf bank_mask:0xf
	v_fmac_f32_dpp v196, v224, v32 row_newbcast:8 row_mask:0xf bank_mask:0xf
	v_fmac_f32_dpp v197, v225, v33 row_newbcast:8 row_mask:0xf bank_mask:0xf
	v_fmac_f32_dpp v198, v226, v34 row_newbcast:8 row_mask:0xf bank_mask:0xf
	v_fmac_f32_dpp v199, v227, v35 row_newbcast:8 row_mask:0xf bank_mask:0xf
	v_fmac_f32_dpp v196, v224, v36 row_newbcast:9 row_mask:0xf bank_mask:0xf
	v_fmac_f32_dpp v197, v225, v37 row_newbcast:9 row_mask:0xf bank_mask:0xf
	v_fmac_f32_dpp v198, v226, v38 row_newbcast:9 row_mask:0xf bank_mask:0xf
	v_fmac_f32_dpp v199, v227, v39 row_newbcast:9 row_mask:0xf bank_mask:0xf
	v_fmac_f32_dpp v196, v224, v40 row_newbcast:10 row_mask:0xf bank_mask:0xf
	v_fmac_f32_dpp v197, v225, v41 row_newbcast:10 row_mask:0xf bank_mask:0xf
	v_fmac_f32_dpp v198, v226, v42 row_newbcast:10 row_mask:0xf bank_mask:0xf
	v_fmac_f32_dpp v199, v227, v43 row_newbcast:10 row_mask:0xf bank_mask:0xf
	v_fmac_f32_dpp v196, v224, v44 row_newbcast:11 row_mask:0xf bank_mask:0xf
	v_fmac_f32_dpp v197, v225, v45 row_newbcast:11 row_mask:0xf bank_mask:0xf
	v_fmac_f32_dpp v198, v226, v46 row_newbcast:11 row_mask:0xf bank_mask:0xf
	v_fmac_f32_dpp v199, v227, v47 row_newbcast:11 row_mask:0xf bank_mask:0xf
	v_fmac_f32_dpp v196, v224, v48 row_newbcast:12 row_mask:0xf bank_mask:0xf
	v_fmac_f32_dpp v197, v225, v49 row_newbcast:12 row_mask:0xf bank_mask:0xf
	v_fmac_f32_dpp v198, v226, v50 row_newbcast:12 row_mask:0xf bank_mask:0xf
	v_fmac_f32_dpp v199, v227, v51 row_newbcast:12 row_mask:0xf bank_mask:0xf
	v_fmac_f32_dpp v196, v224, v52 row_newbcast:13 row_mask:0xf bank_mask:0xf
	v_fmac_f32_dpp v197, v225, v53 row_newbcast:13 row_mask:0xf bank_mask:0xf
	v_fmac_f32_dpp v198, v226, v54 row_newbcast:13 row_mask:0xf bank_mask:0xf
	v_fmac_f32_dpp v199, v227, v55 row_newbcast:13 row_mask:0xf bank_mask:0xf
	v_fmac_f32_dpp v196, v224, v56 row_newbcast:14 row_mask:0xf bank_mask:0xf
	v_fmac_f32_dpp v197, v225, v57 row_newbcast:14 row_mask:0xf bank_mask:0xf
	v_fmac_f32_dpp v198, v226, v58 row_newbcast:14 row_mask:0xf bank_mask:0xf
	v_fmac_f32_dpp v199, v227, v59 row_newbcast:14 row_mask:0xf bank_mask:0xf
	v_fmac_f32_dpp v196, v224, v60 row_newbcast:15 row_mask:0xf bank_mask:0xf
	v_fmac_f32_dpp v197, v225, v61 row_newbcast:15 row_mask:0xf bank_mask:0xf
	v_fmac_f32_dpp v198, v226, v62 row_newbcast:15 row_mask:0xf bank_mask:0xf
	v_fmac_f32_dpp v199, v227, v63 row_newbcast:15 row_mask:0xf bank_mask:0xf
	v_add_f32_e32 v196, v196, v197
	v_add_f32_e32 v198, v198, v199
	v_sub_f32_e64 v202, -v196, v198
	s_waitcnt lgkmcnt(0)
	s_nop 1
	v_mfma_f32_4x4x1_16b_f32 v[0:3], v64, v202, v[0:3]
	v_mfma_f32_4x4x1_16b_f32 v[4:7], v65, v202, v[4:7]
	v_mfma_f32_4x4x1_16b_f32 v[8:11], v66, v202, v[8:11]
	v_mfma_f32_4x4x1_16b_f32 v[12:15], v67, v202, v[12:15]
	v_mfma_f32_4x4x1_16b_f32 v[16:19], v68, v202, v[16:19]
	v_mfma_f32_4x4x1_16b_f32 v[20:23], v69, v202, v[20:23]
	v_mfma_f32_4x4x1_16b_f32 v[24:27], v70, v202, v[24:27]
	v_mfma_f32_4x4x1_16b_f32 v[28:31], v71, v202, v[28:31]
	v_mfma_f32_4x4x1_16b_f32 v[32:35], v72, v202, v[32:35]
	v_mfma_f32_4x4x1_16b_f32 v[36:39], v73, v202, v[36:39]
	v_mfma_f32_4x4x1_16b_f32 v[40:43], v74, v202, v[40:43]
	v_mfma_f32_4x4x1_16b_f32 v[44:47], v75, v202, v[44:47]
	v_mfma_f32_4x4x1_16b_f32 v[48:51], v76, v202, v[48:51]
	v_mfma_f32_4x4x1_16b_f32 v[52:55], v77, v202, v[52:55]
	v_mfma_f32_4x4x1_16b_f32 v[56:59], v78, v202, v[56:59]
	v_mfma_f32_4x4x1_16b_f32 v[60:63], v79, v202, v[60:63]
	v_mfma_f32_4x4x1_16b_f32 v[0:3], v80, v203, v[0:3]
	v_mfma_f32_4x4x1_16b_f32 v[4:7], v81, v203, v[4:7]
	v_mfma_f32_4x4x1_16b_f32 v[8:11], v82, v203, v[8:11]
	v_mfma_f32_4x4x1_16b_f32 v[12:15], v83, v203, v[12:15]
	v_mfma_f32_4x4x1_16b_f32 v[16:19], v84, v203, v[16:19]
	v_mfma_f32_4x4x1_16b_f32 v[20:23], v85, v203, v[20:23]
	v_mfma_f32_4x4x1_16b_f32 v[24:27], v86, v203, v[24:27]
	v_mfma_f32_4x4x1_16b_f32 v[28:31], v87, v203, v[28:31]
	v_mfma_f32_4x4x1_16b_f32 v[32:35], v88, v203, v[32:35]
	v_mfma_f32_4x4x1_16b_f32 v[36:39], v89, v203, v[36:39]
	v_mfma_f32_4x4x1_16b_f32 v[40:43], v90, v203, v[40:43]
	v_mfma_f32_4x4x1_16b_f32 v[44:47], v91, v203, v[44:47]
	v_mfma_f32_4x4x1_16b_f32 v[48:51], v92, v203, v[48:51]
	v_mfma_f32_4x4x1_16b_f32 v[52:55], v93, v203, v[52:55]
	v_mfma_f32_4x4x1_16b_f32 v[56:59], v94, v203, v[56:59]
	v_mfma_f32_4x4x1_16b_f32 v[60:63], v95, v203, v[60:63]
; #define SB __builtin_amdgcn_sched_barrier(0)
; #define ST2(set, s) { DERIVE_BK(set); float sd[4]; ScanK<0>::dot(S, set.a, sd); float y0 = set.yo, y1 = 0.f; ScanK<0>::upd(S, set, -((sd[0] + sd[1]) + (sd[2] + sd[3])), __uint_as_float(set.v << 16), y0, y1); __builtin_amdgcn_raw_buffer_store_b32(__float_as_uint(y0 + y1), rY, lo4b, ob4 + (unsigned)((int)(s) * (int)stp * 4), 0); }
;     static __device__ __forceinline__ void upd(float (&S)[64], const In2& in, float sa, float vv, float& y0, float& y1) {
;         float t0, t1, t2, t3;
;         asm volatile("v_mul_f32_dpp %0, %10, %27 row_newbcast:%28" DPPM "v_mul_f32_dpp %1, %11, %27 row_newbcast:%28" DPPM "v_mul_f32_dpp %2, %12, %27 row_newbcast:%28" DPPM "v_mul_f32_dpp %3, %13, %27 row_newbcast:%28" DPPM
;                      "v_fmac_f32_dpp %0, %14, %6 row_newbcast:%28" DPPM "v_fmac_f32_dpp %1, %15, %7 row_newbcast:%28" DPPM "v_fmac_f32_dpp %2, %16, %8 row_newbcast:%28" DPPM "v_fmac_f32_dpp %3, %17, %9 row_newbcast:%28" DPPM
;                      "v_fmac_f32_dpp %0, %18, %26 row_newbcast:%28" DPPM "v_fmac_f32_dpp %1, %19, %26 row_newbcast:%28" DPPM "v_fmac_f32_dpp %2, %20, %26 row_newbcast:%28" DPPM "v_fmac_f32_dpp %3, %21, %26 row_newbcast:%28" DPPM
;                      "v_fmac_f32_dpp %4, %22, %0 row_newbcast:%28" DPPM "v_fmac_f32_dpp %5, %23, %1 row_newbcast:%28" DPPM "v_fmac_f32_dpp %4, %24, %2 row_newbcast:%28" DPPM "v_fmac_f32_dpp %5, %25, %3 row_newbcast:%28" DPPM
;                      : "=&v"(t0), "=&v"(t1), "=&v"(t2), "=&v"(t3), "+v"(y0), "+v"(y1)
;                      : "v"(S[K]), "v"(S[K + 1]), "v"(S[K + 2]), "v"(S[K + 3]), "v"(in.kd[0]), "v"(in.kd[1]), "v"(in.kd[2]), "v"(in.kd[3]), "v"(in.w[0]), "v"(in.w[1]), "v"(in.w[2]), "v"(in.w[3]),
;                        "v"(in.b[0]), "v"(in.b[1]), "v"(in.b[2]), "v"(in.b[3]), "v"(in.r[0]), "v"(in.r[1]), "v"(in.r[2]), "v"(in.r[3]), "v"(sa), "v"(vv), "n"(N0));
;         S[K] = t0; S[K + 1] = t1; S[K + 2] = t2; S[K + 3] = t3;
;         if constexpr (K + 4 < 64) ScanK<K + 4>::upd(S, in, sa, vv, y0, y1);
; __device__ __forceinline__ void scan_pass2(const Params& p, int d) {
;     ...
;         In2 i0, i1; LD2(i0, 0);
; #pragma unroll 1
;         for (int s = 0; s < LC; s += 2) { TOUCH2(i0); SB; LD2(i1, s + 1); SB; ST2(i0, s); TOUCH2(i1); SB; LD2(i0, s + 2); SB; ST2(i1, s + 1); }
	v_fmac_f32_dpp v135, v228, v0 row_newbcast:0 row_mask:0xf bank_mask:0xf
	v_mul_f32_dpp v201, v229, v1 row_newbcast:0 row_mask:0xf bank_mask:0xf
	v_fmac_f32_dpp v135, v230, v2 row_newbcast:0 row_mask:0xf bank_mask:0xf
	v_fmac_f32_dpp v201, v231, v3 row_newbcast:0 row_mask:0xf bank_mask:0xf
	v_fmac_f32_dpp v135, v228, v4 row_newbcast:1 row_mask:0xf bank_mask:0xf
	v_fmac_f32_dpp v201, v229, v5 row_newbcast:1 row_mask:0xf bank_mask:0xf
	v_fmac_f32_dpp v135, v230, v6 row_newbcast:1 row_mask:0xf bank_mask:0xf
	v_fmac_f32_dpp v201, v231, v7 row_newbcast:1 row_mask:0xf bank_mask:0xf
	v_fmac_f32_dpp v135, v228, v8 row_newbcast:2 row_mask:0xf bank_mask:0xf
	v_fmac_f32_dpp v201, v229, v9 row_newbcast:2 row_mask:0xf bank_mask:0xf
	v_fmac_f32_dpp v135, v230, v10 row_newbcast:2 row_mask:0xf bank_mask:0xf
	v_fmac_f32_dpp v201, v231, v11 row_newbcast:2 row_mask:0xf bank_mask:0xf
	v_fmac_f32_dpp v135, v228, v12 row_newbcast:3 row_mask:0xf bank_mask:0xf
	v_fmac_f32_dpp v201, v229, v13 row_newbcast:3 row_mask:0xf bank_mask:0xf
	v_fmac_f32_dpp v135, v230, v14 row_newbcast:3 row_mask:0xf bank_mask:0xf
	v_fmac_f32_dpp v201, v231, v15 row_newbcast:3 row_mask:0xf bank_mask:0xf
	v_fmac_f32_dpp v135, v228, v16 row_newbcast:4 row_mask:0xf bank_mask:0xf
	v_fmac_f32_dpp v201, v229, v17 row_newbcast:4 row_mask:0xf bank_mask:0xf
	v_fmac_f32_dpp v135, v230, v18 row_newbcast:4 row_mask:0xf bank_mask:0xf
	v_fmac_f32_dpp v201, v231, v19 row_newbcast:4 row_mask:0xf bank_mask:0xf
	v_fmac_f32_dpp v135, v228, v20 row_newbcast:5 row_mask:0xf bank_mask:0xf
	v_fmac_f32_dpp v201, v229, v21 row_newbcast:5 row_mask:0xf bank_mask:0xf
	v_fmac_f32_dpp v135, v230, v22 row_newbcast:5 row_mask:0xf bank_mask:0xf
	v_fmac_f32_dpp v201, v231, v23 row_newbcast:5 row_mask:0xf bank_mask:0xf
	v_fmac_f32_dpp v135, v228, v24 row_newbcast:6 row_mask:0xf bank_mask:0xf
	v_fmac_f32_dpp v201, v229, v25 row_newbcast:6 row_mask:0xf bank_mask:0xf
	v_fmac_f32_dpp v135, v230, v26 row_newbcast:6 row_mask:0xf bank_mask:0xf
	v_fmac_f32_dpp v201, v231, v27 row_newbcast:6 row_mask:0xf bank_mask:0xf
	v_fmac_f32_dpp v135, v228, v28 row_newbcast:7 row_mask:0xf bank_mask:0xf
	v_fmac_f32_dpp v201, v229, v29 row_newbcast:7 row_mask:0xf bank_mask:0xf
	v_fmac_f32_dpp v135, v230, v30 row_newbcast:7 row_mask:0xf bank_mask:0xf
	v_fmac_f32_dpp v201, v231, v31 row_newbcast:7 row_mask:0xf bank_mask:0xf
	v_fmac_f32_dpp v135, v228, v32 row_newbcast:8 row_mask:0xf bank_mask:0xf
	v_fmac_f32_dpp v201, v229, v33 row_newbcast:8 row_mask:0xf bank_mask:0xf
	v_fmac_f32_dpp v135, v230, v34 row_newbcast:8 row_mask:0xf bank_mask:0xf
	v_fmac_f32_dpp v201, v231, v35 row_newbcast:8 row_mask:0xf bank_mask:0xf
	v_fmac_f32_dpp v135, v228, v36 row_newbcast:9 row_mask:0xf bank_mask:0xf
	v_fmac_f32_dpp v201, v229, v37 row_newbcast:9 row_mask:0xf bank_mask:0xf
	v_fmac_f32_dpp v135, v230, v38 row_newbcast:9 row_mask:0xf bank_mask:0xf
	v_fmac_f32_dpp v201, v231, v39 row_newbcast:9 row_mask:0xf bank_mask:0xf
	v_fmac_f32_dpp v135, v228, v40 row_newbcast:10 row_mask:0xf bank_mask:0xf
	v_fmac_f32_dpp v201, v229, v41 row_newbcast:10 row_mask:0xf bank_mask:0xf
	v_fmac_f32_dpp v135, v230, v42 row_newbcast:10 row_mask:0xf bank_mask:0xf
	v_fmac_f32_dpp v201, v231, v43 row_newbcast:10 row_mask:0xf bank_mask:0xf
	v_fmac_f32_dpp v135, v228, v44 row_newbcast:11 row_mask:0xf bank_mask:0xf
	v_fmac_f32_dpp v201, v229, v45 row_newbcast:11 row_mask:0xf bank_mask:0xf
	v_fmac_f32_dpp v135, v230, v46 row_newbcast:11 row_mask:0xf bank_mask:0xf
	v_fmac_f32_dpp v201, v231, v47 row_newbcast:11 row_mask:0xf bank_mask:0xf
	v_fmac_f32_dpp v135, v228, v48 row_newbcast:12 row_mask:0xf bank_mask:0xf
	v_fmac_f32_dpp v201, v229, v49 row_newbcast:12 row_mask:0xf bank_mask:0xf
	v_fmac_f32_dpp v135, v230, v50 row_newbcast:12 row_mask:0xf bank_mask:0xf
	v_fmac_f32_dpp v201, v231, v51 row_newbcast:12 row_mask:0xf bank_mask:0xf
	v_fmac_f32_dpp v135, v228, v52 row_newbcast:13 row_mask:0xf bank_mask:0xf
	v_fmac_f32_dpp v201, v229, v53 row_newbcast:13 row_mask:0xf bank_mask:0xf
	v_fmac_f32_dpp v135, v230, v54 row_newbcast:13 row_mask:0xf bank_mask:0xf
	v_fmac_f32_dpp v201, v231, v55 row_newbcast:13 row_mask:0xf bank_mask:0xf
	v_fmac_f32_dpp v135, v228, v56 row_newbcast:14 row_mask:0xf bank_mask:0xf
	v_fmac_f32_dpp v201, v229, v57 row_newbcast:14 row_mask:0xf bank_mask:0xf
	v_fmac_f32_dpp v135, v230, v58 row_newbcast:14 row_mask:0xf bank_mask:0xf
	v_fmac_f32_dpp v201, v231, v59 row_newbcast:14 row_mask:0xf bank_mask:0xf
	v_fmac_f32_dpp v135, v228, v60 row_newbcast:15 row_mask:0xf bank_mask:0xf
	v_fmac_f32_dpp v201, v229, v61 row_newbcast:15 row_mask:0xf bank_mask:0xf
	v_fmac_f32_dpp v135, v230, v62 row_newbcast:15 row_mask:0xf bank_mask:0xf
	v_fmac_f32_dpp v201, v231, v63 row_newbcast:15 row_mask:0xf bank_mask:0xf
	v_add_f32_e32 v200, v135, v201
	s_waitcnt vmcnt(14)
; #define SB __builtin_amdgcn_sched_barrier(0)
;     static __device__ __forceinline__ void dot(const float (&S)[64], const f32x4& a, float (&s)[4]) {
;         if constexpr (K == 0) {
;             asm volatile("v_mul_f32_dpp %0, %4, %8 row_newbcast:%16" DPPM "v_mul_f32_dpp %1, %5, %9 row_newbcast:%16" DPPM "v_mul_f32_dpp %2, %6, %10 row_newbcast:%16" DPPM "v_mul_f32_dpp %3, %7, %11 row_newbcast:%16" DPPM
;                          "v_fmac_f32_dpp %0, %4, %12 row_newbcast:%17" DPPM "v_fmac_f32_dpp %1, %5, %13 row_newbcast:%17" DPPM "v_fmac_f32_dpp %2, %6, %14 row_newbcast:%17" DPPM "v_fmac_f32_dpp %3, %7, %15 row_newbcast:%17" DPPM
;                          : "=&v"(s[0]), "=&v"(s[1]), "=&v"(s[2]), "=&v"(s[3])
;                          : "v"(a[0]), "v"(a[1]), "v"(a[2]), "v"(a[3]), "v"(S[K]), "v"(S[K + 1]), "v"(S[K + 2]), "v"(S[K + 3]), "v"(S[K + 4]), "v"(S[K + 5]), "v"(S[K + 6]), "v"(S[K + 7]), "n"(N0), "n"(N1));
;         } else
;         asm volatile("v_fmac_f32_dpp %0, %4, %8 row_newbcast:%16" DPPM "v_fmac_f32_dpp %1, %5, %9 row_newbcast:%16" DPPM "v_fmac_f32_dpp %2, %6, %10 row_newbcast:%16" DPPM "v_fmac_f32_dpp %3, %7, %11 row_newbcast:%16" DPPM
;                      "v_fmac_f32_dpp %0, %4, %12 row_newbcast:%17" DPPM "v_fmac_f32_dpp %1, %5, %13 row_newbcast:%17" DPPM "v_fmac_f32_dpp %2, %6, %14 row_newbcast:%17" DPPM "v_fmac_f32_dpp %3, %7, %15 row_newbcast:%17" DPPM
;                      : "+v"(s[0]), "+v"(s[1]), "+v"(s[2]), "+v"(s[3])
;                      : "v"(a[0]), "v"(a[1]), "v"(a[2]), "v"(a[3]), "v"(S[K]), "v"(S[K + 1]), "v"(S[K + 2]), "v"(S[K + 3]), "v"(S[K + 4]), "v"(S[K + 5]), "v"(S[K + 6]), "v"(S[K + 7]), "n"(N0), "n"(N1));
;         if constexpr (K + 8 < 64) ScanK<K + 8>::dot(S, a, s);
;     }
;     static __device__ __forceinline__ void upd(float (&S)[64], const In2& in, float sa, float vv, float& y0, float& y1) {
;         float t0, t1, t2, t3;
;         asm volatile("v_mul_f32_dpp %0, %10, %27 row_newbcast:%28" DPPM "v_mul_f32_dpp %1, %11, %27 row_newbcast:%28" DPPM "v_mul_f32_dpp %2, %12, %27 row_newbcast:%28" DPPM "v_mul_f32_dpp %3, %13, %27 row_newbcast:%28" DPPM
; __device__ __forceinline__ void scan_pass2(const Params& p, int d) {
;     ...
;         In2 i0, i1; LD2(i0, 0);
; #pragma unroll 1
;         for (int s = 0; s < LC; s += 2) { TOUCH2(i0); SB; LD2(i1, s + 1); SB; ST2(i0, s); TOUCH2(i1); SB; LD2(i0, s + 2); SB; ST2(i1, s + 1); }
	buffer_store_dword v200, v207, s[68:71], s79 offen
	s_add_u32 s79, s79, 0xfffff000
	buffer_load_dwordx4 v[116:119], v232, s[64:67], s72 offen
	buffer_load_dwordx4 v[120:123], v233, s[64:67], s72 offen
	buffer_load_dwordx4 v[124:127], v234, s[64:67], s72 offen
	buffer_load_dwordx4 v[128:131], v235, s[64:67], s72 offen
	buffer_load_dwordx2 v[132:133], v236, s[64:67], s76 offen
	buffer_load_ushort v134, v237, s[64:67], s76 offen
	buffer_load_dword v135, v207, s[68:71], s78 offen
	s_add_i32 s72, s72, 0xfffff000
	s_max_i32 s72, s72, 0
	s_add_i32 s76, s76, 0xfffff800
	s_max_i32 s76, s76, 0
	s_add_i32 s78, s78, 0xfffff000
	s_max_i32 s78, s78, 0
	v_pk_mul_f32 v[224:225], v[140:141], v[216:217]
	v_pk_mul_f32 v[226:227], v[142:143], v[218:219]
	v_pk_mul_f32 v[216:217], v[216:217], v[136:137]
	v_pk_mul_f32 v[218:219], v[218:219], v[138:139]
	v_pk_fma_f32 v[184:185], v[144:145], v[188:189], v[192:193]
	v_pk_fma_f32 v[186:187], v[146:147], v[190:191], v[194:195]
	v_pk_mul_f32 v[176:177], v[140:141], v[144:145]
	v_pk_mul_f32 v[178:179], v[142:143], v[146:147]
	v_rcp_f32_e32 v220, v216
	v_rcp_f32_e32 v221, v217
	v_rcp_f32_e32 v222, v218
	v_rcp_f32_e32 v223, v219
	v_lshlrev_b32_e32 v180, 16, v152
	v_and_b32_e32 v181, 0xffff0000, v152
	v_lshlrev_b32_e32 v182, 16, v153
	v_and_b32_e32 v183, 0xffff0000, v153
	v_pk_mul_f32 v[180:181], v[180:181], v[184:185]
	v_pk_mul_f32 v[182:183], v[182:183], v[186:187]
	v_pk_mul_f32 v[228:229], v[148:149], v[216:217]
	v_pk_mul_f32 v[230:231], v[150:151], v[218:219]
	v_pk_mul_f32 v[176:177], v[176:177], v[220:221]
	v_pk_mul_f32 v[178:179], v[178:179], v[222:223]
	v_pk_mul_f32 v[180:181], v[180:181], v[220:221]
	v_pk_mul_f32 v[182:183], v[182:183], v[222:223]
	v_lshlrev_b32_e32 v203, 16, v154
	ds_write2_b32 v208, v176, v177 offset0:0 offset1:16
	ds_write2_b32 v208, v178, v179 offset0:32 offset1:48
	ds_write2_b32 v208, v180, v181 offset0:64 offset1:80
	ds_write2_b32 v208, v182, v183 offset0:96 offset1:112
	ds_read_b128 v[64:67], v209 offset:0
	ds_read_b128 v[68:71], v209 offset:16
	ds_read_b128 v[72:75], v209 offset:32
	ds_read_b128 v[76:79], v209 offset:48
	ds_read_b128 v[80:83], v209 offset:256
	ds_read_b128 v[84:87], v209 offset:272
	ds_read_b128 v[88:91], v209 offset:288
	ds_read_b128 v[92:95], v209 offset:304
	v_mul_f32_dpp v196, v224, v0 row_newbcast:0 row_mask:0xf bank_mask:0xf
	v_mul_f32_dpp v197, v225, v1 row_newbcast:0 row_mask:0xf bank_mask:0xf
	v_mul_f32_dpp v198, v226, v2 row_newbcast:0 row_mask:0xf bank_mask:0xf
	v_mul_f32_dpp v199, v227, v3 row_newbcast:0 row_mask:0xf bank_mask:0xf
	v_fmac_f32_dpp v196, v224, v4 row_newbcast:1 row_mask:0xf bank_mask:0xf
	v_fmac_f32_dpp v197, v225, v5 row_newbcast:1 row_mask:0xf bank_mask:0xf
	v_fmac_f32_dpp v198, v226, v6 row_newbcast:1 row_mask:0xf bank_mask:0xf
	v_fmac_f32_dpp v199, v227, v7 row_newbcast:1 row_mask:0xf bank_mask:0xf
	v_fmac_f32_dpp v196, v224, v8 row_newbcast:2 row_mask:0xf bank_mask:0xf
	v_fmac_f32_dpp v197, v225, v9 row_newbcast:2 row_mask:0xf bank_mask:0xf
	v_fmac_f32_dpp v198, v226, v10 row_newbcast:2 row_mask:0xf bank_mask:0xf
	v_fmac_f32_dpp v199, v227, v11 row_newbcast:2 row_mask:0xf bank_mask:0xf
	v_fmac_f32_dpp v196, v224, v12 row_newbcast:3 row_mask:0xf bank_mask:0xf
	v_fmac_f32_dpp v197, v225, v13 row_newbcast:3 row_mask:0xf bank_mask:0xf
	v_fmac_f32_dpp v198, v226, v14 row_newbcast:3 row_mask:0xf bank_mask:0xf
	v_fmac_f32_dpp v199, v227, v15 row_newbcast:3 row_mask:0xf bank_mask:0xf
	v_fmac_f32_dpp v196, v224, v16 row_newbcast:4 row_mask:0xf bank_mask:0xf
	v_fmac_f32_dpp v197, v225, v17 row_newbcast:4 row_mask:0xf bank_mask:0xf
	v_fmac_f32_dpp v198, v226, v18 row_newbcast:4 row_mask:0xf bank_mask:0xf
	v_fmac_f32_dpp v199, v227, v19 row_newbcast:4 row_mask:0xf bank_mask:0xf
	v_fmac_f32_dpp v196, v224, v20 row_newbcast:5 row_mask:0xf bank_mask:0xf
	v_fmac_f32_dpp v197, v225, v21 row_newbcast:5 row_mask:0xf bank_mask:0xf
	v_fmac_f32_dpp v198, v226, v22 row_newbcast:5 row_mask:0xf bank_mask:0xf
	v_fmac_f32_dpp v199, v227, v23 row_newbcast:5 row_mask:0xf bank_mask:0xf
	v_fmac_f32_dpp v196, v224, v24 row_newbcast:6 row_mask:0xf bank_mask:0xf
	v_fmac_f32_dpp v197, v225, v25 row_newbcast:6 row_mask:0xf bank_mask:0xf
	v_fmac_f32_dpp v198, v226, v26 row_newbcast:6 row_mask:0xf bank_mask:0xf
	v_fmac_f32_dpp v199, v227, v27 row_newbcast:6 row_mask:0xf bank_mask:0xf
	v_fmac_f32_dpp v196, v224, v28 row_newbcast:7 row_mask:0xf bank_mask:0xf
	v_fmac_f32_dpp v197, v225, v29 row_newbcast:7 row_mask:0xf bank_mask:0xf
	v_fmac_f32_dpp v198, v226, v30 row_newbcast:7 row_mask:0xf bank_mask:0xf
	v_fmac_f32_dpp v199, v227, v31 row_newbcast:7 row_mask:0xf bank_mask:0xf
	v_fmac_f32_dpp v196, v224, v32 row_newbcast:8 row_mask:0xf bank_mask:0xf
	v_fmac_f32_dpp v197, v225, v33 row_newbcast:8 row_mask:0xf bank_mask:0xf
	v_fmac_f32_dpp v198, v226, v34 row_newbcast:8 row_mask:0xf bank_mask:0xf
	v_fmac_f32_dpp v199, v227, v35 row_newbcast:8 row_mask:0xf bank_mask:0xf
	v_fmac_f32_dpp v196, v224, v36 row_newbcast:9 row_mask:0xf bank_mask:0xf
	v_fmac_f32_dpp v197, v225, v37 row_newbcast:9 row_mask:0xf bank_mask:0xf
	v_fmac_f32_dpp v198, v226, v38 row_newbcast:9 row_mask:0xf bank_mask:0xf
	v_fmac_f32_dpp v199, v227, v39 row_newbcast:9 row_mask:0xf bank_mask:0xf
	v_fmac_f32_dpp v196, v224, v40 row_newbcast:10 row_mask:0xf bank_mask:0xf
	v_fmac_f32_dpp v197, v225, v41 row_newbcast:10 row_mask:0xf bank_mask:0xf
	v_fmac_f32_dpp v198, v226, v42 row_newbcast:10 row_mask:0xf bank_mask:0xf
	v_fmac_f32_dpp v199, v227, v43 row_newbcast:10 row_mask:0xf bank_mask:0xf
	v_fmac_f32_dpp v196, v224, v44 row_newbcast:11 row_mask:0xf bank_mask:0xf
	v_fmac_f32_dpp v197, v225, v45 row_newbcast:11 row_mask:0xf bank_mask:0xf
;     static __device__ __forceinline__ void dot(const float (&S)[64], const f32x4& a, float (&s)[4]) {
;         if constexpr (K == 0) {
;             asm volatile("v_mul_f32_dpp %0, %4, %8 row_newbcast:%16" DPPM "v_mul_f32_dpp %1, %5, %9 row_newbcast:%16" DPPM "v_mul_f32_dpp %2, %6, %10 row_newbcast:%16" DPPM "v_mul_f32_dpp %3, %7, %11 row_newbcast:%16" DPPM
;                          "v_fmac_f32_dpp %0, %4, %12 row_newbcast:%17" DPPM "v_fmac_f32_dpp %1, %5, %13 row_newbcast:%17" DPPM "v_fmac_f32_dpp %2, %6, %14 row_newbcast:%17" DPPM "v_fmac_f32_dpp %3, %7, %15 row_newbcast:%17" DPPM
;                          : "=&v"(s[0]), "=&v"(s[1]), "=&v"(s[2]), "=&v"(s[3])
;                          : "v"(a[0]), "v"(a[1]), "v"(a[2]), "v"(a[3]), "v"(S[K]), "v"(S[K + 1]), "v"(S[K + 2]), "v"(S[K + 3]), "v"(S[K + 4]), "v"(S[K + 5]), "v"(S[K + 6]), "v"(S[K + 7]), "n"(N0), "n"(N1));
;         } else
;         asm volatile("v_fmac_f32_dpp %0, %4, %8 row_newbcast:%16" DPPM "v_fmac_f32_dpp %1, %5, %9 row_newbcast:%16" DPPM "v_fmac_f32_dpp %2, %6, %10 row_newbcast:%16" DPPM "v_fmac_f32_dpp %3, %7, %11 row_newbcast:%16" DPPM
;                      "v_fmac_f32_dpp %0, %4, %12 row_newbcast:%17" DPPM "v_fmac_f32_dpp %1, %5, %13 row_newbcast:%17" DPPM "v_fmac_f32_dpp %2, %6, %14 row_newbcast:%17" DPPM "v_fmac_f32_dpp %3, %7, %15 row_newbcast:%17" DPPM
;                      : "+v"(s[0]), "+v"(s[1]), "+v"(s[2]), "+v"(s[3])
;                      : "v"(a[0]), "v"(a[1]), "v"(a[2]), "v"(a[3]), "v"(S[K]), "v"(S[K + 1]), "v"(S[K + 2]), "v"(S[K + 3]), "v"(S[K + 4]), "v"(S[K + 5]), "v"(S[K + 6]), "v"(S[K + 7]), "n"(N0), "n"(N1));
;         if constexpr (K + 8 < 64) ScanK<K + 8>::dot(S, a, s);
;     }
;     static __device__ __forceinline__ void upd(float (&S)[64], const In2& in, float sa, float vv, float& y0, float& y1) {
;         float t0, t1, t2, t3;
;         asm volatile("v_mul_f32_dpp %0, %10, %27 row_newbcast:%28" DPPM "v_mul_f32_dpp %1, %11, %27 row_newbcast:%28" DPPM "v_mul_f32_dpp %2, %12, %27 row_newbcast:%28" DPPM "v_mul_f32_dpp %3, %13, %27 row_newbcast:%28" DPPM
;                      "v_fmac_f32_dpp %0, %14, %6 row_newbcast:%28" DPPM "v_fmac_f32_dpp %1, %15, %7 row_newbcast:%28" DPPM "v_fmac_f32_dpp %2, %16, %8 row_newbcast:%28" DPPM "v_fmac_f32_dpp %3, %17, %9 row_newbcast:%28" DPPM
	v_fmac_f32_dpp v198, v226, v46 row_newbcast:11 row_mask:0xf bank_mask:0xf
	v_fmac_f32_dpp v199, v227, v47 row_newbcast:11 row_mask:0xf bank_mask:0xf
	v_fmac_f32_dpp v196, v224, v48 row_newbcast:12 row_mask:0xf bank_mask:0xf
	v_fmac_f32_dpp v197, v225, v49 row_newbcast:12 row_mask:0xf bank_mask:0xf
	v_fmac_f32_dpp v198, v226, v50 row_newbcast:12 row_mask:0xf bank_mask:0xf
	v_fmac_f32_dpp v199, v227, v51 row_newbcast:12 row_mask:0xf bank_mask:0xf
	v_fmac_f32_dpp v196, v224, v52 row_newbcast:13 row_mask:0xf bank_mask:0xf
	v_fmac_f32_dpp v197, v225, v53 row_newbcast:13 row_mask:0xf bank_mask:0xf
	v_fmac_f32_dpp v198, v226, v54 row_newbcast:13 row_mask:0xf bank_mask:0xf
	v_fmac_f32_dpp v199, v227, v55 row_newbcast:13 row_mask:0xf bank_mask:0xf
	v_fmac_f32_dpp v196, v224, v56 row_newbcast:14 row_mask:0xf bank_mask:0xf
	v_fmac_f32_dpp v197, v225, v57 row_newbcast:14 row_mask:0xf bank_mask:0xf
	v_fmac_f32_dpp v198, v226, v58 row_newbcast:14 row_mask:0xf bank_mask:0xf
	v_fmac_f32_dpp v199, v227, v59 row_newbcast:14 row_mask:0xf bank_mask:0xf
	v_fmac_f32_dpp v196, v224, v60 row_newbcast:15 row_mask:0xf bank_mask:0xf
	v_fmac_f32_dpp v197, v225, v61 row_newbcast:15 row_mask:0xf bank_mask:0xf
	v_fmac_f32_dpp v198, v226, v62 row_newbcast:15 row_mask:0xf bank_mask:0xf
	v_fmac_f32_dpp v199, v227, v63 row_newbcast:15 row_mask:0xf bank_mask:0xf
	v_add_f32_e32 v196, v196, v197
	v_add_f32_e32 v198, v198, v199
	v_sub_f32_e64 v202, -v196, v198
	s_waitcnt lgkmcnt(0)
	s_nop 1
	v_mfma_f32_4x4x1_16b_f32 v[0:3], v64, v202, v[0:3]
	v_mfma_f32_4x4x1_16b_f32 v[4:7], v65, v202, v[4:7]
	v_mfma_f32_4x4x1_16b_f32 v[8:11], v66, v202, v[8:11]
	v_mfma_f32_4x4x1_16b_f32 v[12:15], v67, v202, v[12:15]
	v_mfma_f32_4x4x1_16b_f32 v[16:19], v68, v202, v[16:19]
	v_mfma_f32_4x4x1_16b_f32 v[20:23], v69, v202, v[20:23]
	v_mfma_f32_4x4x1_16b_f32 v[24:27], v70, v202, v[24:27]
	v_mfma_f32_4x4x1_16b_f32 v[28:31], v71, v202, v[28:31]
	v_mfma_f32_4x4x1_16b_f32 v[32:35], v72, v202, v[32:35]
	v_mfma_f32_4x4x1_16b_f32 v[36:39], v73, v202, v[36:39]
	v_mfma_f32_4x4x1_16b_f32 v[40:43], v74, v202, v[40:43]
	v_mfma_f32_4x4x1_16b_f32 v[44:47], v75, v202, v[44:47]
	v_mfma_f32_4x4x1_16b_f32 v[48:51], v76, v202, v[48:51]
	v_mfma_f32_4x4x1_16b_f32 v[52:55], v77, v202, v[52:55]
	v_mfma_f32_4x4x1_16b_f32 v[56:59], v78, v202, v[56:59]
	v_mfma_f32_4x4x1_16b_f32 v[60:63], v79, v202, v[60:63]
	v_mfma_f32_4x4x1_16b_f32 v[0:3], v80, v203, v[0:3]
	v_mfma_f32_4x4x1_16b_f32 v[4:7], v81, v203, v[4:7]
	v_mfma_f32_4x4x1_16b_f32 v[8:11], v82, v203, v[8:11]
	v_mfma_f32_4x4x1_16b_f32 v[12:15], v83, v203, v[12:15]
	v_mfma_f32_4x4x1_16b_f32 v[16:19], v84, v203, v[16:19]
	v_mfma_f32_4x4x1_16b_f32 v[20:23], v85, v203, v[20:23]
	v_mfma_f32_4x4x1_16b_f32 v[24:27], v86, v203, v[24:27]
	v_mfma_f32_4x4x1_16b_f32 v[28:31], v87, v203, v[28:31]
	v_mfma_f32_4x4x1_16b_f32 v[32:35], v88, v203, v[32:35]
	v_mfma_f32_4x4x1_16b_f32 v[36:39], v89, v203, v[36:39]
	v_mfma_f32_4x4x1_16b_f32 v[40:43], v90, v203, v[40:43]
	v_mfma_f32_4x4x1_16b_f32 v[44:47], v91, v203, v[44:47]
	v_mfma_f32_4x4x1_16b_f32 v[48:51], v92, v203, v[48:51]
	v_mfma_f32_4x4x1_16b_f32 v[52:55], v93, v203, v[52:55]
	v_mfma_f32_4x4x1_16b_f32 v[56:59], v94, v203, v[56:59]
	v_mfma_f32_4x4x1_16b_f32 v[60:63], v95, v203, v[60:63]
	v_fmac_f32_dpp v155, v228, v0 row_newbcast:0 row_mask:0xf bank_mask:0xf
	v_mul_f32_dpp v201, v229, v1 row_newbcast:0 row_mask:0xf bank_mask:0xf
	v_fmac_f32_dpp v155, v230, v2 row_newbcast:0 row_mask:0xf bank_mask:0xf
	v_fmac_f32_dpp v201, v231, v3 row_newbcast:0 row_mask:0xf bank_mask:0xf
	v_fmac_f32_dpp v155, v228, v4 row_newbcast:1 row_mask:0xf bank_mask:0xf
	v_fmac_f32_dpp v201, v229, v5 row_newbcast:1 row_mask:0xf bank_mask:0xf
	v_fmac_f32_dpp v155, v230, v6 row_newbcast:1 row_mask:0xf bank_mask:0xf
	v_fmac_f32_dpp v201, v231, v7 row_newbcast:1 row_mask:0xf bank_mask:0xf
	v_fmac_f32_dpp v155, v228, v8 row_newbcast:2 row_mask:0xf bank_mask:0xf
	v_fmac_f32_dpp v201, v229, v9 row_newbcast:2 row_mask:0xf bank_mask:0xf
	v_fmac_f32_dpp v155, v230, v10 row_newbcast:2 row_mask:0xf bank_mask:0xf
	v_fmac_f32_dpp v201, v231, v11 row_newbcast:2 row_mask:0xf bank_mask:0xf
	v_fmac_f32_dpp v155, v228, v12 row_newbcast:3 row_mask:0xf bank_mask:0xf
	v_fmac_f32_dpp v201, v229, v13 row_newbcast:3 row_mask:0xf bank_mask:0xf
	v_fmac_f32_dpp v155, v230, v14 row_newbcast:3 row_mask:0xf bank_mask:0xf
	v_fmac_f32_dpp v201, v231, v15 row_newbcast:3 row_mask:0xf bank_mask:0xf
	v_fmac_f32_dpp v155, v228, v16 row_newbcast:4 row_mask:0xf bank_mask:0xf
	v_fmac_f32_dpp v201, v229, v17 row_newbcast:4 row_mask:0xf bank_mask:0xf
	v_fmac_f32_dpp v155, v230, v18 row_newbcast:4 row_mask:0xf bank_mask:0xf
	v_fmac_f32_dpp v201, v231, v19 row_newbcast:4 row_mask:0xf bank_mask:0xf
	v_fmac_f32_dpp v155, v228, v20 row_newbcast:5 row_mask:0xf bank_mask:0xf
	v_fmac_f32_dpp v201, v229, v21 row_newbcast:5 row_mask:0xf bank_mask:0xf
	v_fmac_f32_dpp v155, v230, v22 row_newbcast:5 row_mask:0xf bank_mask:0xf
	v_fmac_f32_dpp v201, v231, v23 row_newbcast:5 row_mask:0xf bank_mask:0xf
	v_fmac_f32_dpp v155, v228, v24 row_newbcast:6 row_mask:0xf bank_mask:0xf
	v_fmac_f32_dpp v201, v229, v25 row_newbcast:6 row_mask:0xf bank_mask:0xf
	v_fmac_f32_dpp v155, v230, v26 row_newbcast:6 row_mask:0xf bank_mask:0xf
	v_fmac_f32_dpp v201, v231, v27 row_newbcast:6 row_mask:0xf bank_mask:0xf
	v_fmac_f32_dpp v155, v228, v28 row_newbcast:7 row_mask:0xf bank_mask:0xf
	v_fmac_f32_dpp v201, v229, v29 row_newbcast:7 row_mask:0xf bank_mask:0xf
	v_fmac_f32_dpp v155, v230, v30 row_newbcast:7 row_mask:0xf bank_mask:0xf
	v_fmac_f32_dpp v201, v231, v31 row_newbcast:7 row_mask:0xf bank_mask:0xf
; #define SB __builtin_amdgcn_sched_barrier(0)
; #define ST2(set, s) { DERIVE_BK(set); float sd[4]; ScanK<0>::dot(S, set.a, sd); float y0 = set.yo, y1 = 0.f; ScanK<0>::upd(S, set, -((sd[0] + sd[1]) + (sd[2] + sd[3])), __uint_as_float(set.v << 16), y0, y1); __builtin_amdgcn_raw_buffer_store_b32(__float_as_uint(y0 + y1), rY, lo4b, ob4 + (unsigned)((int)(s) * (int)stp * 4), 0); }
;     static __device__ __forceinline__ void upd(float (&S)[64], const In2& in, float sa, float vv, float& y0, float& y1) {
;         float t0, t1, t2, t3;
;         asm volatile("v_mul_f32_dpp %0, %10, %27 row_newbcast:%28" DPPM "v_mul_f32_dpp %1, %11, %27 row_newbcast:%28" DPPM "v_mul_f32_dpp %2, %12, %27 row_newbcast:%28" DPPM "v_mul_f32_dpp %3, %13, %27 row_newbcast:%28" DPPM
;                      "v_fmac_f32_dpp %0, %14, %6 row_newbcast:%28" DPPM "v_fmac_f32_dpp %1, %15, %7 row_newbcast:%28" DPPM "v_fmac_f32_dpp %2, %16, %8 row_newbcast:%28" DPPM "v_fmac_f32_dpp %3, %17, %9 row_newbcast:%28" DPPM
;                      "v_fmac_f32_dpp %0, %18, %26 row_newbcast:%28" DPPM "v_fmac_f32_dpp %1, %19, %26 row_newbcast:%28" DPPM "v_fmac_f32_dpp %2, %20, %26 row_newbcast:%28" DPPM "v_fmac_f32_dpp %3, %21, %26 row_newbcast:%28" DPPM
;                      "v_fmac_f32_dpp %4, %22, %0 row_newbcast:%28" DPPM "v_fmac_f32_dpp %5, %23, %1 row_newbcast:%28" DPPM "v_fmac_f32_dpp %4, %24, %2 row_newbcast:%28" DPPM "v_fmac_f32_dpp %5, %25, %3 row_newbcast:%28" DPPM
;                      : "=&v"(t0), "=&v"(t1), "=&v"(t2), "=&v"(t3), "+v"(y0), "+v"(y1)
;                      : "v"(S[K]), "v"(S[K + 1]), "v"(S[K + 2]), "v"(S[K + 3]), "v"(in.kd[0]), "v"(in.kd[1]), "v"(in.kd[2]), "v"(in.kd[3]), "v"(in.w[0]), "v"(in.w[1]), "v"(in.w[2]), "v"(in.w[3]),
;                        "v"(in.b[0]), "v"(in.b[1]), "v"(in.b[2]), "v"(in.b[3]), "v"(in.r[0]), "v"(in.r[1]), "v"(in.r[2]), "v"(in.r[3]), "v"(sa), "v"(vv), "n"(N0));
;         S[K] = t0; S[K + 1] = t1; S[K + 2] = t2; S[K + 3] = t3;
;         if constexpr (K + 4 < 64) ScanK<K + 4>::upd(S, in, sa, vv, y0, y1);
; __device__ __forceinline__ void scan_pass2(const Params& p, int d) {
;     ...
;         In2 i0, i1; LD2(i0, 0);
; #pragma unroll 1
;         for (int s = 0; s < LC; s += 2) { TOUCH2(i0); SB; LD2(i1, s + 1); SB; ST2(i0, s); TOUCH2(i1); SB; LD2(i0, s + 2); SB; ST2(i1, s + 1); }
	v_fmac_f32_dpp v155, v228, v32 row_newbcast:8 row_mask:0xf bank_mask:0xf
	v_fmac_f32_dpp v201, v229, v33 row_newbcast:8 row_mask:0xf bank_mask:0xf
	v_fmac_f32_dpp v155, v230, v34 row_newbcast:8 row_mask:0xf bank_mask:0xf
	v_fmac_f32_dpp v201, v231, v35 row_newbcast:8 row_mask:0xf bank_mask:0xf
	v_fmac_f32_dpp v155, v228, v36 row_newbcast:9 row_mask:0xf bank_mask:0xf
	v_fmac_f32_dpp v201, v229, v37 row_newbcast:9 row_mask:0xf bank_mask:0xf
	v_fmac_f32_dpp v155, v230, v38 row_newbcast:9 row_mask:0xf bank_mask:0xf
	v_fmac_f32_dpp v201, v231, v39 row_newbcast:9 row_mask:0xf bank_mask:0xf
	v_fmac_f32_dpp v155, v228, v40 row_newbcast:10 row_mask:0xf bank_mask:0xf
	v_fmac_f32_dpp v201, v229, v41 row_newbcast:10 row_mask:0xf bank_mask:0xf
	v_fmac_f32_dpp v155, v230, v42 row_newbcast:10 row_mask:0xf bank_mask:0xf
	v_fmac_f32_dpp v201, v231, v43 row_newbcast:10 row_mask:0xf bank_mask:0xf
	v_fmac_f32_dpp v155, v228, v44 row_newbcast:11 row_mask:0xf bank_mask:0xf
	v_fmac_f32_dpp v201, v229, v45 row_newbcast:11 row_mask:0xf bank_mask:0xf
	v_fmac_f32_dpp v155, v230, v46 row_newbcast:11 row_mask:0xf bank_mask:0xf
	v_fmac_f32_dpp v201, v231, v47 row_newbcast:11 row_mask:0xf bank_mask:0xf
	v_fmac_f32_dpp v155, v228, v48 row_newbcast:12 row_mask:0xf bank_mask:0xf
	v_fmac_f32_dpp v201, v229, v49 row_newbcast:12 row_mask:0xf bank_mask:0xf
	v_fmac_f32_dpp v155, v230, v50 row_newbcast:12 row_mask:0xf bank_mask:0xf
	v_fmac_f32_dpp v201, v231, v51 row_newbcast:12 row_mask:0xf bank_mask:0xf
	v_fmac_f32_dpp v155, v228, v52 row_newbcast:13 row_mask:0xf bank_mask:0xf
	v_fmac_f32_dpp v201, v229, v53 row_newbcast:13 row_mask:0xf bank_mask:0xf
	v_fmac_f32_dpp v155, v230, v54 row_newbcast:13 row_mask:0xf bank_mask:0xf
	v_fmac_f32_dpp v201, v231, v55 row_newbcast:13 row_mask:0xf bank_mask:0xf
	v_fmac_f32_dpp v155, v228, v56 row_newbcast:14 row_mask:0xf bank_mask:0xf
	v_fmac_f32_dpp v201, v229, v57 row_newbcast:14 row_mask:0xf bank_mask:0xf
	v_fmac_f32_dpp v155, v230, v58 row_newbcast:14 row_mask:0xf bank_mask:0xf
	v_fmac_f32_dpp v201, v231, v59 row_newbcast:14 row_mask:0xf bank_mask:0xf
	v_fmac_f32_dpp v155, v228, v60 row_newbcast:15 row_mask:0xf bank_mask:0xf
	v_fmac_f32_dpp v201, v229, v61 row_newbcast:15 row_mask:0xf bank_mask:0xf
	v_fmac_f32_dpp v155, v230, v62 row_newbcast:15 row_mask:0xf bank_mask:0xf
	v_fmac_f32_dpp v201, v231, v63 row_newbcast:15 row_mask:0xf bank_mask:0xf
	v_add_f32_e32 v200, v155, v201
	s_waitcnt vmcnt(14)
	buffer_store_dword v200, v207, s[68:71], s79 offen
	s_add_u32 s79, s79, 0xfffff000
	buffer_load_dwordx4 v[136:139], v232, s[64:67], s72 offen
	buffer_load_dwordx4 v[140:143], v233, s[64:67], s72 offen
	buffer_load_dwordx4 v[144:147], v234, s[64:67], s72 offen
	buffer_load_dwordx4 v[148:151], v235, s[64:67], s72 offen
	buffer_load_dwordx2 v[152:153], v236, s[64:67], s76 offen
	buffer_load_ushort v154, v237, s[64:67], s76 offen
	buffer_load_dword v155, v207, s[68:71], s78 offen
	s_add_i32 s72, s72, 0xfffff000
	s_max_i32 s72, s72, 0
	s_add_i32 s76, s76, 0xfffff800
	s_max_i32 s76, s76, 0
	s_add_i32 s78, s78, 0xfffff000
	s_max_i32 s78, s78, 0
	v_pk_mul_f32 v[224:225], v[160:161], v[216:217]
	v_pk_mul_f32 v[226:227], v[162:163], v[218:219]
	v_pk_mul_f32 v[216:217], v[216:217], v[156:157]
	v_pk_mul_f32 v[218:219], v[218:219], v[158:159]
	v_pk_fma_f32 v[184:185], v[164:165], v[188:189], v[192:193]
	v_pk_fma_f32 v[186:187], v[166:167], v[190:191], v[194:195]
	v_pk_mul_f32 v[176:177], v[160:161], v[164:165]
	v_pk_mul_f32 v[178:179], v[162:163], v[166:167]
	v_rcp_f32_e32 v220, v216
	v_rcp_f32_e32 v221, v217
	v_rcp_f32_e32 v222, v218
	v_rcp_f32_e32 v223, v219
	v_lshlrev_b32_e32 v180, 16, v172
	v_and_b32_e32 v181, 0xffff0000, v172
	v_lshlrev_b32_e32 v182, 16, v173
	v_and_b32_e32 v183, 0xffff0000, v173
	v_pk_mul_f32 v[180:181], v[180:181], v[184:185]
	v_pk_mul_f32 v[182:183], v[182:183], v[186:187]
	v_pk_mul_f32 v[228:229], v[168:169], v[216:217]
	v_pk_mul_f32 v[230:231], v[170:171], v[218:219]
	v_pk_mul_f32 v[176:177], v[176:177], v[220:221]
	v_pk_mul_f32 v[178:179], v[178:179], v[222:223]
	v_pk_mul_f32 v[180:181], v[180:181], v[220:221]
	v_pk_mul_f32 v[182:183], v[182:183], v[222:223]
	v_lshlrev_b32_e32 v203, 16, v174
	ds_write2_b32 v208, v176, v177 offset0:0 offset1:16
	ds_write2_b32 v208, v178, v179 offset0:32 offset1:48
	ds_write2_b32 v208, v180, v181 offset0:64 offset1:80
	ds_write2_b32 v208, v182, v183 offset0:96 offset1:112
	ds_read_b128 v[64:67], v209 offset:0
	ds_read_b128 v[68:71], v209 offset:16
	ds_read_b128 v[72:75], v209 offset:32
	ds_read_b128 v[76:79], v209 offset:48
	ds_read_b128 v[80:83], v209 offset:256
	ds_read_b128 v[84:87], v209 offset:272
	ds_read_b128 v[88:91], v209 offset:288
	ds_read_b128 v[92:95], v209 offset:304
	v_mul_f32_dpp v196, v224, v0 row_newbcast:0 row_mask:0xf bank_mask:0xf
	v_mul_f32_dpp v197, v225, v1 row_newbcast:0 row_mask:0xf bank_mask:0xf
	v_mul_f32_dpp v198, v226, v2 row_newbcast:0 row_mask:0xf bank_mask:0xf
	v_mul_f32_dpp v199, v227, v3 row_newbcast:0 row_mask:0xf bank_mask:0xf
	v_fmac_f32_dpp v196, v224, v4 row_newbcast:1 row_mask:0xf bank_mask:0xf
	v_fmac_f32_dpp v197, v225, v5 row_newbcast:1 row_mask:0xf bank_mask:0xf
	v_fmac_f32_dpp v198, v226, v6 row_newbcast:1 row_mask:0xf bank_mask:0xf
	v_fmac_f32_dpp v199, v227, v7 row_newbcast:1 row_mask:0xf bank_mask:0xf
	v_fmac_f32_dpp v196, v224, v8 row_newbcast:2 row_mask:0xf bank_mask:0xf
	v_fmac_f32_dpp v197, v225, v9 row_newbcast:2 row_mask:0xf bank_mask:0xf
	v_fmac_f32_dpp v198, v226, v10 row_newbcast:2 row_mask:0xf bank_mask:0xf
	v_fmac_f32_dpp v199, v227, v11 row_newbcast:2 row_mask:0xf bank_mask:0xf
	v_fmac_f32_dpp v196, v224, v12 row_newbcast:3 row_mask:0xf bank_mask:0xf
;     static __device__ __forceinline__ void dot(const float (&S)[64], const f32x4& a, float (&s)[4]) {
;         if constexpr (K == 0) {
;             asm volatile("v_mul_f32_dpp %0, %4, %8 row_newbcast:%16" DPPM "v_mul_f32_dpp %1, %5, %9 row_newbcast:%16" DPPM "v_mul_f32_dpp %2, %6, %10 row_newbcast:%16" DPPM "v_mul_f32_dpp %3, %7, %11 row_newbcast:%16" DPPM
;                          "v_fmac_f32_dpp %0, %4, %12 row_newbcast:%17" DPPM "v_fmac_f32_dpp %1, %5, %13 row_newbcast:%17" DPPM "v_fmac_f32_dpp %2, %6, %14 row_newbcast:%17" DPPM "v_fmac_f32_dpp %3, %7, %15 row_newbcast:%17" DPPM
;                          : "=&v"(s[0]), "=&v"(s[1]), "=&v"(s[2]), "=&v"(s[3])
;                          : "v"(a[0]), "v"(a[1]), "v"(a[2]), "v"(a[3]), "v"(S[K]), "v"(S[K + 1]), "v"(S[K + 2]), "v"(S[K + 3]), "v"(S[K + 4]), "v"(S[K + 5]), "v"(S[K + 6]), "v"(S[K + 7]), "n"(N0), "n"(N1));
;         } else
;         asm volatile("v_fmac_f32_dpp %0, %4, %8 row_newbcast:%16" DPPM "v_fmac_f32_dpp %1, %5, %9 row_newbcast:%16" DPPM "v_fmac_f32_dpp %2, %6, %10 row_newbcast:%16" DPPM "v_fmac_f32_dpp %3, %7, %11 row_newbcast:%16" DPPM
;                      "v_fmac_f32_dpp %0, %4, %12 row_newbcast:%17" DPPM "v_fmac_f32_dpp %1, %5, %13 row_newbcast:%17" DPPM "v_fmac_f32_dpp %2, %6, %14 row_newbcast:%17" DPPM "v_fmac_f32_dpp %3, %7, %15 row_newbcast:%17" DPPM
;                      : "+v"(s[0]), "+v"(s[1]), "+v"(s[2]), "+v"(s[3])
;                      : "v"(a[0]), "v"(a[1]), "v"(a[2]), "v"(a[3]), "v"(S[K]), "v"(S[K + 1]), "v"(S[K + 2]), "v"(S[K + 3]), "v"(S[K + 4]), "v"(S[K + 5]), "v"(S[K + 6]), "v"(S[K + 7]), "n"(N0), "n"(N1));
;         if constexpr (K + 8 < 64) ScanK<K + 8>::dot(S, a, s);
;     }
	v_fmac_f32_dpp v197, v225, v13 row_newbcast:3 row_mask:0xf bank_mask:0xf
	v_fmac_f32_dpp v198, v226, v14 row_newbcast:3 row_mask:0xf bank_mask:0xf
	v_fmac_f32_dpp v199, v227, v15 row_newbcast:3 row_mask:0xf bank_mask:0xf
	v_fmac_f32_dpp v196, v224, v16 row_newbcast:4 row_mask:0xf bank_mask:0xf
	v_fmac_f32_dpp v197, v225, v17 row_newbcast:4 row_mask:0xf bank_mask:0xf
	v_fmac_f32_dpp v198, v226, v18 row_newbcast:4 row_mask:0xf bank_mask:0xf
	v_fmac_f32_dpp v199, v227, v19 row_newbcast:4 row_mask:0xf bank_mask:0xf
	v_fmac_f32_dpp v196, v224, v20 row_newbcast:5 row_mask:0xf bank_mask:0xf
	v_fmac_f32_dpp v197, v225, v21 row_newbcast:5 row_mask:0xf bank_mask:0xf
	v_fmac_f32_dpp v198, v226, v22 row_newbcast:5 row_mask:0xf bank_mask:0xf
	v_fmac_f32_dpp v199, v227, v23 row_newbcast:5 row_mask:0xf bank_mask:0xf
	v_fmac_f32_dpp v196, v224, v24 row_newbcast:6 row_mask:0xf bank_mask:0xf
	v_fmac_f32_dpp v197, v225, v25 row_newbcast:6 row_mask:0xf bank_mask:0xf
	v_fmac_f32_dpp v198, v226, v26 row_newbcast:6 row_mask:0xf bank_mask:0xf
	v_fmac_f32_dpp v199, v227, v27 row_newbcast:6 row_mask:0xf bank_mask:0xf
	v_fmac_f32_dpp v196, v224, v28 row_newbcast:7 row_mask:0xf bank_mask:0xf
	v_fmac_f32_dpp v197, v225, v29 row_newbcast:7 row_mask:0xf bank_mask:0xf
	v_fmac_f32_dpp v198, v226, v30 row_newbcast:7 row_mask:0xf bank_mask:0xf
	v_fmac_f32_dpp v199, v227, v31 row_newbcast:7 row_mask:0xf bank_mask:0xf
	v_fmac_f32_dpp v196, v224, v32 row_newbcast:8 row_mask:0xf bank_mask:0xf
	v_fmac_f32_dpp v197, v225, v33 row_newbcast:8 row_mask:0xf bank_mask:0xf
	v_fmac_f32_dpp v198, v226, v34 row_newbcast:8 row_mask:0xf bank_mask:0xf
	v_fmac_f32_dpp v199, v227, v35 row_newbcast:8 row_mask:0xf bank_mask:0xf
	v_fmac_f32_dpp v196, v224, v36 row_newbcast:9 row_mask:0xf bank_mask:0xf
	v_fmac_f32_dpp v197, v225, v37 row_newbcast:9 row_mask:0xf bank_mask:0xf
	v_fmac_f32_dpp v198, v226, v38 row_newbcast:9 row_mask:0xf bank_mask:0xf
	v_fmac_f32_dpp v199, v227, v39 row_newbcast:9 row_mask:0xf bank_mask:0xf
	v_fmac_f32_dpp v196, v224, v40 row_newbcast:10 row_mask:0xf bank_mask:0xf
	v_fmac_f32_dpp v197, v225, v41 row_newbcast:10 row_mask:0xf bank_mask:0xf
	v_fmac_f32_dpp v198, v226, v42 row_newbcast:10 row_mask:0xf bank_mask:0xf
	v_fmac_f32_dpp v199, v227, v43 row_newbcast:10 row_mask:0xf bank_mask:0xf
	v_fmac_f32_dpp v196, v224, v44 row_newbcast:11 row_mask:0xf bank_mask:0xf
	v_fmac_f32_dpp v197, v225, v45 row_newbcast:11 row_mask:0xf bank_mask:0xf
	v_fmac_f32_dpp v198, v226, v46 row_newbcast:11 row_mask:0xf bank_mask:0xf
	v_fmac_f32_dpp v199, v227, v47 row_newbcast:11 row_mask:0xf bank_mask:0xf
	v_fmac_f32_dpp v196, v224, v48 row_newbcast:12 row_mask:0xf bank_mask:0xf
	v_fmac_f32_dpp v197, v225, v49 row_newbcast:12 row_mask:0xf bank_mask:0xf
	v_fmac_f32_dpp v198, v226, v50 row_newbcast:12 row_mask:0xf bank_mask:0xf
	v_fmac_f32_dpp v199, v227, v51 row_newbcast:12 row_mask:0xf bank_mask:0xf
	v_fmac_f32_dpp v196, v224, v52 row_newbcast:13 row_mask:0xf bank_mask:0xf
	v_fmac_f32_dpp v197, v225, v53 row_newbcast:13 row_mask:0xf bank_mask:0xf
	v_fmac_f32_dpp v198, v226, v54 row_newbcast:13 row_mask:0xf bank_mask:0xf
	v_fmac_f32_dpp v199, v227, v55 row_newbcast:13 row_mask:0xf bank_mask:0xf
	v_fmac_f32_dpp v196, v224, v56 row_newbcast:14 row_mask:0xf bank_mask:0xf
	v_fmac_f32_dpp v197, v225, v57 row_newbcast:14 row_mask:0xf bank_mask:0xf
	v_fmac_f32_dpp v198, v226, v58 row_newbcast:14 row_mask:0xf bank_mask:0xf
	v_fmac_f32_dpp v199, v227, v59 row_newbcast:14 row_mask:0xf bank_mask:0xf
	v_fmac_f32_dpp v196, v224, v60 row_newbcast:15 row_mask:0xf bank_mask:0xf
	v_fmac_f32_dpp v197, v225, v61 row_newbcast:15 row_mask:0xf bank_mask:0xf
	v_fmac_f32_dpp v198, v226, v62 row_newbcast:15 row_mask:0xf bank_mask:0xf
	v_fmac_f32_dpp v199, v227, v63 row_newbcast:15 row_mask:0xf bank_mask:0xf
	v_add_f32_e32 v196, v196, v197
	v_add_f32_e32 v198, v198, v199
	v_sub_f32_e64 v202, -v196, v198
	s_waitcnt lgkmcnt(0)
; #define SB __builtin_amdgcn_sched_barrier(0)
; #define ST2(set, s) { DERIVE_BK(set); float sd[4]; ScanK<0>::dot(S, set.a, sd); float y0 = set.yo, y1 = 0.f; ScanK<0>::upd(S, set, -((sd[0] + sd[1]) + (sd[2] + sd[3])), __uint_as_float(set.v << 16), y0, y1); __builtin_amdgcn_raw_buffer_store_b32(__float_as_uint(y0 + y1), rY, lo4b, ob4 + (unsigned)((int)(s) * (int)stp * 4), 0); }
;     static __device__ __forceinline__ void upd(float (&S)[64], const In2& in, float sa, float vv, float& y0, float& y1) {
;         float t0, t1, t2, t3;
;         asm volatile("v_mul_f32_dpp %0, %10, %27 row_newbcast:%28" DPPM "v_mul_f32_dpp %1, %11, %27 row_newbcast:%28" DPPM "v_mul_f32_dpp %2, %12, %27 row_newbcast:%28" DPPM "v_mul_f32_dpp %3, %13, %27 row_newbcast:%28" DPPM
;                      "v_fmac_f32_dpp %0, %14, %6 row_newbcast:%28" DPPM "v_fmac_f32_dpp %1, %15, %7 row_newbcast:%28" DPPM "v_fmac_f32_dpp %2, %16, %8 row_newbcast:%28" DPPM "v_fmac_f32_dpp %3, %17, %9 row_newbcast:%28" DPPM
;                      "v_fmac_f32_dpp %0, %18, %26 row_newbcast:%28" DPPM "v_fmac_f32_dpp %1, %19, %26 row_newbcast:%28" DPPM "v_fmac_f32_dpp %2, %20, %26 row_newbcast:%28" DPPM "v_fmac_f32_dpp %3, %21, %26 row_newbcast:%28" DPPM
;                      "v_fmac_f32_dpp %4, %22, %0 row_newbcast:%28" DPPM "v_fmac_f32_dpp %5, %23, %1 row_newbcast:%28" DPPM "v_fmac_f32_dpp %4, %24, %2 row_newbcast:%28" DPPM "v_fmac_f32_dpp %5, %25, %3 row_newbcast:%28" DPPM
;                      : "=&v"(t0), "=&v"(t1), "=&v"(t2), "=&v"(t3), "+v"(y0), "+v"(y1)
;                      : "v"(S[K]), "v"(S[K + 1]), "v"(S[K + 2]), "v"(S[K + 3]), "v"(in.kd[0]), "v"(in.kd[1]), "v"(in.kd[2]), "v"(in.kd[3]), "v"(in.w[0]), "v"(in.w[1]), "v"(in.w[2]), "v"(in.w[3]),
;                        "v"(in.b[0]), "v"(in.b[1]), "v"(in.b[2]), "v"(in.b[3]), "v"(in.r[0]), "v"(in.r[1]), "v"(in.r[2]), "v"(in.r[3]), "v"(sa), "v"(vv), "n"(N0));
;         S[K] = t0; S[K + 1] = t1; S[K + 2] = t2; S[K + 3] = t3;
;         if constexpr (K + 4 < 64) ScanK<K + 4>::upd(S, in, sa, vv, y0, y1);
; __device__ __forceinline__ void scan_pass2(const Params& p, int d) {
;     ...
;         In2 i0, i1; LD2(i0, 0);
; #pragma unroll 1
;         for (int s = 0; s < LC; s += 2) { TOUCH2(i0); SB; LD2(i1, s + 1); SB; ST2(i0, s); TOUCH2(i1); SB; LD2(i0, s + 2); SB; ST2(i1, s + 1); }
	s_nop 1
	v_mfma_f32_4x4x1_16b_f32 v[0:3], v64, v202, v[0:3]
	v_mfma_f32_4x4x1_16b_f32 v[4:7], v65, v202, v[4:7]
	v_mfma_f32_4x4x1_16b_f32 v[8:11], v66, v202, v[8:11]
	v_mfma_f32_4x4x1_16b_f32 v[12:15], v67, v202, v[12:15]
	v_mfma_f32_4x4x1_16b_f32 v[16:19], v68, v202, v[16:19]
	v_mfma_f32_4x4x1_16b_f32 v[20:23], v69, v202, v[20:23]
	v_mfma_f32_4x4x1_16b_f32 v[24:27], v70, v202, v[24:27]
	v_mfma_f32_4x4x1_16b_f32 v[28:31], v71, v202, v[28:31]
	v_mfma_f32_4x4x1_16b_f32 v[32:35], v72, v202, v[32:35]
	v_mfma_f32_4x4x1_16b_f32 v[36:39], v73, v202, v[36:39]
	v_mfma_f32_4x4x1_16b_f32 v[40:43], v74, v202, v[40:43]
	v_mfma_f32_4x4x1_16b_f32 v[44:47], v75, v202, v[44:47]
	v_mfma_f32_4x4x1_16b_f32 v[48:51], v76, v202, v[48:51]
	v_mfma_f32_4x4x1_16b_f32 v[52:55], v77, v202, v[52:55]
	v_mfma_f32_4x4x1_16b_f32 v[56:59], v78, v202, v[56:59]
	v_mfma_f32_4x4x1_16b_f32 v[60:63], v79, v202, v[60:63]
	v_mfma_f32_4x4x1_16b_f32 v[0:3], v80, v203, v[0:3]
	v_mfma_f32_4x4x1_16b_f32 v[4:7], v81, v203, v[4:7]
	v_mfma_f32_4x4x1_16b_f32 v[8:11], v82, v203, v[8:11]
	v_mfma_f32_4x4x1_16b_f32 v[12:15], v83, v203, v[12:15]
	v_mfma_f32_4x4x1_16b_f32 v[16:19], v84, v203, v[16:19]
	v_mfma_f32_4x4x1_16b_f32 v[20:23], v85, v203, v[20:23]
	v_mfma_f32_4x4x1_16b_f32 v[24:27], v86, v203, v[24:27]
	v_mfma_f32_4x4x1_16b_f32 v[28:31], v87, v203, v[28:31]
	v_mfma_f32_4x4x1_16b_f32 v[32:35], v88, v203, v[32:35]
	v_mfma_f32_4x4x1_16b_f32 v[36:39], v89, v203, v[36:39]
	v_mfma_f32_4x4x1_16b_f32 v[40:43], v90, v203, v[40:43]
	v_mfma_f32_4x4x1_16b_f32 v[44:47], v91, v203, v[44:47]
	v_mfma_f32_4x4x1_16b_f32 v[48:51], v92, v203, v[48:51]
	v_mfma_f32_4x4x1_16b_f32 v[52:55], v93, v203, v[52:55]
	v_mfma_f32_4x4x1_16b_f32 v[56:59], v94, v203, v[56:59]
	v_mfma_f32_4x4x1_16b_f32 v[60:63], v95, v203, v[60:63]
	v_fmac_f32_dpp v175, v228, v0 row_newbcast:0 row_mask:0xf bank_mask:0xf
	v_mul_f32_dpp v201, v229, v1 row_newbcast:0 row_mask:0xf bank_mask:0xf
	v_fmac_f32_dpp v175, v230, v2 row_newbcast:0 row_mask:0xf bank_mask:0xf
	v_fmac_f32_dpp v201, v231, v3 row_newbcast:0 row_mask:0xf bank_mask:0xf
	v_fmac_f32_dpp v175, v228, v4 row_newbcast:1 row_mask:0xf bank_mask:0xf
	v_fmac_f32_dpp v201, v229, v5 row_newbcast:1 row_mask:0xf bank_mask:0xf
	v_fmac_f32_dpp v175, v230, v6 row_newbcast:1 row_mask:0xf bank_mask:0xf
	v_fmac_f32_dpp v201, v231, v7 row_newbcast:1 row_mask:0xf bank_mask:0xf
	v_fmac_f32_dpp v175, v228, v8 row_newbcast:2 row_mask:0xf bank_mask:0xf
	v_fmac_f32_dpp v201, v229, v9 row_newbcast:2 row_mask:0xf bank_mask:0xf
	v_fmac_f32_dpp v175, v230, v10 row_newbcast:2 row_mask:0xf bank_mask:0xf
	v_fmac_f32_dpp v201, v231, v11 row_newbcast:2 row_mask:0xf bank_mask:0xf
	v_fmac_f32_dpp v175, v228, v12 row_newbcast:3 row_mask:0xf bank_mask:0xf
	v_fmac_f32_dpp v201, v229, v13 row_newbcast:3 row_mask:0xf bank_mask:0xf
	v_fmac_f32_dpp v175, v230, v14 row_newbcast:3 row_mask:0xf bank_mask:0xf
	v_fmac_f32_dpp v201, v231, v15 row_newbcast:3 row_mask:0xf bank_mask:0xf
	v_fmac_f32_dpp v175, v228, v16 row_newbcast:4 row_mask:0xf bank_mask:0xf
	v_fmac_f32_dpp v201, v229, v17 row_newbcast:4 row_mask:0xf bank_mask:0xf
	v_fmac_f32_dpp v175, v230, v18 row_newbcast:4 row_mask:0xf bank_mask:0xf
	v_fmac_f32_dpp v201, v231, v19 row_newbcast:4 row_mask:0xf bank_mask:0xf
	v_fmac_f32_dpp v175, v228, v20 row_newbcast:5 row_mask:0xf bank_mask:0xf
	v_fmac_f32_dpp v201, v229, v21 row_newbcast:5 row_mask:0xf bank_mask:0xf
	v_fmac_f32_dpp v175, v230, v22 row_newbcast:5 row_mask:0xf bank_mask:0xf
	v_fmac_f32_dpp v201, v231, v23 row_newbcast:5 row_mask:0xf bank_mask:0xf
	v_fmac_f32_dpp v175, v228, v24 row_newbcast:6 row_mask:0xf bank_mask:0xf
	v_fmac_f32_dpp v201, v229, v25 row_newbcast:6 row_mask:0xf bank_mask:0xf
	v_fmac_f32_dpp v175, v230, v26 row_newbcast:6 row_mask:0xf bank_mask:0xf
	v_fmac_f32_dpp v201, v231, v27 row_newbcast:6 row_mask:0xf bank_mask:0xf
	v_fmac_f32_dpp v175, v228, v28 row_newbcast:7 row_mask:0xf bank_mask:0xf
	v_fmac_f32_dpp v201, v229, v29 row_newbcast:7 row_mask:0xf bank_mask:0xf
	v_fmac_f32_dpp v175, v230, v30 row_newbcast:7 row_mask:0xf bank_mask:0xf
	v_fmac_f32_dpp v201, v231, v31 row_newbcast:7 row_mask:0xf bank_mask:0xf
	v_fmac_f32_dpp v175, v228, v32 row_newbcast:8 row_mask:0xf bank_mask:0xf
	v_fmac_f32_dpp v201, v229, v33 row_newbcast:8 row_mask:0xf bank_mask:0xf
	v_fmac_f32_dpp v175, v230, v34 row_newbcast:8 row_mask:0xf bank_mask:0xf
	v_fmac_f32_dpp v201, v231, v35 row_newbcast:8 row_mask:0xf bank_mask:0xf
	v_fmac_f32_dpp v175, v228, v36 row_newbcast:9 row_mask:0xf bank_mask:0xf
	v_fmac_f32_dpp v201, v229, v37 row_newbcast:9 row_mask:0xf bank_mask:0xf
	v_fmac_f32_dpp v175, v230, v38 row_newbcast:9 row_mask:0xf bank_mask:0xf
	v_fmac_f32_dpp v201, v231, v39 row_newbcast:9 row_mask:0xf bank_mask:0xf
	v_fmac_f32_dpp v175, v228, v40 row_newbcast:10 row_mask:0xf bank_mask:0xf
	v_fmac_f32_dpp v201, v229, v41 row_newbcast:10 row_mask:0xf bank_mask:0xf
	v_fmac_f32_dpp v175, v230, v42 row_newbcast:10 row_mask:0xf bank_mask:0xf
	v_fmac_f32_dpp v201, v231, v43 row_newbcast:10 row_mask:0xf bank_mask:0xf
	v_fmac_f32_dpp v175, v228, v44 row_newbcast:11 row_mask:0xf bank_mask:0xf
	v_fmac_f32_dpp v201, v229, v45 row_newbcast:11 row_mask:0xf bank_mask:0xf
	v_fmac_f32_dpp v175, v230, v46 row_newbcast:11 row_mask:0xf bank_mask:0xf
	v_fmac_f32_dpp v201, v231, v47 row_newbcast:11 row_mask:0xf bank_mask:0xf
	v_fmac_f32_dpp v175, v228, v48 row_newbcast:12 row_mask:0xf bank_mask:0xf
	v_fmac_f32_dpp v201, v229, v49 row_newbcast:12 row_mask:0xf bank_mask:0xf
	v_fmac_f32_dpp v175, v230, v50 row_newbcast:12 row_mask:0xf bank_mask:0xf
	v_fmac_f32_dpp v201, v231, v51 row_newbcast:12 row_mask:0xf bank_mask:0xf
	v_fmac_f32_dpp v175, v228, v52 row_newbcast:13 row_mask:0xf bank_mask:0xf
	v_fmac_f32_dpp v201, v229, v53 row_newbcast:13 row_mask:0xf bank_mask:0xf
	v_fmac_f32_dpp v175, v230, v54 row_newbcast:13 row_mask:0xf bank_mask:0xf
	v_fmac_f32_dpp v201, v231, v55 row_newbcast:13 row_mask:0xf bank_mask:0xf
	v_fmac_f32_dpp v175, v228, v56 row_newbcast:14 row_mask:0xf bank_mask:0xf
	v_fmac_f32_dpp v201, v229, v57 row_newbcast:14 row_mask:0xf bank_mask:0xf
	v_fmac_f32_dpp v175, v230, v58 row_newbcast:14 row_mask:0xf bank_mask:0xf
	v_fmac_f32_dpp v201, v231, v59 row_newbcast:14 row_mask:0xf bank_mask:0xf
	v_fmac_f32_dpp v175, v228, v60 row_newbcast:15 row_mask:0xf bank_mask:0xf
	v_fmac_f32_dpp v201, v229, v61 row_newbcast:15 row_mask:0xf bank_mask:0xf
	v_fmac_f32_dpp v175, v230, v62 row_newbcast:15 row_mask:0xf bank_mask:0xf
	v_fmac_f32_dpp v201, v231, v63 row_newbcast:15 row_mask:0xf bank_mask:0xf
	v_add_f32_e32 v200, v175, v201
	s_sub_u32 s83, s83, 1
	s_cmp_eq_u32 s83, 0
	s_cbranch_scc1 .Lmy_p2d1_ldone
	s_and_b32 s9, s83, 15
	s_cmp_eq_u32 s9, 0
	s_cbranch_scc1 .Lmy_p2d1_renorm
	s_branch .Lmy_p2d1_loop
